# GEMM tile loops (bf16-epilogue instances): next tile's first two K-step global loads are issued before the current tile's epilogue stores
# speedup vs baseline: 1.1227x; 1.0040x over previous
.LBB0_193:
	s_bfe_u32 s100, s36, 0x30005
	s_and_b32 s101, s36, 31
	s_lshr_b32 s82, s36, 8
	s_lshr_b32 s64, s100, 2
	s_lshl_b32 s64, s64, 5
	s_add_u32 s64, s64, s101
	s_lshl_b32 s82, s82, 2
	s_and_b32 s100, s100, 3
	s_add_u32 s82, s82, s100
	s_lshl_b32 s64, s64, 8
	s_lshl_b32 s82, s82, 8
	s_lshl_b32 s100, s64, 12
	s_add_u32 s100, s100, 0x6224000
	s_add_u32 s48, s92, s100
	s_addc_u32 s49, s93, 0
	s_and_b32 s49, s49, 0xffff
	s_mov_b32 s50, 0x100000
	s_mov_b32 s51, 0x20000
	s_lshl_b32 s100, s82, 12
	s_add_u32 s100, s100, 0x0
	s_add_u32 s52, s92, s100
	s_addc_u32 s53, s93, 0
	s_and_b32 s53, s53, 0xffff
	s_sub_u32 s100, 0x1380, s82
	s_min_u32 s100, s100, 0x100
	s_lshl_b32 s54, s100, 12
	s_mov_b32 s55, 0x20000
	s_mov_b32 s46, 0x40000
	s_mov_b32 s47, 0x80000
	s_mov_b32 s58, 0xc0000
	v_lshrrev_b32_e32 v128, 3, v190
	v_and_b32_e32 v129, 7, v190
	v_lshlrev_b32_e32 v129, 4, v129
	v_lshl_add_u32 v160, v128, 12, v129
	v_mul_u32_u24_e32 v130, 0x90, v128
	v_add_u32_e32 v170, v130, v129
	v_add_u32_e32 v171, 0x12000, v170
	v_and_b32_e32 v131, 31, v190
	v_bfe_u32 v132, v190, 5, 1
	v_bfe_u32 v133, v190, 6, 2
	v_bfe_u32 v134, v190, 8, 1
	v_lshl_add_u32 v135, v134, 7, v131
	v_mul_u32_u24_e32 v135, 0x90, v135
	v_lshl_add_u32 v175, v132, 4, v135
	v_lshl_add_u32 v136, v133, 6, v131
	v_mul_u32_u24_e32 v136, 0x90, v136
	v_lshl_add_u32 v136, v132, 4, v136
	v_add_u32_e32 v254, 0x12000, v136
	buffer_load_dwordx4 v[216:219], v160, s[48:51], 0 offen
	buffer_load_dwordx4 v[220:223], v160, s[48:51], s46 offen
	buffer_load_dwordx4 v[224:227], v160, s[48:51], s47 offen
	buffer_load_dwordx4 v[228:231], v160, s[48:51], s58 offen
	buffer_load_dwordx4 v[232:235], v160, s[52:55], 0 offen
	buffer_load_dwordx4 v[236:239], v160, s[52:55], s46 offen
	buffer_load_dwordx4 v[152:155], v160, s[52:55], s47 offen
	buffer_load_dwordx4 v[156:159], v160, s[52:55], s58 offen
	v_add_u32_e32 v160, 0x80, v160
	buffer_load_dwordx4 v[162:165], v160, s[48:51], 0 offen
	buffer_load_dwordx4 v[166:169], v160, s[48:51], s46 offen
	buffer_load_dwordx4 v[176:179], v160, s[48:51], s47 offen
	buffer_load_dwordx4 v[180:183], v160, s[48:51], s58 offen
	buffer_load_dwordx4 v[184:187], v160, s[52:55], 0 offen
	buffer_load_dwordx4 v[242:245], v160, s[52:55], s46 offen
	buffer_load_dwordx4 v[246:249], v160, s[52:55], s47 offen
	buffer_load_dwordx4 v[250:253], v160, s[52:55], s58 offen
	v_add_u32_e32 v160, 0x80, v160
.Lgin0_tile:
	s_mov_b32 s46, 0x40000
	s_mov_b32 s47, 0x80000
	s_mov_b32 s58, 0xc0000
	v_mov_b32_e32 v0, 0
	v_mov_b32_e32 v1, 0
	v_mov_b32_e32 v2, 0
	v_mov_b32_e32 v3, 0
	v_mov_b32_e32 v4, 0
	v_mov_b32_e32 v5, 0
	v_mov_b32_e32 v6, 0
	v_mov_b32_e32 v7, 0
	v_mov_b32_e32 v8, 0
	v_mov_b32_e32 v9, 0
	v_mov_b32_e32 v10, 0
	v_mov_b32_e32 v11, 0
	v_mov_b32_e32 v12, 0
	v_mov_b32_e32 v13, 0
	v_mov_b32_e32 v14, 0
	v_mov_b32_e32 v15, 0
	v_mov_b32_e32 v16, 0
	v_mov_b32_e32 v17, 0
	v_mov_b32_e32 v18, 0
	v_mov_b32_e32 v19, 0
	v_mov_b32_e32 v20, 0
	v_mov_b32_e32 v21, 0
	v_mov_b32_e32 v22, 0
	v_mov_b32_e32 v23, 0
	v_mov_b32_e32 v24, 0
	v_mov_b32_e32 v25, 0
	v_mov_b32_e32 v26, 0
	v_mov_b32_e32 v27, 0
	v_mov_b32_e32 v28, 0
	v_mov_b32_e32 v29, 0
	v_mov_b32_e32 v30, 0
	v_mov_b32_e32 v31, 0
	v_mov_b32_e32 v32, 0
	v_mov_b32_e32 v33, 0
	v_mov_b32_e32 v34, 0
	v_mov_b32_e32 v35, 0
	v_mov_b32_e32 v36, 0
	v_mov_b32_e32 v37, 0
	v_mov_b32_e32 v38, 0
	v_mov_b32_e32 v39, 0
	v_mov_b32_e32 v40, 0
	v_mov_b32_e32 v41, 0
	v_mov_b32_e32 v42, 0
	v_mov_b32_e32 v43, 0
	v_mov_b32_e32 v44, 0
	v_mov_b32_e32 v45, 0
	v_mov_b32_e32 v46, 0
	v_mov_b32_e32 v47, 0
	v_mov_b32_e32 v48, 0
	v_mov_b32_e32 v49, 0
	v_mov_b32_e32 v50, 0
	v_mov_b32_e32 v51, 0
	v_mov_b32_e32 v52, 0
	v_mov_b32_e32 v53, 0
	v_mov_b32_e32 v54, 0
	v_mov_b32_e32 v55, 0
	v_mov_b32_e32 v56, 0
	v_mov_b32_e32 v57, 0
	v_mov_b32_e32 v58, 0
	v_mov_b32_e32 v59, 0
	v_mov_b32_e32 v60, 0
	v_mov_b32_e32 v61, 0
	v_mov_b32_e32 v62, 0
	v_mov_b32_e32 v63, 0
	v_mov_b32_e32 v64, 0
	v_mov_b32_e32 v65, 0
	v_mov_b32_e32 v66, 0
	v_mov_b32_e32 v67, 0
	v_mov_b32_e32 v68, 0
	v_mov_b32_e32 v69, 0
	v_mov_b32_e32 v70, 0
	v_mov_b32_e32 v71, 0
	v_mov_b32_e32 v72, 0
	v_mov_b32_e32 v73, 0
	v_mov_b32_e32 v74, 0
	v_mov_b32_e32 v75, 0
	v_mov_b32_e32 v76, 0
	v_mov_b32_e32 v77, 0
	v_mov_b32_e32 v78, 0
	v_mov_b32_e32 v79, 0
	v_mov_b32_e32 v80, 0
	v_mov_b32_e32 v81, 0
	v_mov_b32_e32 v82, 0
	v_mov_b32_e32 v83, 0
	v_mov_b32_e32 v84, 0
	v_mov_b32_e32 v85, 0
	v_mov_b32_e32 v86, 0
	v_mov_b32_e32 v87, 0
	v_mov_b32_e32 v88, 0
	v_mov_b32_e32 v89, 0
	v_mov_b32_e32 v90, 0
	v_mov_b32_e32 v91, 0
	v_mov_b32_e32 v92, 0
	v_mov_b32_e32 v93, 0
	v_mov_b32_e32 v94, 0
	v_mov_b32_e32 v95, 0
	v_mov_b32_e32 v96, 0
	v_mov_b32_e32 v97, 0
	v_mov_b32_e32 v98, 0
	v_mov_b32_e32 v99, 0
	v_mov_b32_e32 v100, 0
	v_mov_b32_e32 v101, 0
	v_mov_b32_e32 v102, 0
	v_mov_b32_e32 v103, 0
	v_mov_b32_e32 v104, 0
	v_mov_b32_e32 v105, 0
	v_mov_b32_e32 v106, 0
	v_mov_b32_e32 v107, 0
	v_mov_b32_e32 v108, 0
	v_mov_b32_e32 v109, 0
	v_mov_b32_e32 v110, 0
	v_mov_b32_e32 v111, 0
	v_mov_b32_e32 v112, 0
	v_mov_b32_e32 v113, 0
	v_mov_b32_e32 v114, 0
	v_mov_b32_e32 v115, 0
	v_mov_b32_e32 v116, 0
	v_mov_b32_e32 v117, 0
	v_mov_b32_e32 v118, 0
	v_mov_b32_e32 v119, 0
	v_mov_b32_e32 v120, 0
	v_mov_b32_e32 v121, 0
	v_mov_b32_e32 v122, 0
	v_mov_b32_e32 v123, 0
	v_mov_b32_e32 v124, 0
	v_mov_b32_e32 v125, 0
	v_mov_b32_e32 v126, 0
	v_mov_b32_e32 v127, 0
	v_mov_b32_e32 v192, 0
	v_mov_b32_e32 v193, 0
	v_mov_b32_e32 v194, 0
	v_mov_b32_e32 v195, 0
	v_mov_b32_e32 v196, 0
	v_mov_b32_e32 v197, 0
	v_mov_b32_e32 v198, 0
	v_mov_b32_e32 v199, 0
	v_mov_b32_e32 v200, 0
	v_mov_b32_e32 v201, 0
	v_mov_b32_e32 v202, 0
	v_mov_b32_e32 v203, 0
	v_mov_b32_e32 v204, 0
	v_mov_b32_e32 v205, 0
	v_mov_b32_e32 v206, 0
	v_mov_b32_e32 v207, 0
	v_mov_b32_e32 v208, 0
	v_mov_b32_e32 v209, 0
	v_mov_b32_e32 v210, 0
	v_mov_b32_e32 v211, 0
	v_mov_b32_e32 v212, 0
	v_mov_b32_e32 v213, 0
	v_mov_b32_e32 v214, 0
	v_mov_b32_e32 v215, 0
	v_mov_b32_e32 v188, 0
	v_mov_b32_e32 v189, 0
	s_waitcnt vmcnt(8)
	ds_write_b128 v170, v[216:219] offset:0
	ds_write_b128 v170, v[220:223] offset:9216
	ds_write_b128 v170, v[224:227] offset:18432
	ds_write_b128 v170, v[228:231] offset:27648
	ds_write_b128 v171, v[232:235] offset:0
	ds_write_b128 v171, v[236:239] offset:9216
	ds_write_b128 v171, v[152:155] offset:18432
	ds_write_b128 v171, v[156:159] offset:27648
	buffer_load_dwordx4 v[216:219], v160, s[48:51], 0 offen
	buffer_load_dwordx4 v[220:223], v160, s[48:51], s46 offen
	buffer_load_dwordx4 v[224:227], v160, s[48:51], s47 offen
	buffer_load_dwordx4 v[228:231], v160, s[48:51], s58 offen
	buffer_load_dwordx4 v[232:235], v160, s[52:55], 0 offen
	buffer_load_dwordx4 v[236:239], v160, s[52:55], s46 offen
	buffer_load_dwordx4 v[152:155], v160, s[52:55], s47 offen
	buffer_load_dwordx4 v[156:159], v160, s[52:55], s58 offen
	v_add_u32_e32 v160, 0x80, v160
	s_waitcnt lgkmcnt(0)
	s_barrier
	s_movk_i32 s59, 14
.Lgin0_loop:
	ds_read_b128 v[144:147], v254 offset:0
	ds_read_b128 v[148:151], v254 offset:4608
	ds_read_b128 v[128:131], v175 offset:0
	ds_read_b128 v[132:135], v175 offset:4608
	ds_read_b128 v[136:139], v175 offset:9216
	ds_read_b128 v[140:143], v175 offset:13824
	v_mfma_f32_32x32x16_bf16 v[112:127], v[192:195], v[208:211], v[112:127]
	s_waitcnt vmcnt(8)
	v_mfma_f32_32x32x16_bf16 v[96:111], v[192:195], v[212:215], v[96:111]
	ds_write_b128 v170, v[162:165] offset:36864
	v_mfma_f32_32x32x16_bf16 v[80:95], v[196:199], v[208:211], v[80:95]
	ds_write_b128 v170, v[166:169] offset:46080
	v_mfma_f32_32x32x16_bf16 v[64:79], v[196:199], v[212:215], v[64:79]
	ds_write_b128 v170, v[176:179] offset:55296
	v_mfma_f32_32x32x16_bf16 v[48:63], v[200:203], v[208:211], v[48:63]
	ds_write_b128 v170, v[180:183] offset:64512
	v_mfma_f32_32x32x16_bf16 v[32:47], v[200:203], v[212:215], v[32:47]
	ds_write_b128 v171, v[184:187] offset:36864
	v_mfma_f32_32x32x16_bf16 v[16:31], v[204:207], v[208:211], v[16:31]
	ds_write_b128 v171, v[242:245] offset:46080
	v_mfma_f32_32x32x16_bf16 v[0:15], v[204:207], v[212:215], v[0:15]
	ds_write_b128 v171, v[246:249] offset:55296
	ds_write_b128 v171, v[250:253] offset:64512
	s_waitcnt lgkmcnt(8)
	v_mfma_f32_32x32x16_bf16 v[112:127], v[128:131], v[144:147], v[112:127]
	ds_read_b128 v[208:211], v254 offset:32
	v_mfma_f32_32x32x16_bf16 v[96:111], v[128:131], v[148:151], v[96:111]
	ds_read_b128 v[212:215], v254 offset:4640
	ds_read_b128 v[192:195], v175 offset:32
	v_mfma_f32_32x32x16_bf16 v[80:95], v[132:135], v[144:147], v[80:95]
	ds_read_b128 v[196:199], v175 offset:4640
	ds_read_b128 v[200:203], v175 offset:9248
	v_mfma_f32_32x32x16_bf16 v[64:79], v[132:135], v[148:151], v[64:79]
	ds_read_b128 v[204:207], v175 offset:13856
	buffer_load_dwordx4 v[162:165], v160, s[48:51], 0 offen
	v_mfma_f32_32x32x16_bf16 v[48:63], v[136:139], v[144:147], v[48:63]
	buffer_load_dwordx4 v[166:169], v160, s[48:51], s46 offen
	buffer_load_dwordx4 v[176:179], v160, s[48:51], s47 offen
	v_mfma_f32_32x32x16_bf16 v[32:47], v[136:139], v[148:151], v[32:47]
	buffer_load_dwordx4 v[180:183], v160, s[48:51], s58 offen
	buffer_load_dwordx4 v[184:187], v160, s[52:55], 0 offen
	v_mfma_f32_32x32x16_bf16 v[16:31], v[140:143], v[144:147], v[16:31]
	buffer_load_dwordx4 v[242:245], v160, s[52:55], s46 offen
	buffer_load_dwordx4 v[246:249], v160, s[52:55], s47 offen
	v_mfma_f32_32x32x16_bf16 v[0:15], v[140:143], v[148:151], v[0:15]
	buffer_load_dwordx4 v[250:253], v160, s[52:55], s58 offen
	v_add_u32_e32 v160, 0x80, v160
	s_waitcnt lgkmcnt(0)
	v_mfma_f32_32x32x16_bf16 v[112:127], v[192:195], v[208:211], v[112:127]
	v_mfma_f32_32x32x16_bf16 v[96:111], v[192:195], v[212:215], v[96:111]
	ds_read_b128 v[144:147], v254 offset:64
	v_mfma_f32_32x32x16_bf16 v[80:95], v[196:199], v[208:211], v[80:95]
	ds_read_b128 v[148:151], v254 offset:4672
	v_mfma_f32_32x32x16_bf16 v[64:79], v[196:199], v[212:215], v[64:79]
	ds_read_b128 v[128:131], v175 offset:64
	v_mfma_f32_32x32x16_bf16 v[48:63], v[200:203], v[208:211], v[48:63]
	v_mfma_f32_32x32x16_bf16 v[32:47], v[200:203], v[212:215], v[32:47]
	ds_read_b128 v[132:135], v175 offset:4672
	v_mfma_f32_32x32x16_bf16 v[16:31], v[204:207], v[208:211], v[16:31]
	ds_read_b128 v[136:139], v175 offset:9280
	v_mfma_f32_32x32x16_bf16 v[0:15], v[204:207], v[212:215], v[0:15]
	ds_read_b128 v[140:143], v175 offset:13888
	s_waitcnt lgkmcnt(0)
	v_mfma_f32_32x32x16_bf16 v[112:127], v[128:131], v[144:147], v[112:127]
	v_mfma_f32_32x32x16_bf16 v[96:111], v[128:131], v[148:151], v[96:111]
	ds_read_b128 v[208:211], v254 offset:96
	v_mfma_f32_32x32x16_bf16 v[80:95], v[132:135], v[144:147], v[80:95]
	ds_read_b128 v[212:215], v254 offset:4704
	v_mfma_f32_32x32x16_bf16 v[64:79], v[132:135], v[148:151], v[64:79]
	ds_read_b128 v[192:195], v175 offset:96
	v_mfma_f32_32x32x16_bf16 v[48:63], v[136:139], v[144:147], v[48:63]
	v_mfma_f32_32x32x16_bf16 v[32:47], v[136:139], v[148:151], v[32:47]
	ds_read_b128 v[196:199], v175 offset:4704
	v_mfma_f32_32x32x16_bf16 v[16:31], v[140:143], v[144:147], v[16:31]
	ds_read_b128 v[200:203], v175 offset:9312
	v_mfma_f32_32x32x16_bf16 v[0:15], v[140:143], v[148:151], v[0:15]
	ds_read_b128 v[204:207], v175 offset:13920
	s_waitcnt lgkmcnt(0)
	s_barrier
	ds_read_b128 v[144:147], v254 offset:36864
	ds_read_b128 v[148:151], v254 offset:41472
	ds_read_b128 v[128:131], v175 offset:36864
	ds_read_b128 v[132:135], v175 offset:41472
	ds_read_b128 v[136:139], v175 offset:46080
	ds_read_b128 v[140:143], v175 offset:50688
	v_mfma_f32_32x32x16_bf16 v[112:127], v[192:195], v[208:211], v[112:127]
	s_waitcnt vmcnt(8)
	v_mfma_f32_32x32x16_bf16 v[96:111], v[192:195], v[212:215], v[96:111]
	ds_write_b128 v170, v[216:219] offset:0
	v_mfma_f32_32x32x16_bf16 v[80:95], v[196:199], v[208:211], v[80:95]
	ds_write_b128 v170, v[220:223] offset:9216
	v_mfma_f32_32x32x16_bf16 v[64:79], v[196:199], v[212:215], v[64:79]
	ds_write_b128 v170, v[224:227] offset:18432
	v_mfma_f32_32x32x16_bf16 v[48:63], v[200:203], v[208:211], v[48:63]
	ds_write_b128 v170, v[228:231] offset:27648
	v_mfma_f32_32x32x16_bf16 v[32:47], v[200:203], v[212:215], v[32:47]
	ds_write_b128 v171, v[232:235] offset:0
	v_mfma_f32_32x32x16_bf16 v[16:31], v[204:207], v[208:211], v[16:31]
	ds_write_b128 v171, v[236:239] offset:9216
	v_mfma_f32_32x32x16_bf16 v[0:15], v[204:207], v[212:215], v[0:15]
	ds_write_b128 v171, v[152:155] offset:18432
	ds_write_b128 v171, v[156:159] offset:27648
	s_waitcnt lgkmcnt(8)
	v_mfma_f32_32x32x16_bf16 v[112:127], v[128:131], v[144:147], v[112:127]
	ds_read_b128 v[208:211], v254 offset:36896
	v_mfma_f32_32x32x16_bf16 v[96:111], v[128:131], v[148:151], v[96:111]
	ds_read_b128 v[212:215], v254 offset:41504
	ds_read_b128 v[192:195], v175 offset:36896
	v_mfma_f32_32x32x16_bf16 v[80:95], v[132:135], v[144:147], v[80:95]
	ds_read_b128 v[196:199], v175 offset:41504
	ds_read_b128 v[200:203], v175 offset:46112
	v_mfma_f32_32x32x16_bf16 v[64:79], v[132:135], v[148:151], v[64:79]
	ds_read_b128 v[204:207], v175 offset:50720
	buffer_load_dwordx4 v[216:219], v160, s[48:51], 0 offen
	v_mfma_f32_32x32x16_bf16 v[48:63], v[136:139], v[144:147], v[48:63]
	buffer_load_dwordx4 v[220:223], v160, s[48:51], s46 offen
	buffer_load_dwordx4 v[224:227], v160, s[48:51], s47 offen
	v_mfma_f32_32x32x16_bf16 v[32:47], v[136:139], v[148:151], v[32:47]
	buffer_load_dwordx4 v[228:231], v160, s[48:51], s58 offen
	buffer_load_dwordx4 v[232:235], v160, s[52:55], 0 offen
	v_mfma_f32_32x32x16_bf16 v[16:31], v[140:143], v[144:147], v[16:31]
	buffer_load_dwordx4 v[236:239], v160, s[52:55], s46 offen
	buffer_load_dwordx4 v[152:155], v160, s[52:55], s47 offen
	v_mfma_f32_32x32x16_bf16 v[0:15], v[140:143], v[148:151], v[0:15]
	buffer_load_dwordx4 v[156:159], v160, s[52:55], s58 offen
	v_add_u32_e32 v160, 0x80, v160
	s_waitcnt lgkmcnt(0)
	v_mfma_f32_32x32x16_bf16 v[112:127], v[192:195], v[208:211], v[112:127]
	v_mfma_f32_32x32x16_bf16 v[96:111], v[192:195], v[212:215], v[96:111]
	ds_read_b128 v[144:147], v254 offset:36928
	v_mfma_f32_32x32x16_bf16 v[80:95], v[196:199], v[208:211], v[80:95]
	ds_read_b128 v[148:151], v254 offset:41536
	v_mfma_f32_32x32x16_bf16 v[64:79], v[196:199], v[212:215], v[64:79]
	ds_read_b128 v[128:131], v175 offset:36928
	v_mfma_f32_32x32x16_bf16 v[48:63], v[200:203], v[208:211], v[48:63]
	v_mfma_f32_32x32x16_bf16 v[32:47], v[200:203], v[212:215], v[32:47]
	ds_read_b128 v[132:135], v175 offset:41536
	v_mfma_f32_32x32x16_bf16 v[16:31], v[204:207], v[208:211], v[16:31]
	ds_read_b128 v[136:139], v175 offset:46144
	v_mfma_f32_32x32x16_bf16 v[0:15], v[204:207], v[212:215], v[0:15]
	ds_read_b128 v[140:143], v175 offset:50752
	s_waitcnt lgkmcnt(0)
	v_mfma_f32_32x32x16_bf16 v[112:127], v[128:131], v[144:147], v[112:127]
	v_mfma_f32_32x32x16_bf16 v[96:111], v[128:131], v[148:151], v[96:111]
	ds_read_b128 v[208:211], v254 offset:36960
	v_mfma_f32_32x32x16_bf16 v[80:95], v[132:135], v[144:147], v[80:95]
	ds_read_b128 v[212:215], v254 offset:41568
	v_mfma_f32_32x32x16_bf16 v[64:79], v[132:135], v[148:151], v[64:79]
	ds_read_b128 v[192:195], v175 offset:36960
	v_mfma_f32_32x32x16_bf16 v[48:63], v[136:139], v[144:147], v[48:63]
	v_mfma_f32_32x32x16_bf16 v[32:47], v[136:139], v[148:151], v[32:47]
	ds_read_b128 v[196:199], v175 offset:41568
	v_mfma_f32_32x32x16_bf16 v[16:31], v[140:143], v[144:147], v[16:31]
	ds_read_b128 v[200:203], v175 offset:46176
	v_mfma_f32_32x32x16_bf16 v[0:15], v[140:143], v[148:151], v[0:15]
	ds_read_b128 v[204:207], v175 offset:50784
	s_waitcnt lgkmcnt(0)
	s_barrier
	s_add_i32 s59, s59, -1
	s_cmp_lg_u32 s59, 0
	s_cbranch_scc1 .Lgin0_loop
	ds_read_b128 v[144:147], v254 offset:0
	ds_read_b128 v[148:151], v254 offset:4608
	ds_read_b128 v[128:131], v175 offset:0
	ds_read_b128 v[132:135], v175 offset:4608
	ds_read_b128 v[136:139], v175 offset:9216
	ds_read_b128 v[140:143], v175 offset:13824
	v_mfma_f32_32x32x16_bf16 v[112:127], v[192:195], v[208:211], v[112:127]
	s_waitcnt vmcnt(8)
	v_mfma_f32_32x32x16_bf16 v[96:111], v[192:195], v[212:215], v[96:111]
	ds_write_b128 v170, v[162:165] offset:36864
	v_mfma_f32_32x32x16_bf16 v[80:95], v[196:199], v[208:211], v[80:95]
	ds_write_b128 v170, v[166:169] offset:46080
	v_mfma_f32_32x32x16_bf16 v[64:79], v[196:199], v[212:215], v[64:79]
	ds_write_b128 v170, v[176:179] offset:55296
	v_mfma_f32_32x32x16_bf16 v[48:63], v[200:203], v[208:211], v[48:63]
	ds_write_b128 v170, v[180:183] offset:64512
	v_mfma_f32_32x32x16_bf16 v[32:47], v[200:203], v[212:215], v[32:47]
	ds_write_b128 v171, v[184:187] offset:36864
	v_mfma_f32_32x32x16_bf16 v[16:31], v[204:207], v[208:211], v[16:31]
	ds_write_b128 v171, v[242:245] offset:46080
	v_mfma_f32_32x32x16_bf16 v[0:15], v[204:207], v[212:215], v[0:15]
	ds_write_b128 v171, v[246:249] offset:55296
	ds_write_b128 v171, v[250:253] offset:64512
	s_waitcnt lgkmcnt(8)
	v_mfma_f32_32x32x16_bf16 v[112:127], v[128:131], v[144:147], v[112:127]
	ds_read_b128 v[208:211], v254 offset:32
	v_mfma_f32_32x32x16_bf16 v[96:111], v[128:131], v[148:151], v[96:111]
	ds_read_b128 v[212:215], v254 offset:4640
	ds_read_b128 v[192:195], v175 offset:32
	v_mfma_f32_32x32x16_bf16 v[80:95], v[132:135], v[144:147], v[80:95]
	ds_read_b128 v[196:199], v175 offset:4640
	ds_read_b128 v[200:203], v175 offset:9248
	v_mfma_f32_32x32x16_bf16 v[64:79], v[132:135], v[148:151], v[64:79]
	ds_read_b128 v[204:207], v175 offset:13856
	buffer_load_dwordx4 v[162:165], v160, s[48:51], 0 offen
	v_mfma_f32_32x32x16_bf16 v[48:63], v[136:139], v[144:147], v[48:63]
	buffer_load_dwordx4 v[166:169], v160, s[48:51], s46 offen
	buffer_load_dwordx4 v[176:179], v160, s[48:51], s47 offen
	v_mfma_f32_32x32x16_bf16 v[32:47], v[136:139], v[148:151], v[32:47]
	buffer_load_dwordx4 v[180:183], v160, s[48:51], s58 offen
	buffer_load_dwordx4 v[184:187], v160, s[52:55], 0 offen
	v_mfma_f32_32x32x16_bf16 v[16:31], v[140:143], v[144:147], v[16:31]
	buffer_load_dwordx4 v[242:245], v160, s[52:55], s46 offen
	buffer_load_dwordx4 v[246:249], v160, s[52:55], s47 offen
	v_mfma_f32_32x32x16_bf16 v[0:15], v[140:143], v[148:151], v[0:15]
	buffer_load_dwordx4 v[250:253], v160, s[52:55], s58 offen
	v_add_u32_e32 v160, 0x80, v160
	s_waitcnt lgkmcnt(0)
	v_mfma_f32_32x32x16_bf16 v[112:127], v[192:195], v[208:211], v[112:127]
	v_mfma_f32_32x32x16_bf16 v[96:111], v[192:195], v[212:215], v[96:111]
	ds_read_b128 v[144:147], v254 offset:64
	v_mfma_f32_32x32x16_bf16 v[80:95], v[196:199], v[208:211], v[80:95]
	ds_read_b128 v[148:151], v254 offset:4672
	v_mfma_f32_32x32x16_bf16 v[64:79], v[196:199], v[212:215], v[64:79]
	ds_read_b128 v[128:131], v175 offset:64
	v_mfma_f32_32x32x16_bf16 v[48:63], v[200:203], v[208:211], v[48:63]
	v_mfma_f32_32x32x16_bf16 v[32:47], v[200:203], v[212:215], v[32:47]
	ds_read_b128 v[132:135], v175 offset:4672
	v_mfma_f32_32x32x16_bf16 v[16:31], v[204:207], v[208:211], v[16:31]
	ds_read_b128 v[136:139], v175 offset:9280
	v_mfma_f32_32x32x16_bf16 v[0:15], v[204:207], v[212:215], v[0:15]
	ds_read_b128 v[140:143], v175 offset:13888
	s_waitcnt lgkmcnt(0)
	v_mfma_f32_32x32x16_bf16 v[112:127], v[128:131], v[144:147], v[112:127]
	v_mfma_f32_32x32x16_bf16 v[96:111], v[128:131], v[148:151], v[96:111]
	ds_read_b128 v[208:211], v254 offset:96
	v_mfma_f32_32x32x16_bf16 v[80:95], v[132:135], v[144:147], v[80:95]
	ds_read_b128 v[212:215], v254 offset:4704
	v_mfma_f32_32x32x16_bf16 v[64:79], v[132:135], v[148:151], v[64:79]
	ds_read_b128 v[192:195], v175 offset:96
	v_mfma_f32_32x32x16_bf16 v[48:63], v[136:139], v[144:147], v[48:63]
	v_mfma_f32_32x32x16_bf16 v[32:47], v[136:139], v[148:151], v[32:47]
	ds_read_b128 v[196:199], v175 offset:4704
	v_mfma_f32_32x32x16_bf16 v[16:31], v[140:143], v[144:147], v[16:31]
	ds_read_b128 v[200:203], v175 offset:9312
	v_mfma_f32_32x32x16_bf16 v[0:15], v[140:143], v[148:151], v[0:15]
	ds_read_b128 v[204:207], v175 offset:13920
	s_waitcnt lgkmcnt(0)
	s_barrier
	ds_read_b128 v[144:147], v254 offset:36864
	ds_read_b128 v[148:151], v254 offset:41472
	ds_read_b128 v[128:131], v175 offset:36864
	ds_read_b128 v[132:135], v175 offset:41472
	ds_read_b128 v[136:139], v175 offset:46080
	ds_read_b128 v[140:143], v175 offset:50688
	v_mfma_f32_32x32x16_bf16 v[112:127], v[192:195], v[208:211], v[112:127]
	s_waitcnt vmcnt(8)
	v_mfma_f32_32x32x16_bf16 v[96:111], v[192:195], v[212:215], v[96:111]
	ds_write_b128 v170, v[216:219] offset:0
	v_mfma_f32_32x32x16_bf16 v[80:95], v[196:199], v[208:211], v[80:95]
	ds_write_b128 v170, v[220:223] offset:9216
	v_mfma_f32_32x32x16_bf16 v[64:79], v[196:199], v[212:215], v[64:79]
	ds_write_b128 v170, v[224:227] offset:18432
	v_mfma_f32_32x32x16_bf16 v[48:63], v[200:203], v[208:211], v[48:63]
	ds_write_b128 v170, v[228:231] offset:27648
	v_mfma_f32_32x32x16_bf16 v[32:47], v[200:203], v[212:215], v[32:47]
	ds_write_b128 v171, v[232:235] offset:0
	v_mfma_f32_32x32x16_bf16 v[16:31], v[204:207], v[208:211], v[16:31]
	ds_write_b128 v171, v[236:239] offset:9216
	v_mfma_f32_32x32x16_bf16 v[0:15], v[204:207], v[212:215], v[0:15]
	ds_write_b128 v171, v[152:155] offset:18432
	ds_write_b128 v171, v[156:159] offset:27648
	s_waitcnt lgkmcnt(8)
	v_mfma_f32_32x32x16_bf16 v[112:127], v[128:131], v[144:147], v[112:127]
	v_mfma_f32_32x32x16_bf16 v[96:111], v[128:131], v[148:151], v[96:111]
	ds_read_b128 v[208:211], v254 offset:36896
	v_mfma_f32_32x32x16_bf16 v[80:95], v[132:135], v[144:147], v[80:95]
	ds_read_b128 v[212:215], v254 offset:41504
	v_mfma_f32_32x32x16_bf16 v[64:79], v[132:135], v[148:151], v[64:79]
	ds_read_b128 v[192:195], v175 offset:36896
	v_mfma_f32_32x32x16_bf16 v[48:63], v[136:139], v[144:147], v[48:63]
	v_mfma_f32_32x32x16_bf16 v[32:47], v[136:139], v[148:151], v[32:47]
	ds_read_b128 v[196:199], v175 offset:41504
	v_mfma_f32_32x32x16_bf16 v[16:31], v[140:143], v[144:147], v[16:31]
	ds_read_b128 v[200:203], v175 offset:46112
	v_mfma_f32_32x32x16_bf16 v[0:15], v[140:143], v[148:151], v[0:15]
	ds_read_b128 v[204:207], v175 offset:50720
	s_waitcnt lgkmcnt(0)
	v_mfma_f32_32x32x16_bf16 v[112:127], v[192:195], v[208:211], v[112:127]
	v_mfma_f32_32x32x16_bf16 v[96:111], v[192:195], v[212:215], v[96:111]
	ds_read_b128 v[144:147], v254 offset:36928
	v_mfma_f32_32x32x16_bf16 v[80:95], v[196:199], v[208:211], v[80:95]
	ds_read_b128 v[148:151], v254 offset:41536
	v_mfma_f32_32x32x16_bf16 v[64:79], v[196:199], v[212:215], v[64:79]
	ds_read_b128 v[128:131], v175 offset:36928
	v_mfma_f32_32x32x16_bf16 v[48:63], v[200:203], v[208:211], v[48:63]
	v_mfma_f32_32x32x16_bf16 v[32:47], v[200:203], v[212:215], v[32:47]
	ds_read_b128 v[132:135], v175 offset:41536
	v_mfma_f32_32x32x16_bf16 v[16:31], v[204:207], v[208:211], v[16:31]
	ds_read_b128 v[136:139], v175 offset:46144
	v_mfma_f32_32x32x16_bf16 v[0:15], v[204:207], v[212:215], v[0:15]
	ds_read_b128 v[140:143], v175 offset:50752
	s_waitcnt lgkmcnt(0)
	v_mfma_f32_32x32x16_bf16 v[112:127], v[128:131], v[144:147], v[112:127]
	v_mfma_f32_32x32x16_bf16 v[96:111], v[128:131], v[148:151], v[96:111]
	ds_read_b128 v[208:211], v254 offset:36960
	v_mfma_f32_32x32x16_bf16 v[80:95], v[132:135], v[144:147], v[80:95]
	ds_read_b128 v[212:215], v254 offset:41568
	v_mfma_f32_32x32x16_bf16 v[64:79], v[132:135], v[148:151], v[64:79]
	ds_read_b128 v[192:195], v175 offset:36960
	v_mfma_f32_32x32x16_bf16 v[48:63], v[136:139], v[144:147], v[48:63]
	v_mfma_f32_32x32x16_bf16 v[32:47], v[136:139], v[148:151], v[32:47]
	ds_read_b128 v[196:199], v175 offset:41568
	v_mfma_f32_32x32x16_bf16 v[16:31], v[140:143], v[144:147], v[16:31]
	ds_read_b128 v[200:203], v175 offset:46176
	v_mfma_f32_32x32x16_bf16 v[0:15], v[140:143], v[148:151], v[0:15]
	ds_read_b128 v[204:207], v175 offset:50784
	s_waitcnt lgkmcnt(0)
	s_barrier
	ds_read_b128 v[144:147], v254 offset:0
	ds_read_b128 v[148:151], v254 offset:4608
	ds_read_b128 v[128:131], v175 offset:0
	ds_read_b128 v[132:135], v175 offset:4608
	ds_read_b128 v[136:139], v175 offset:9216
	ds_read_b128 v[140:143], v175 offset:13824
	v_mfma_f32_32x32x16_bf16 v[112:127], v[192:195], v[208:211], v[112:127]
	s_waitcnt vmcnt(0)
	v_mfma_f32_32x32x16_bf16 v[96:111], v[192:195], v[212:215], v[96:111]
	ds_write_b128 v170, v[162:165] offset:36864
	v_mfma_f32_32x32x16_bf16 v[80:95], v[196:199], v[208:211], v[80:95]
	ds_write_b128 v170, v[166:169] offset:46080
	v_mfma_f32_32x32x16_bf16 v[64:79], v[196:199], v[212:215], v[64:79]
	ds_write_b128 v170, v[176:179] offset:55296
	v_mfma_f32_32x32x16_bf16 v[48:63], v[200:203], v[208:211], v[48:63]
	ds_write_b128 v170, v[180:183] offset:64512
	v_mfma_f32_32x32x16_bf16 v[32:47], v[200:203], v[212:215], v[32:47]
	ds_write_b128 v171, v[184:187] offset:36864
	v_mfma_f32_32x32x16_bf16 v[16:31], v[204:207], v[208:211], v[16:31]
	ds_write_b128 v171, v[242:245] offset:46080
	v_mfma_f32_32x32x16_bf16 v[0:15], v[204:207], v[212:215], v[0:15]
	ds_write_b128 v171, v[246:249] offset:55296
	ds_write_b128 v171, v[250:253] offset:64512
	s_waitcnt lgkmcnt(8)
	v_mfma_f32_32x32x16_bf16 v[112:127], v[128:131], v[144:147], v[112:127]
	v_mfma_f32_32x32x16_bf16 v[96:111], v[128:131], v[148:151], v[96:111]
	ds_read_b128 v[208:211], v254 offset:32
	v_mfma_f32_32x32x16_bf16 v[80:95], v[132:135], v[144:147], v[80:95]
	ds_read_b128 v[212:215], v254 offset:4640
	v_mfma_f32_32x32x16_bf16 v[64:79], v[132:135], v[148:151], v[64:79]
	ds_read_b128 v[192:195], v175 offset:32
	v_mfma_f32_32x32x16_bf16 v[48:63], v[136:139], v[144:147], v[48:63]
	v_mfma_f32_32x32x16_bf16 v[32:47], v[136:139], v[148:151], v[32:47]
	ds_read_b128 v[196:199], v175 offset:4640
	v_mfma_f32_32x32x16_bf16 v[16:31], v[140:143], v[144:147], v[16:31]
	ds_read_b128 v[200:203], v175 offset:9248
	v_mfma_f32_32x32x16_bf16 v[0:15], v[140:143], v[148:151], v[0:15]
	ds_read_b128 v[204:207], v175 offset:13856
	s_waitcnt lgkmcnt(0)
	v_mfma_f32_32x32x16_bf16 v[112:127], v[192:195], v[208:211], v[112:127]
	v_mfma_f32_32x32x16_bf16 v[96:111], v[192:195], v[212:215], v[96:111]
	ds_read_b128 v[144:147], v254 offset:64
	v_mfma_f32_32x32x16_bf16 v[80:95], v[196:199], v[208:211], v[80:95]
	ds_read_b128 v[148:151], v254 offset:4672
	v_mfma_f32_32x32x16_bf16 v[64:79], v[196:199], v[212:215], v[64:79]
	ds_read_b128 v[128:131], v175 offset:64
	v_mfma_f32_32x32x16_bf16 v[48:63], v[200:203], v[208:211], v[48:63]
	v_mfma_f32_32x32x16_bf16 v[32:47], v[200:203], v[212:215], v[32:47]
	ds_read_b128 v[132:135], v175 offset:4672
	v_mfma_f32_32x32x16_bf16 v[16:31], v[204:207], v[208:211], v[16:31]
	ds_read_b128 v[136:139], v175 offset:9280
	v_mfma_f32_32x32x16_bf16 v[0:15], v[204:207], v[212:215], v[0:15]
	ds_read_b128 v[140:143], v175 offset:13888
	s_waitcnt lgkmcnt(0)
	v_mfma_f32_32x32x16_bf16 v[112:127], v[128:131], v[144:147], v[112:127]
	v_mfma_f32_32x32x16_bf16 v[96:111], v[128:131], v[148:151], v[96:111]
	ds_read_b128 v[208:211], v254 offset:96
	v_mfma_f32_32x32x16_bf16 v[80:95], v[132:135], v[144:147], v[80:95]
	ds_read_b128 v[212:215], v254 offset:4704
	v_mfma_f32_32x32x16_bf16 v[64:79], v[132:135], v[148:151], v[64:79]
	ds_read_b128 v[192:195], v175 offset:96
	v_mfma_f32_32x32x16_bf16 v[48:63], v[136:139], v[144:147], v[48:63]
	v_mfma_f32_32x32x16_bf16 v[32:47], v[136:139], v[148:151], v[32:47]
	ds_read_b128 v[196:199], v175 offset:4704
	v_mfma_f32_32x32x16_bf16 v[16:31], v[140:143], v[144:147], v[16:31]
	ds_read_b128 v[200:203], v175 offset:9312
	v_mfma_f32_32x32x16_bf16 v[0:15], v[140:143], v[148:151], v[0:15]
	ds_read_b128 v[204:207], v175 offset:13920
	s_waitcnt lgkmcnt(0)
	s_barrier
	ds_read_b128 v[144:147], v254 offset:36864
	ds_read_b128 v[148:151], v254 offset:41472
	ds_read_b128 v[128:131], v175 offset:36864
	ds_read_b128 v[132:135], v175 offset:41472
	ds_read_b128 v[136:139], v175 offset:46080
	ds_read_b128 v[140:143], v175 offset:50688
	v_mfma_f32_32x32x16_bf16 v[112:127], v[192:195], v[208:211], v[112:127]
	v_mfma_f32_32x32x16_bf16 v[96:111], v[192:195], v[212:215], v[96:111]
	v_mfma_f32_32x32x16_bf16 v[80:95], v[196:199], v[208:211], v[80:95]
	v_mfma_f32_32x32x16_bf16 v[64:79], v[196:199], v[212:215], v[64:79]
	v_mfma_f32_32x32x16_bf16 v[48:63], v[200:203], v[208:211], v[48:63]
	v_mfma_f32_32x32x16_bf16 v[32:47], v[200:203], v[212:215], v[32:47]
	v_mfma_f32_32x32x16_bf16 v[16:31], v[204:207], v[208:211], v[16:31]
	v_mfma_f32_32x32x16_bf16 v[0:15], v[204:207], v[212:215], v[0:15]
	s_waitcnt lgkmcnt(0)
	v_mfma_f32_32x32x16_bf16 v[112:127], v[128:131], v[144:147], v[112:127]
	v_mfma_f32_32x32x16_bf16 v[96:111], v[128:131], v[148:151], v[96:111]
	ds_read_b128 v[208:211], v254 offset:36896
	v_mfma_f32_32x32x16_bf16 v[80:95], v[132:135], v[144:147], v[80:95]
	ds_read_b128 v[212:215], v254 offset:41504
	v_mfma_f32_32x32x16_bf16 v[64:79], v[132:135], v[148:151], v[64:79]
	ds_read_b128 v[192:195], v175 offset:36896
	v_mfma_f32_32x32x16_bf16 v[48:63], v[136:139], v[144:147], v[48:63]
	v_mfma_f32_32x32x16_bf16 v[32:47], v[136:139], v[148:151], v[32:47]
	ds_read_b128 v[196:199], v175 offset:41504
	v_mfma_f32_32x32x16_bf16 v[16:31], v[140:143], v[144:147], v[16:31]
	ds_read_b128 v[200:203], v175 offset:46112
	v_mfma_f32_32x32x16_bf16 v[0:15], v[140:143], v[148:151], v[0:15]
	ds_read_b128 v[204:207], v175 offset:50720
	s_waitcnt lgkmcnt(0)
	v_mfma_f32_32x32x16_bf16 v[112:127], v[192:195], v[208:211], v[112:127]
	v_mfma_f32_32x32x16_bf16 v[96:111], v[192:195], v[212:215], v[96:111]
	ds_read_b128 v[144:147], v254 offset:36928
	v_mfma_f32_32x32x16_bf16 v[80:95], v[196:199], v[208:211], v[80:95]
	ds_read_b128 v[148:151], v254 offset:41536
	v_mfma_f32_32x32x16_bf16 v[64:79], v[196:199], v[212:215], v[64:79]
	ds_read_b128 v[128:131], v175 offset:36928
	v_mfma_f32_32x32x16_bf16 v[48:63], v[200:203], v[208:211], v[48:63]
	v_mfma_f32_32x32x16_bf16 v[32:47], v[200:203], v[212:215], v[32:47]
	ds_read_b128 v[132:135], v175 offset:41536
	v_mfma_f32_32x32x16_bf16 v[16:31], v[204:207], v[208:211], v[16:31]
	ds_read_b128 v[136:139], v175 offset:46144
	v_mfma_f32_32x32x16_bf16 v[0:15], v[204:207], v[212:215], v[0:15]
	ds_read_b128 v[140:143], v175 offset:50752
	s_waitcnt lgkmcnt(0)
	v_mfma_f32_32x32x16_bf16 v[112:127], v[128:131], v[144:147], v[112:127]
	v_mfma_f32_32x32x16_bf16 v[96:111], v[128:131], v[148:151], v[96:111]
	ds_read_b128 v[208:211], v254 offset:36960
	v_mfma_f32_32x32x16_bf16 v[80:95], v[132:135], v[144:147], v[80:95]
	ds_read_b128 v[212:215], v254 offset:41568
	v_mfma_f32_32x32x16_bf16 v[64:79], v[132:135], v[148:151], v[64:79]
	ds_read_b128 v[192:195], v175 offset:36960
	v_mfma_f32_32x32x16_bf16 v[48:63], v[136:139], v[144:147], v[48:63]
	v_mfma_f32_32x32x16_bf16 v[32:47], v[136:139], v[148:151], v[32:47]
	ds_read_b128 v[196:199], v175 offset:41568
	v_mfma_f32_32x32x16_bf16 v[16:31], v[140:143], v[144:147], v[16:31]
	ds_read_b128 v[200:203], v175 offset:46176
	v_mfma_f32_32x32x16_bf16 v[0:15], v[140:143], v[148:151], v[0:15]
	ds_read_b128 v[204:207], v175 offset:50784
	s_waitcnt lgkmcnt(0)
	s_barrier
	v_mfma_f32_32x32x16_bf16 v[112:127], v[192:195], v[208:211], v[112:127]
	v_mfma_f32_32x32x16_bf16 v[96:111], v[192:195], v[212:215], v[96:111]
	v_mfma_f32_32x32x16_bf16 v[80:95], v[196:199], v[208:211], v[80:95]
	v_mfma_f32_32x32x16_bf16 v[64:79], v[196:199], v[212:215], v[64:79]
	v_mfma_f32_32x32x16_bf16 v[48:63], v[200:203], v[208:211], v[48:63]
	v_mfma_f32_32x32x16_bf16 v[32:47], v[200:203], v[212:215], v[32:47]
	v_mfma_f32_32x32x16_bf16 v[16:31], v[204:207], v[208:211], v[16:31]
	v_mfma_f32_32x32x16_bf16 v[0:15], v[204:207], v[212:215], v[0:15]
	s_nop 7
	s_nop 7
	s_mul_i32 s100, s64, 0x2700
	s_mul_hi_u32 s101, s64, 0x2700
	s_add_u32 s100, s100, 0xa224000
	s_addc_u32 s101, s101, 0
	s_add_u32 s96, s92, s100
	s_addc_u32 s97, s93, s101
	s_and_b32 s97, s97, 0xffff
	s_mov_b32 s98, 0x270000
	s_mov_b32 s99, 0x20000
	v_and_b32_e32 v132, 31, v190
	v_bfe_u32 v133, v190, 5, 1
	v_bfe_u32 v134, v190, 6, 2
	v_bfe_u32 v135, v190, 8, 1
	v_lshl_add_u32 v132, v134, 6, v132
	v_add_u32_e32 v132, s82, v132
	v_cmp_gt_u32_e32 vcc, 0x1380, v132
	s_mov_b64 s[74:75], vcc
	v_add_u32_e32 v136, 32, v132
	v_cmp_gt_u32_e32 vcc, 0x1380, v136
	s_mov_b64 s[76:77], vcc
	v_lshlrev_b32_e32 v132, 1, v132
	v_lshlrev_b32_e32 v135, 7, v135
	v_lshl_add_u32 v135, v133, 2, v135
	s_mov_b32 s47, 0x2700
	v_mul_lo_u32 v135, s47, v135
	v_add_u32_e32 v128, v135, v132
	v_add_u32_e32 v129, 0x2700, v128
	v_add_u32_e32 v130, 0x4e00, v128
	v_add_u32_e32 v131, 0x7500, v128
	s_add_i32 s36, s36, s94
	s_cmpk_lt_i32 s36, 0x500
	s_cbranch_scc0 .Lgin0_last
	s_bfe_u32 s100, s36, 0x30005
	s_and_b32 s101, s36, 31
	s_lshr_b32 s82, s36, 8
	s_lshr_b32 s64, s100, 2
	s_lshl_b32 s64, s64, 5
	s_add_u32 s64, s64, s101
	s_lshl_b32 s82, s82, 2
	s_and_b32 s100, s100, 3
	s_add_u32 s82, s82, s100
	s_lshl_b32 s64, s64, 8
	s_lshl_b32 s82, s82, 8
	s_lshl_b32 s100, s64, 12
	s_add_u32 s100, s100, 0x6224000
	s_add_u32 s48, s92, s100
	s_addc_u32 s49, s93, 0
	s_and_b32 s49, s49, 0xffff
	s_mov_b32 s50, 0x100000
	s_mov_b32 s51, 0x20000
	s_lshl_b32 s100, s82, 12
	s_add_u32 s100, s100, 0x0
	s_add_u32 s52, s92, s100
	s_addc_u32 s53, s93, 0
	s_and_b32 s53, s53, 0xffff
	s_sub_u32 s100, 0x1380, s82
	s_min_u32 s100, s100, 0x100
	s_lshl_b32 s54, s100, 12
	s_mov_b32 s55, 0x20000
	s_mov_b32 s46, 0x40000
	s_mov_b32 s47, 0x80000
	s_mov_b32 s58, 0xc0000
	v_lshrrev_b32_e32 v137, 3, v190
	v_and_b32_e32 v138, 7, v190
	v_lshlrev_b32_e32 v138, 4, v138
	v_lshl_add_u32 v160, v137, 12, v138
	buffer_load_dwordx4 v[216:219], v160, s[48:51], 0 offen
	buffer_load_dwordx4 v[220:223], v160, s[48:51], s46 offen
	buffer_load_dwordx4 v[224:227], v160, s[48:51], s47 offen
	buffer_load_dwordx4 v[228:231], v160, s[48:51], s58 offen
	buffer_load_dwordx4 v[232:235], v160, s[52:55], 0 offen
	buffer_load_dwordx4 v[236:239], v160, s[52:55], s46 offen
	buffer_load_dwordx4 v[152:155], v160, s[52:55], s47 offen
	buffer_load_dwordx4 v[156:159], v160, s[52:55], s58 offen
	v_add_u32_e32 v160, 0x80, v160
	buffer_load_dwordx4 v[162:165], v160, s[48:51], 0 offen
	buffer_load_dwordx4 v[166:169], v160, s[48:51], s46 offen
	buffer_load_dwordx4 v[176:179], v160, s[48:51], s47 offen
	buffer_load_dwordx4 v[180:183], v160, s[48:51], s58 offen
	buffer_load_dwordx4 v[184:187], v160, s[52:55], 0 offen
	buffer_load_dwordx4 v[242:245], v160, s[52:55], s46 offen
	buffer_load_dwordx4 v[246:249], v160, s[52:55], s47 offen
	buffer_load_dwordx4 v[250:253], v160, s[52:55], s58 offen
	v_add_u32_e32 v160, 0x80, v160
.Lgin0_last:
	s_movk_i32 s46, 0x7fff
	s_mov_b64 exec, s[74:75]
	s_cbranch_execz .Lgskip_0_0
	v_bfe_u32 v136, v112, 16, 1
	v_bfe_u32 v137, v113, 16, 1
	v_bfe_u32 v138, v114, 16, 1
	v_bfe_u32 v139, v115, 16, 1
	v_add3_u32 v112, v112, v136, s46
	v_add3_u32 v113, v113, v137, s46
	v_add3_u32 v114, v114, v138, s46
	v_add3_u32 v115, v115, v139, s46
	s_mov_b32 s101, 0x0
	buffer_store_short_d16_hi v112, v128, s[96:99], s101 offen
	buffer_store_short_d16_hi v113, v129, s[96:99], s101 offen
	buffer_store_short_d16_hi v114, v130, s[96:99], s101 offen
	buffer_store_short_d16_hi v115, v131, s[96:99], s101 offen
	v_bfe_u32 v136, v116, 16, 1
	v_bfe_u32 v137, v117, 16, 1
	v_bfe_u32 v138, v118, 16, 1
	v_bfe_u32 v139, v119, 16, 1
	v_add3_u32 v116, v116, v136, s46
	v_add3_u32 v117, v117, v137, s46
	v_add3_u32 v118, v118, v138, s46
	v_add3_u32 v119, v119, v139, s46
	s_mov_b32 s101, 0x13800
	buffer_store_short_d16_hi v116, v128, s[96:99], s101 offen
	buffer_store_short_d16_hi v117, v129, s[96:99], s101 offen
	buffer_store_short_d16_hi v118, v130, s[96:99], s101 offen
	buffer_store_short_d16_hi v119, v131, s[96:99], s101 offen
	v_bfe_u32 v136, v120, 16, 1
	v_bfe_u32 v137, v121, 16, 1
	v_bfe_u32 v138, v122, 16, 1
	v_bfe_u32 v139, v123, 16, 1
	v_add3_u32 v120, v120, v136, s46
	v_add3_u32 v121, v121, v137, s46
	v_add3_u32 v122, v122, v138, s46
	v_add3_u32 v123, v123, v139, s46
	s_mov_b32 s101, 0x27000
	buffer_store_short_d16_hi v120, v128, s[96:99], s101 offen
	buffer_store_short_d16_hi v121, v129, s[96:99], s101 offen
	buffer_store_short_d16_hi v122, v130, s[96:99], s101 offen
	buffer_store_short_d16_hi v123, v131, s[96:99], s101 offen
	v_bfe_u32 v136, v124, 16, 1
	v_bfe_u32 v137, v125, 16, 1
	v_bfe_u32 v138, v126, 16, 1
	v_bfe_u32 v139, v127, 16, 1
	v_add3_u32 v124, v124, v136, s46
	v_add3_u32 v125, v125, v137, s46
	v_add3_u32 v126, v126, v138, s46
	v_add3_u32 v127, v127, v139, s46
	s_mov_b32 s101, 0x3a800
	buffer_store_short_d16_hi v124, v128, s[96:99], s101 offen
	buffer_store_short_d16_hi v125, v129, s[96:99], s101 offen
	buffer_store_short_d16_hi v126, v130, s[96:99], s101 offen
	buffer_store_short_d16_hi v127, v131, s[96:99], s101 offen

.Lgskip_3_1:
	s_mov_b64 exec, -1
	s_cmpk_lt_i32 s36, 0x500
	s_cbranch_scc1 .Lgin0_tile
	s_branch .LBB0_211

.LBB0_1415:
	s_bfe_u32 s100, s39, 0x30005
	s_and_b32 s101, s39, 31
	s_lshr_b32 s82, s39, 8
	s_lshl_b32 s64, s82, 5
	s_lshr_b32 s82, s100, 3
	s_lshl_b32 s82, s82, 5
	s_add_u32 s64, s64, s82
	s_lshr_b32 s82, s101, 0
	s_add_u32 s64, s64, s82
	s_and_b32 s82, s100, 7
	s_lshl_b32 s82, s82, 0
	s_and_b32 s101, s101, 0
	s_add_u32 s82, s82, s101
	s_lshl_b32 s64, s64, 8
	s_lshl_b32 s82, s82, 8
	s_lshl_b32 s100, s64, 12
	s_add_u32 s100, s100, 0x6224000
	s_add_u32 s48, s92, s100
	s_addc_u32 s49, s93, 0
	s_and_b32 s49, s49, 0xffff
	s_mov_b32 s50, 0x100000
	s_mov_b32 s51, 0x20000
	s_lshl_b32 s100, s82, 12
	s_add_u32 s100, s100, 0x3b80000
	s_add_u32 s52, s92, s100
	s_addc_u32 s53, s93, 0
	s_and_b32 s53, s53, 0xffff
	s_sub_u32 s100, 0x800, s82
	s_min_u32 s100, s100, 0x100
	s_lshl_b32 s54, s100, 12
	s_mov_b32 s55, 0x20000
	s_mov_b32 s46, 0x40000
	s_mov_b32 s47, 0x80000
	s_mov_b32 s58, 0xc0000
	v_lshrrev_b32_e32 v128, 3, v190
	v_and_b32_e32 v129, 7, v190
	v_lshlrev_b32_e32 v129, 4, v129
	v_lshl_add_u32 v160, v128, 12, v129
	v_mul_u32_u24_e32 v130, 0x90, v128
	v_add_u32_e32 v170, v130, v129
	v_add_u32_e32 v171, 0x12000, v170
	v_and_b32_e32 v131, 31, v190
	v_bfe_u32 v132, v190, 5, 1
	v_bfe_u32 v133, v190, 6, 2
	v_bfe_u32 v134, v190, 8, 1
	v_lshl_add_u32 v135, v134, 7, v131
	v_mul_u32_u24_e32 v135, 0x90, v135
	v_lshl_add_u32 v175, v132, 4, v135
	v_lshl_add_u32 v136, v133, 6, v131
	v_mul_u32_u24_e32 v136, 0x90, v136
	v_lshl_add_u32 v136, v132, 4, v136
	v_add_u32_e32 v254, 0x12000, v136
	buffer_load_dwordx4 v[216:219], v160, s[48:51], 0 offen
	buffer_load_dwordx4 v[220:223], v160, s[48:51], s46 offen
	buffer_load_dwordx4 v[224:227], v160, s[48:51], s47 offen
	buffer_load_dwordx4 v[228:231], v160, s[48:51], s58 offen
	buffer_load_dwordx4 v[232:235], v160, s[52:55], 0 offen
	buffer_load_dwordx4 v[236:239], v160, s[52:55], s46 offen
	buffer_load_dwordx4 v[152:155], v160, s[52:55], s47 offen
	buffer_load_dwordx4 v[156:159], v160, s[52:55], s58 offen
	v_add_u32_e32 v160, 0x80, v160
	buffer_load_dwordx4 v[162:165], v160, s[48:51], 0 offen
	buffer_load_dwordx4 v[166:169], v160, s[48:51], s46 offen
	buffer_load_dwordx4 v[176:179], v160, s[48:51], s47 offen
	buffer_load_dwordx4 v[180:183], v160, s[48:51], s58 offen
	buffer_load_dwordx4 v[184:187], v160, s[52:55], 0 offen
	buffer_load_dwordx4 v[242:245], v160, s[52:55], s46 offen
	buffer_load_dwordx4 v[246:249], v160, s[52:55], s47 offen
	buffer_load_dwordx4 v[250:253], v160, s[52:55], s58 offen
	v_add_u32_e32 v160, 0x80, v160

.Lgwq0_loop:
	ds_read_b128 v[144:147], v254 offset:0
	ds_read_b128 v[148:151], v254 offset:4608
	ds_read_b128 v[128:131], v175 offset:0
	ds_read_b128 v[132:135], v175 offset:4608
	ds_read_b128 v[136:139], v175 offset:9216
	ds_read_b128 v[140:143], v175 offset:13824
	v_mfma_f32_32x32x16_bf16 v[112:127], v[192:195], v[208:211], v[112:127]
	s_waitcnt vmcnt(8)
	v_mfma_f32_32x32x16_bf16 v[96:111], v[192:195], v[212:215], v[96:111]
	ds_write_b128 v170, v[162:165] offset:36864
	v_mfma_f32_32x32x16_bf16 v[80:95], v[196:199], v[208:211], v[80:95]
	ds_write_b128 v170, v[166:169] offset:46080
	v_mfma_f32_32x32x16_bf16 v[64:79], v[196:199], v[212:215], v[64:79]
	ds_write_b128 v170, v[176:179] offset:55296
	v_mfma_f32_32x32x16_bf16 v[48:63], v[200:203], v[208:211], v[48:63]
	ds_write_b128 v170, v[180:183] offset:64512
	v_mfma_f32_32x32x16_bf16 v[32:47], v[200:203], v[212:215], v[32:47]
	ds_write_b128 v171, v[184:187] offset:36864
	v_mfma_f32_32x32x16_bf16 v[16:31], v[204:207], v[208:211], v[16:31]
	ds_write_b128 v171, v[242:245] offset:46080
	v_mfma_f32_32x32x16_bf16 v[0:15], v[204:207], v[212:215], v[0:15]
	ds_write_b128 v171, v[246:249] offset:55296
	ds_write_b128 v171, v[250:253] offset:64512
	s_waitcnt lgkmcnt(8)
	v_mfma_f32_32x32x16_bf16 v[112:127], v[128:131], v[144:147], v[112:127]
	ds_read_b128 v[208:211], v254 offset:32
	v_mfma_f32_32x32x16_bf16 v[96:111], v[128:131], v[148:151], v[96:111]
	ds_read_b128 v[212:215], v254 offset:4640
	ds_read_b128 v[192:195], v175 offset:32
	v_mfma_f32_32x32x16_bf16 v[80:95], v[132:135], v[144:147], v[80:95]
	ds_read_b128 v[196:199], v175 offset:4640
	ds_read_b128 v[200:203], v175 offset:9248
	v_mfma_f32_32x32x16_bf16 v[64:79], v[132:135], v[148:151], v[64:79]
	ds_read_b128 v[204:207], v175 offset:13856
	buffer_load_dwordx4 v[162:165], v160, s[48:51], 0 offen
	v_mfma_f32_32x32x16_bf16 v[48:63], v[136:139], v[144:147], v[48:63]
	buffer_load_dwordx4 v[166:169], v160, s[48:51], s46 offen
	buffer_load_dwordx4 v[176:179], v160, s[48:51], s47 offen
	v_mfma_f32_32x32x16_bf16 v[32:47], v[136:139], v[148:151], v[32:47]
	buffer_load_dwordx4 v[180:183], v160, s[48:51], s58 offen
	buffer_load_dwordx4 v[184:187], v160, s[52:55], 0 offen
	v_mfma_f32_32x32x16_bf16 v[16:31], v[140:143], v[144:147], v[16:31]
	buffer_load_dwordx4 v[242:245], v160, s[52:55], s46 offen
	buffer_load_dwordx4 v[246:249], v160, s[52:55], s47 offen
	v_mfma_f32_32x32x16_bf16 v[0:15], v[140:143], v[148:151], v[0:15]
	buffer_load_dwordx4 v[250:253], v160, s[52:55], s58 offen
	v_add_u32_e32 v160, 0x80, v160
	s_waitcnt lgkmcnt(0)
	v_mfma_f32_32x32x16_bf16 v[112:127], v[192:195], v[208:211], v[112:127]
	v_mfma_f32_32x32x16_bf16 v[96:111], v[192:195], v[212:215], v[96:111]
	ds_read_b128 v[144:147], v254 offset:64
	v_mfma_f32_32x32x16_bf16 v[80:95], v[196:199], v[208:211], v[80:95]
	ds_read_b128 v[148:151], v254 offset:4672
	v_mfma_f32_32x32x16_bf16 v[64:79], v[196:199], v[212:215], v[64:79]
	ds_read_b128 v[128:131], v175 offset:64
	v_mfma_f32_32x32x16_bf16 v[48:63], v[200:203], v[208:211], v[48:63]
	v_mfma_f32_32x32x16_bf16 v[32:47], v[200:203], v[212:215], v[32:47]
	ds_read_b128 v[132:135], v175 offset:4672
	v_mfma_f32_32x32x16_bf16 v[16:31], v[204:207], v[208:211], v[16:31]
	ds_read_b128 v[136:139], v175 offset:9280
	v_mfma_f32_32x32x16_bf16 v[0:15], v[204:207], v[212:215], v[0:15]
	ds_read_b128 v[140:143], v175 offset:13888
	s_waitcnt lgkmcnt(0)
	v_mfma_f32_32x32x16_bf16 v[112:127], v[128:131], v[144:147], v[112:127]
	v_mfma_f32_32x32x16_bf16 v[96:111], v[128:131], v[148:151], v[96:111]
	ds_read_b128 v[208:211], v254 offset:96
	v_mfma_f32_32x32x16_bf16 v[80:95], v[132:135], v[144:147], v[80:95]
	ds_read_b128 v[212:215], v254 offset:4704
	v_mfma_f32_32x32x16_bf16 v[64:79], v[132:135], v[148:151], v[64:79]
	ds_read_b128 v[192:195], v175 offset:96
	v_mfma_f32_32x32x16_bf16 v[48:63], v[136:139], v[144:147], v[48:63]
	v_mfma_f32_32x32x16_bf16 v[32:47], v[136:139], v[148:151], v[32:47]
	ds_read_b128 v[196:199], v175 offset:4704
	v_mfma_f32_32x32x16_bf16 v[16:31], v[140:143], v[144:147], v[16:31]
	ds_read_b128 v[200:203], v175 offset:9312
	v_mfma_f32_32x32x16_bf16 v[0:15], v[140:143], v[148:151], v[0:15]
	ds_read_b128 v[204:207], v175 offset:13920
	s_waitcnt lgkmcnt(0)
	s_barrier
	ds_read_b128 v[144:147], v254 offset:36864
	ds_read_b128 v[148:151], v254 offset:41472
	ds_read_b128 v[128:131], v175 offset:36864
	ds_read_b128 v[132:135], v175 offset:41472
	ds_read_b128 v[136:139], v175 offset:46080
	ds_read_b128 v[140:143], v175 offset:50688
	v_mfma_f32_32x32x16_bf16 v[112:127], v[192:195], v[208:211], v[112:127]
	s_waitcnt vmcnt(8)
	v_mfma_f32_32x32x16_bf16 v[96:111], v[192:195], v[212:215], v[96:111]
	ds_write_b128 v170, v[216:219] offset:0
	v_mfma_f32_32x32x16_bf16 v[80:95], v[196:199], v[208:211], v[80:95]
	ds_write_b128 v170, v[220:223] offset:9216
	v_mfma_f32_32x32x16_bf16 v[64:79], v[196:199], v[212:215], v[64:79]
	ds_write_b128 v170, v[224:227] offset:18432
	v_mfma_f32_32x32x16_bf16 v[48:63], v[200:203], v[208:211], v[48:63]
	ds_write_b128 v170, v[228:231] offset:27648
	v_mfma_f32_32x32x16_bf16 v[32:47], v[200:203], v[212:215], v[32:47]
	ds_write_b128 v171, v[232:235] offset:0
	v_mfma_f32_32x32x16_bf16 v[16:31], v[204:207], v[208:211], v[16:31]
	ds_write_b128 v171, v[236:239] offset:9216
	v_mfma_f32_32x32x16_bf16 v[0:15], v[204:207], v[212:215], v[0:15]
	ds_write_b128 v171, v[152:155] offset:18432
	ds_write_b128 v171, v[156:159] offset:27648
	s_waitcnt lgkmcnt(8)
	v_mfma_f32_32x32x16_bf16 v[112:127], v[128:131], v[144:147], v[112:127]
	ds_read_b128 v[208:211], v254 offset:36896
	v_mfma_f32_32x32x16_bf16 v[96:111], v[128:131], v[148:151], v[96:111]
	ds_read_b128 v[212:215], v254 offset:41504
	ds_read_b128 v[192:195], v175 offset:36896
	v_mfma_f32_32x32x16_bf16 v[80:95], v[132:135], v[144:147], v[80:95]
	ds_read_b128 v[196:199], v175 offset:41504
	ds_read_b128 v[200:203], v175 offset:46112
	v_mfma_f32_32x32x16_bf16 v[64:79], v[132:135], v[148:151], v[64:79]
	ds_read_b128 v[204:207], v175 offset:50720
	buffer_load_dwordx4 v[216:219], v160, s[48:51], 0 offen
	v_mfma_f32_32x32x16_bf16 v[48:63], v[136:139], v[144:147], v[48:63]
	buffer_load_dwordx4 v[220:223], v160, s[48:51], s46 offen
	buffer_load_dwordx4 v[224:227], v160, s[48:51], s47 offen
	v_mfma_f32_32x32x16_bf16 v[32:47], v[136:139], v[148:151], v[32:47]
	buffer_load_dwordx4 v[228:231], v160, s[48:51], s58 offen
	buffer_load_dwordx4 v[232:235], v160, s[52:55], 0 offen
	v_mfma_f32_32x32x16_bf16 v[16:31], v[140:143], v[144:147], v[16:31]
	buffer_load_dwordx4 v[236:239], v160, s[52:55], s46 offen
	buffer_load_dwordx4 v[152:155], v160, s[52:55], s47 offen
	v_mfma_f32_32x32x16_bf16 v[0:15], v[140:143], v[148:151], v[0:15]
	buffer_load_dwordx4 v[156:159], v160, s[52:55], s58 offen
	v_add_u32_e32 v160, 0x80, v160
	s_waitcnt lgkmcnt(0)
	v_mfma_f32_32x32x16_bf16 v[112:127], v[192:195], v[208:211], v[112:127]
	v_mfma_f32_32x32x16_bf16 v[96:111], v[192:195], v[212:215], v[96:111]
	ds_read_b128 v[144:147], v254 offset:36928
	v_mfma_f32_32x32x16_bf16 v[80:95], v[196:199], v[208:211], v[80:95]
	ds_read_b128 v[148:151], v254 offset:41536
	v_mfma_f32_32x32x16_bf16 v[64:79], v[196:199], v[212:215], v[64:79]
	ds_read_b128 v[128:131], v175 offset:36928
	v_mfma_f32_32x32x16_bf16 v[48:63], v[200:203], v[208:211], v[48:63]
	v_mfma_f32_32x32x16_bf16 v[32:47], v[200:203], v[212:215], v[32:47]
	ds_read_b128 v[132:135], v175 offset:41536
	v_mfma_f32_32x32x16_bf16 v[16:31], v[204:207], v[208:211], v[16:31]
	ds_read_b128 v[136:139], v175 offset:46144
	v_mfma_f32_32x32x16_bf16 v[0:15], v[204:207], v[212:215], v[0:15]
	ds_read_b128 v[140:143], v175 offset:50752
	s_waitcnt lgkmcnt(0)
	v_mfma_f32_32x32x16_bf16 v[112:127], v[128:131], v[144:147], v[112:127]
	v_mfma_f32_32x32x16_bf16 v[96:111], v[128:131], v[148:151], v[96:111]
	ds_read_b128 v[208:211], v254 offset:36960
	v_mfma_f32_32x32x16_bf16 v[80:95], v[132:135], v[144:147], v[80:95]
	ds_read_b128 v[212:215], v254 offset:41568
	v_mfma_f32_32x32x16_bf16 v[64:79], v[132:135], v[148:151], v[64:79]
	ds_read_b128 v[192:195], v175 offset:36960
	v_mfma_f32_32x32x16_bf16 v[48:63], v[136:139], v[144:147], v[48:63]
	v_mfma_f32_32x32x16_bf16 v[32:47], v[136:139], v[148:151], v[32:47]
	ds_read_b128 v[196:199], v175 offset:41568
	v_mfma_f32_32x32x16_bf16 v[16:31], v[140:143], v[144:147], v[16:31]
	ds_read_b128 v[200:203], v175 offset:46176
	v_mfma_f32_32x32x16_bf16 v[0:15], v[140:143], v[148:151], v[0:15]
	ds_read_b128 v[204:207], v175 offset:50784
	s_waitcnt lgkmcnt(0)
	s_barrier
	s_add_i32 s59, s59, -1
	s_cmp_lg_u32 s59, 0
	s_cbranch_scc1 .Lgwq0_loop
	ds_read_b128 v[144:147], v254 offset:0
	ds_read_b128 v[148:151], v254 offset:4608
	ds_read_b128 v[128:131], v175 offset:0
	ds_read_b128 v[132:135], v175 offset:4608
	ds_read_b128 v[136:139], v175 offset:9216
	ds_read_b128 v[140:143], v175 offset:13824
	v_mfma_f32_32x32x16_bf16 v[112:127], v[192:195], v[208:211], v[112:127]
	s_waitcnt vmcnt(8)
	v_mfma_f32_32x32x16_bf16 v[96:111], v[192:195], v[212:215], v[96:111]
	ds_write_b128 v170, v[162:165] offset:36864
	v_mfma_f32_32x32x16_bf16 v[80:95], v[196:199], v[208:211], v[80:95]
	ds_write_b128 v170, v[166:169] offset:46080
	v_mfma_f32_32x32x16_bf16 v[64:79], v[196:199], v[212:215], v[64:79]
	ds_write_b128 v170, v[176:179] offset:55296
	v_mfma_f32_32x32x16_bf16 v[48:63], v[200:203], v[208:211], v[48:63]
	ds_write_b128 v170, v[180:183] offset:64512
	v_mfma_f32_32x32x16_bf16 v[32:47], v[200:203], v[212:215], v[32:47]
	ds_write_b128 v171, v[184:187] offset:36864
	v_mfma_f32_32x32x16_bf16 v[16:31], v[204:207], v[208:211], v[16:31]
	ds_write_b128 v171, v[242:245] offset:46080
	v_mfma_f32_32x32x16_bf16 v[0:15], v[204:207], v[212:215], v[0:15]
	ds_write_b128 v171, v[246:249] offset:55296
	ds_write_b128 v171, v[250:253] offset:64512
	s_waitcnt lgkmcnt(8)
	v_mfma_f32_32x32x16_bf16 v[112:127], v[128:131], v[144:147], v[112:127]
	ds_read_b128 v[208:211], v254 offset:32
	v_mfma_f32_32x32x16_bf16 v[96:111], v[128:131], v[148:151], v[96:111]
	ds_read_b128 v[212:215], v254 offset:4640
	ds_read_b128 v[192:195], v175 offset:32
	v_mfma_f32_32x32x16_bf16 v[80:95], v[132:135], v[144:147], v[80:95]
	ds_read_b128 v[196:199], v175 offset:4640
	ds_read_b128 v[200:203], v175 offset:9248
	v_mfma_f32_32x32x16_bf16 v[64:79], v[132:135], v[148:151], v[64:79]
	ds_read_b128 v[204:207], v175 offset:13856
	buffer_load_dwordx4 v[162:165], v160, s[48:51], 0 offen
	v_mfma_f32_32x32x16_bf16 v[48:63], v[136:139], v[144:147], v[48:63]
	buffer_load_dwordx4 v[166:169], v160, s[48:51], s46 offen
	buffer_load_dwordx4 v[176:179], v160, s[48:51], s47 offen
	v_mfma_f32_32x32x16_bf16 v[32:47], v[136:139], v[148:151], v[32:47]
	buffer_load_dwordx4 v[180:183], v160, s[48:51], s58 offen
	buffer_load_dwordx4 v[184:187], v160, s[52:55], 0 offen
	v_mfma_f32_32x32x16_bf16 v[16:31], v[140:143], v[144:147], v[16:31]
	buffer_load_dwordx4 v[242:245], v160, s[52:55], s46 offen
	buffer_load_dwordx4 v[246:249], v160, s[52:55], s47 offen
	v_mfma_f32_32x32x16_bf16 v[0:15], v[140:143], v[148:151], v[0:15]
	buffer_load_dwordx4 v[250:253], v160, s[52:55], s58 offen
	v_add_u32_e32 v160, 0x80, v160
	s_waitcnt lgkmcnt(0)
	v_mfma_f32_32x32x16_bf16 v[112:127], v[192:195], v[208:211], v[112:127]
	v_mfma_f32_32x32x16_bf16 v[96:111], v[192:195], v[212:215], v[96:111]
	ds_read_b128 v[144:147], v254 offset:64
	v_mfma_f32_32x32x16_bf16 v[80:95], v[196:199], v[208:211], v[80:95]
	ds_read_b128 v[148:151], v254 offset:4672
	v_mfma_f32_32x32x16_bf16 v[64:79], v[196:199], v[212:215], v[64:79]
	ds_read_b128 v[128:131], v175 offset:64
	v_mfma_f32_32x32x16_bf16 v[48:63], v[200:203], v[208:211], v[48:63]
	v_mfma_f32_32x32x16_bf16 v[32:47], v[200:203], v[212:215], v[32:47]
	ds_read_b128 v[132:135], v175 offset:4672
	v_mfma_f32_32x32x16_bf16 v[16:31], v[204:207], v[208:211], v[16:31]
	ds_read_b128 v[136:139], v175 offset:9280
	v_mfma_f32_32x32x16_bf16 v[0:15], v[204:207], v[212:215], v[0:15]
	ds_read_b128 v[140:143], v175 offset:13888
	s_waitcnt lgkmcnt(0)
	v_mfma_f32_32x32x16_bf16 v[112:127], v[128:131], v[144:147], v[112:127]
	v_mfma_f32_32x32x16_bf16 v[96:111], v[128:131], v[148:151], v[96:111]
	ds_read_b128 v[208:211], v254 offset:96
	v_mfma_f32_32x32x16_bf16 v[80:95], v[132:135], v[144:147], v[80:95]
	ds_read_b128 v[212:215], v254 offset:4704
	v_mfma_f32_32x32x16_bf16 v[64:79], v[132:135], v[148:151], v[64:79]
	ds_read_b128 v[192:195], v175 offset:96
	v_mfma_f32_32x32x16_bf16 v[48:63], v[136:139], v[144:147], v[48:63]
	v_mfma_f32_32x32x16_bf16 v[32:47], v[136:139], v[148:151], v[32:47]
	ds_read_b128 v[196:199], v175 offset:4704
	v_mfma_f32_32x32x16_bf16 v[16:31], v[140:143], v[144:147], v[16:31]
	ds_read_b128 v[200:203], v175 offset:9312
	v_mfma_f32_32x32x16_bf16 v[0:15], v[140:143], v[148:151], v[0:15]
	ds_read_b128 v[204:207], v175 offset:13920
	s_waitcnt lgkmcnt(0)
	s_barrier
	ds_read_b128 v[144:147], v254 offset:36864
	ds_read_b128 v[148:151], v254 offset:41472
	ds_read_b128 v[128:131], v175 offset:36864
	ds_read_b128 v[132:135], v175 offset:41472
	ds_read_b128 v[136:139], v175 offset:46080
	ds_read_b128 v[140:143], v175 offset:50688
	v_mfma_f32_32x32x16_bf16 v[112:127], v[192:195], v[208:211], v[112:127]
	s_waitcnt vmcnt(8)
	v_mfma_f32_32x32x16_bf16 v[96:111], v[192:195], v[212:215], v[96:111]
	ds_write_b128 v170, v[216:219] offset:0
	v_mfma_f32_32x32x16_bf16 v[80:95], v[196:199], v[208:211], v[80:95]
	ds_write_b128 v170, v[220:223] offset:9216
	v_mfma_f32_32x32x16_bf16 v[64:79], v[196:199], v[212:215], v[64:79]
	ds_write_b128 v170, v[224:227] offset:18432
	v_mfma_f32_32x32x16_bf16 v[48:63], v[200:203], v[208:211], v[48:63]
	ds_write_b128 v170, v[228:231] offset:27648
	v_mfma_f32_32x32x16_bf16 v[32:47], v[200:203], v[212:215], v[32:47]
	ds_write_b128 v171, v[232:235] offset:0
	v_mfma_f32_32x32x16_bf16 v[16:31], v[204:207], v[208:211], v[16:31]
	ds_write_b128 v171, v[236:239] offset:9216
	v_mfma_f32_32x32x16_bf16 v[0:15], v[204:207], v[212:215], v[0:15]
	ds_write_b128 v171, v[152:155] offset:18432
	ds_write_b128 v171, v[156:159] offset:27648
	s_waitcnt lgkmcnt(8)
	v_mfma_f32_32x32x16_bf16 v[112:127], v[128:131], v[144:147], v[112:127]
	v_mfma_f32_32x32x16_bf16 v[96:111], v[128:131], v[148:151], v[96:111]
	ds_read_b128 v[208:211], v254 offset:36896
	v_mfma_f32_32x32x16_bf16 v[80:95], v[132:135], v[144:147], v[80:95]
	ds_read_b128 v[212:215], v254 offset:41504
	v_mfma_f32_32x32x16_bf16 v[64:79], v[132:135], v[148:151], v[64:79]
	ds_read_b128 v[192:195], v175 offset:36896
	v_mfma_f32_32x32x16_bf16 v[48:63], v[136:139], v[144:147], v[48:63]
	v_mfma_f32_32x32x16_bf16 v[32:47], v[136:139], v[148:151], v[32:47]
	ds_read_b128 v[196:199], v175 offset:41504
	v_mfma_f32_32x32x16_bf16 v[16:31], v[140:143], v[144:147], v[16:31]
	ds_read_b128 v[200:203], v175 offset:46112
	v_mfma_f32_32x32x16_bf16 v[0:15], v[140:143], v[148:151], v[0:15]
	ds_read_b128 v[204:207], v175 offset:50720
	s_waitcnt lgkmcnt(0)
	v_mfma_f32_32x32x16_bf16 v[112:127], v[192:195], v[208:211], v[112:127]
	v_mfma_f32_32x32x16_bf16 v[96:111], v[192:195], v[212:215], v[96:111]
	ds_read_b128 v[144:147], v254 offset:36928
	v_mfma_f32_32x32x16_bf16 v[80:95], v[196:199], v[208:211], v[80:95]
	ds_read_b128 v[148:151], v254 offset:41536
	v_mfma_f32_32x32x16_bf16 v[64:79], v[196:199], v[212:215], v[64:79]
	ds_read_b128 v[128:131], v175 offset:36928
	v_mfma_f32_32x32x16_bf16 v[48:63], v[200:203], v[208:211], v[48:63]
	v_mfma_f32_32x32x16_bf16 v[32:47], v[200:203], v[212:215], v[32:47]
	ds_read_b128 v[132:135], v175 offset:41536
	v_mfma_f32_32x32x16_bf16 v[16:31], v[204:207], v[208:211], v[16:31]
	ds_read_b128 v[136:139], v175 offset:46144
	v_mfma_f32_32x32x16_bf16 v[0:15], v[204:207], v[212:215], v[0:15]
	ds_read_b128 v[140:143], v175 offset:50752
	s_waitcnt lgkmcnt(0)
	v_mfma_f32_32x32x16_bf16 v[112:127], v[128:131], v[144:147], v[112:127]
	v_mfma_f32_32x32x16_bf16 v[96:111], v[128:131], v[148:151], v[96:111]
	ds_read_b128 v[208:211], v254 offset:36960
	v_mfma_f32_32x32x16_bf16 v[80:95], v[132:135], v[144:147], v[80:95]
	ds_read_b128 v[212:215], v254 offset:41568
	v_mfma_f32_32x32x16_bf16 v[64:79], v[132:135], v[148:151], v[64:79]
	ds_read_b128 v[192:195], v175 offset:36960
	v_mfma_f32_32x32x16_bf16 v[48:63], v[136:139], v[144:147], v[48:63]
	v_mfma_f32_32x32x16_bf16 v[32:47], v[136:139], v[148:151], v[32:47]
	ds_read_b128 v[196:199], v175 offset:41568
	v_mfma_f32_32x32x16_bf16 v[16:31], v[140:143], v[144:147], v[16:31]
	ds_read_b128 v[200:203], v175 offset:46176
	v_mfma_f32_32x32x16_bf16 v[0:15], v[140:143], v[148:151], v[0:15]
	ds_read_b128 v[204:207], v175 offset:50784
	s_waitcnt lgkmcnt(0)
	s_barrier
	ds_read_b128 v[144:147], v254 offset:0
	ds_read_b128 v[148:151], v254 offset:4608
	ds_read_b128 v[128:131], v175 offset:0
	ds_read_b128 v[132:135], v175 offset:4608
	ds_read_b128 v[136:139], v175 offset:9216
	ds_read_b128 v[140:143], v175 offset:13824
	v_mfma_f32_32x32x16_bf16 v[112:127], v[192:195], v[208:211], v[112:127]
	s_waitcnt vmcnt(0)
	v_mfma_f32_32x32x16_bf16 v[96:111], v[192:195], v[212:215], v[96:111]
	ds_write_b128 v170, v[162:165] offset:36864
	v_mfma_f32_32x32x16_bf16 v[80:95], v[196:199], v[208:211], v[80:95]
	ds_write_b128 v170, v[166:169] offset:46080
	v_mfma_f32_32x32x16_bf16 v[64:79], v[196:199], v[212:215], v[64:79]
	ds_write_b128 v170, v[176:179] offset:55296
	v_mfma_f32_32x32x16_bf16 v[48:63], v[200:203], v[208:211], v[48:63]
	ds_write_b128 v170, v[180:183] offset:64512
	v_mfma_f32_32x32x16_bf16 v[32:47], v[200:203], v[212:215], v[32:47]
	ds_write_b128 v171, v[184:187] offset:36864
	v_mfma_f32_32x32x16_bf16 v[16:31], v[204:207], v[208:211], v[16:31]
	ds_write_b128 v171, v[242:245] offset:46080
	v_mfma_f32_32x32x16_bf16 v[0:15], v[204:207], v[212:215], v[0:15]
	ds_write_b128 v171, v[246:249] offset:55296
	ds_write_b128 v171, v[250:253] offset:64512
	s_waitcnt lgkmcnt(8)
	v_mfma_f32_32x32x16_bf16 v[112:127], v[128:131], v[144:147], v[112:127]
	v_mfma_f32_32x32x16_bf16 v[96:111], v[128:131], v[148:151], v[96:111]
	ds_read_b128 v[208:211], v254 offset:32
	v_mfma_f32_32x32x16_bf16 v[80:95], v[132:135], v[144:147], v[80:95]
	ds_read_b128 v[212:215], v254 offset:4640
	v_mfma_f32_32x32x16_bf16 v[64:79], v[132:135], v[148:151], v[64:79]
	ds_read_b128 v[192:195], v175 offset:32
	v_mfma_f32_32x32x16_bf16 v[48:63], v[136:139], v[144:147], v[48:63]
	v_mfma_f32_32x32x16_bf16 v[32:47], v[136:139], v[148:151], v[32:47]
	ds_read_b128 v[196:199], v175 offset:4640
	v_mfma_f32_32x32x16_bf16 v[16:31], v[140:143], v[144:147], v[16:31]
	ds_read_b128 v[200:203], v175 offset:9248
	v_mfma_f32_32x32x16_bf16 v[0:15], v[140:143], v[148:151], v[0:15]
	ds_read_b128 v[204:207], v175 offset:13856
	s_waitcnt lgkmcnt(0)
	v_mfma_f32_32x32x16_bf16 v[112:127], v[192:195], v[208:211], v[112:127]
	v_mfma_f32_32x32x16_bf16 v[96:111], v[192:195], v[212:215], v[96:111]
	ds_read_b128 v[144:147], v254 offset:64
	v_mfma_f32_32x32x16_bf16 v[80:95], v[196:199], v[208:211], v[80:95]
	ds_read_b128 v[148:151], v254 offset:4672
	v_mfma_f32_32x32x16_bf16 v[64:79], v[196:199], v[212:215], v[64:79]
	ds_read_b128 v[128:131], v175 offset:64
	v_mfma_f32_32x32x16_bf16 v[48:63], v[200:203], v[208:211], v[48:63]
	v_mfma_f32_32x32x16_bf16 v[32:47], v[200:203], v[212:215], v[32:47]
	ds_read_b128 v[132:135], v175 offset:4672
	v_mfma_f32_32x32x16_bf16 v[16:31], v[204:207], v[208:211], v[16:31]
	ds_read_b128 v[136:139], v175 offset:9280
	v_mfma_f32_32x32x16_bf16 v[0:15], v[204:207], v[212:215], v[0:15]
	ds_read_b128 v[140:143], v175 offset:13888
	s_waitcnt lgkmcnt(0)
	v_mfma_f32_32x32x16_bf16 v[112:127], v[128:131], v[144:147], v[112:127]
	v_mfma_f32_32x32x16_bf16 v[96:111], v[128:131], v[148:151], v[96:111]
	ds_read_b128 v[208:211], v254 offset:96
	v_mfma_f32_32x32x16_bf16 v[80:95], v[132:135], v[144:147], v[80:95]
	ds_read_b128 v[212:215], v254 offset:4704
	v_mfma_f32_32x32x16_bf16 v[64:79], v[132:135], v[148:151], v[64:79]
	ds_read_b128 v[192:195], v175 offset:96
	v_mfma_f32_32x32x16_bf16 v[48:63], v[136:139], v[144:147], v[48:63]
	v_mfma_f32_32x32x16_bf16 v[32:47], v[136:139], v[148:151], v[32:47]
	ds_read_b128 v[196:199], v175 offset:4704
	v_mfma_f32_32x32x16_bf16 v[16:31], v[140:143], v[144:147], v[16:31]
	ds_read_b128 v[200:203], v175 offset:9312
	v_mfma_f32_32x32x16_bf16 v[0:15], v[140:143], v[148:151], v[0:15]
	ds_read_b128 v[204:207], v175 offset:13920
	s_waitcnt lgkmcnt(0)
	s_barrier
	ds_read_b128 v[144:147], v254 offset:36864
	ds_read_b128 v[148:151], v254 offset:41472
	ds_read_b128 v[128:131], v175 offset:36864
	ds_read_b128 v[132:135], v175 offset:41472
	ds_read_b128 v[136:139], v175 offset:46080
	ds_read_b128 v[140:143], v175 offset:50688
	v_mfma_f32_32x32x16_bf16 v[112:127], v[192:195], v[208:211], v[112:127]
	v_mfma_f32_32x32x16_bf16 v[96:111], v[192:195], v[212:215], v[96:111]
	v_mfma_f32_32x32x16_bf16 v[80:95], v[196:199], v[208:211], v[80:95]
	v_mfma_f32_32x32x16_bf16 v[64:79], v[196:199], v[212:215], v[64:79]
	v_mfma_f32_32x32x16_bf16 v[48:63], v[200:203], v[208:211], v[48:63]
	v_mfma_f32_32x32x16_bf16 v[32:47], v[200:203], v[212:215], v[32:47]
	v_mfma_f32_32x32x16_bf16 v[16:31], v[204:207], v[208:211], v[16:31]
	v_mfma_f32_32x32x16_bf16 v[0:15], v[204:207], v[212:215], v[0:15]
	s_waitcnt lgkmcnt(0)
	v_mfma_f32_32x32x16_bf16 v[112:127], v[128:131], v[144:147], v[112:127]
	v_mfma_f32_32x32x16_bf16 v[96:111], v[128:131], v[148:151], v[96:111]
	ds_read_b128 v[208:211], v254 offset:36896
	v_mfma_f32_32x32x16_bf16 v[80:95], v[132:135], v[144:147], v[80:95]
	ds_read_b128 v[212:215], v254 offset:41504
	v_mfma_f32_32x32x16_bf16 v[64:79], v[132:135], v[148:151], v[64:79]
	ds_read_b128 v[192:195], v175 offset:36896
	v_mfma_f32_32x32x16_bf16 v[48:63], v[136:139], v[144:147], v[48:63]
	v_mfma_f32_32x32x16_bf16 v[32:47], v[136:139], v[148:151], v[32:47]
	ds_read_b128 v[196:199], v175 offset:41504
	v_mfma_f32_32x32x16_bf16 v[16:31], v[140:143], v[144:147], v[16:31]
	ds_read_b128 v[200:203], v175 offset:46112
	v_mfma_f32_32x32x16_bf16 v[0:15], v[140:143], v[148:151], v[0:15]
	ds_read_b128 v[204:207], v175 offset:50720
	s_waitcnt lgkmcnt(0)
	v_mfma_f32_32x32x16_bf16 v[112:127], v[192:195], v[208:211], v[112:127]
	v_mfma_f32_32x32x16_bf16 v[96:111], v[192:195], v[212:215], v[96:111]
	ds_read_b128 v[144:147], v254 offset:36928
	v_mfma_f32_32x32x16_bf16 v[80:95], v[196:199], v[208:211], v[80:95]
	ds_read_b128 v[148:151], v254 offset:41536
	v_mfma_f32_32x32x16_bf16 v[64:79], v[196:199], v[212:215], v[64:79]
	ds_read_b128 v[128:131], v175 offset:36928
	v_mfma_f32_32x32x16_bf16 v[48:63], v[200:203], v[208:211], v[48:63]
	v_mfma_f32_32x32x16_bf16 v[32:47], v[200:203], v[212:215], v[32:47]
	ds_read_b128 v[132:135], v175 offset:41536
	v_mfma_f32_32x32x16_bf16 v[16:31], v[204:207], v[208:211], v[16:31]
	ds_read_b128 v[136:139], v175 offset:46144
	v_mfma_f32_32x32x16_bf16 v[0:15], v[204:207], v[212:215], v[0:15]
	ds_read_b128 v[140:143], v175 offset:50752
	s_waitcnt lgkmcnt(0)
	v_mfma_f32_32x32x16_bf16 v[112:127], v[128:131], v[144:147], v[112:127]
	v_mfma_f32_32x32x16_bf16 v[96:111], v[128:131], v[148:151], v[96:111]
	ds_read_b128 v[208:211], v254 offset:36960
	v_mfma_f32_32x32x16_bf16 v[80:95], v[132:135], v[144:147], v[80:95]
	ds_read_b128 v[212:215], v254 offset:41568
	v_mfma_f32_32x32x16_bf16 v[64:79], v[132:135], v[148:151], v[64:79]
	ds_read_b128 v[192:195], v175 offset:36960
	v_mfma_f32_32x32x16_bf16 v[48:63], v[136:139], v[144:147], v[48:63]
	v_mfma_f32_32x32x16_bf16 v[32:47], v[136:139], v[148:151], v[32:47]
	ds_read_b128 v[196:199], v175 offset:41568
	v_mfma_f32_32x32x16_bf16 v[16:31], v[140:143], v[144:147], v[16:31]
	ds_read_b128 v[200:203], v175 offset:46176
	v_mfma_f32_32x32x16_bf16 v[0:15], v[140:143], v[148:151], v[0:15]
	ds_read_b128 v[204:207], v175 offset:50784
	s_waitcnt lgkmcnt(0)
	s_barrier
	v_mfma_f32_32x32x16_bf16 v[112:127], v[192:195], v[208:211], v[112:127]
	v_mfma_f32_32x32x16_bf16 v[96:111], v[192:195], v[212:215], v[96:111]
	v_mfma_f32_32x32x16_bf16 v[80:95], v[196:199], v[208:211], v[80:95]
	v_mfma_f32_32x32x16_bf16 v[64:79], v[196:199], v[212:215], v[64:79]
	v_mfma_f32_32x32x16_bf16 v[48:63], v[200:203], v[208:211], v[48:63]
	v_mfma_f32_32x32x16_bf16 v[32:47], v[200:203], v[212:215], v[32:47]
	v_mfma_f32_32x32x16_bf16 v[16:31], v[204:207], v[208:211], v[16:31]
	v_mfma_f32_32x32x16_bf16 v[0:15], v[204:207], v[212:215], v[0:15]
	s_nop 7
	s_nop 7
	s_mul_i32 s100, s64, 0x1000
	s_mul_hi_u32 s101, s64, 0x1000
	s_add_u32 s100, s100, 0xa224000
	s_addc_u32 s101, s101, 0
	s_add_u32 s96, s92, s100
	s_addc_u32 s97, s93, s101
	s_and_b32 s97, s97, 0xffff
	s_mov_b32 s98, 0x100000
	s_mov_b32 s99, 0x20000
	v_and_b32_e32 v132, 31, v190
	v_bfe_u32 v133, v190, 5, 1
	v_bfe_u32 v134, v190, 6, 2
	v_bfe_u32 v135, v190, 8, 1
	v_lshl_add_u32 v132, v134, 6, v132
	v_add_u32_e32 v132, s82, v132
	v_lshlrev_b32_e32 v132, 1, v132
	v_lshlrev_b32_e32 v135, 7, v135
	v_lshl_add_u32 v135, v133, 2, v135
	s_mov_b32 s47, 0x1000
	v_mul_lo_u32 v135, s47, v135
	v_add_u32_e32 v128, v135, v132
	v_add_u32_e32 v129, 0x1000, v128
	v_add_u32_e32 v130, 0x2000, v128
	v_add_u32_e32 v131, 0x3000, v128
	s_add_i32 s39, s39, s94
	s_cmpk_lt_i32 s39, 0x200
	s_cbranch_scc0 .Lgwq0_last
	s_bfe_u32 s100, s39, 0x30005
	s_and_b32 s101, s39, 31
	s_lshr_b32 s82, s39, 8
	s_lshl_b32 s64, s82, 5
	s_lshr_b32 s82, s100, 3
	s_lshl_b32 s82, s82, 5
	s_add_u32 s64, s64, s82
	s_lshr_b32 s82, s101, 0
	s_add_u32 s64, s64, s82
	s_and_b32 s82, s100, 7
	s_lshl_b32 s82, s82, 0
	s_and_b32 s101, s101, 0
	s_add_u32 s82, s82, s101
	s_lshl_b32 s64, s64, 8
	s_lshl_b32 s82, s82, 8
	s_lshl_b32 s100, s64, 12
	s_add_u32 s100, s100, 0x6224000
	s_add_u32 s48, s92, s100
	s_addc_u32 s49, s93, 0
	s_and_b32 s49, s49, 0xffff
	s_mov_b32 s50, 0x100000
	s_mov_b32 s51, 0x20000
	s_lshl_b32 s100, s82, 12
	s_add_u32 s100, s100, 0x3b80000
	s_add_u32 s52, s92, s100
	s_addc_u32 s53, s93, 0
	s_and_b32 s53, s53, 0xffff
	s_sub_u32 s100, 0x800, s82
	s_min_u32 s100, s100, 0x100
	s_lshl_b32 s54, s100, 12
	s_mov_b32 s55, 0x20000
	s_mov_b32 s46, 0x40000
	s_mov_b32 s47, 0x80000
	s_mov_b32 s58, 0xc0000
	v_lshrrev_b32_e32 v137, 3, v190
	v_and_b32_e32 v138, 7, v190
	v_lshlrev_b32_e32 v138, 4, v138
	v_lshl_add_u32 v160, v137, 12, v138
	buffer_load_dwordx4 v[216:219], v160, s[48:51], 0 offen
	buffer_load_dwordx4 v[220:223], v160, s[48:51], s46 offen
	buffer_load_dwordx4 v[224:227], v160, s[48:51], s47 offen
	buffer_load_dwordx4 v[228:231], v160, s[48:51], s58 offen
	buffer_load_dwordx4 v[232:235], v160, s[52:55], 0 offen
	buffer_load_dwordx4 v[236:239], v160, s[52:55], s46 offen
	buffer_load_dwordx4 v[152:155], v160, s[52:55], s47 offen
	buffer_load_dwordx4 v[156:159], v160, s[52:55], s58 offen
	v_add_u32_e32 v160, 0x80, v160
	buffer_load_dwordx4 v[162:165], v160, s[48:51], 0 offen
	buffer_load_dwordx4 v[166:169], v160, s[48:51], s46 offen
	buffer_load_dwordx4 v[176:179], v160, s[48:51], s47 offen
	buffer_load_dwordx4 v[180:183], v160, s[48:51], s58 offen
	buffer_load_dwordx4 v[184:187], v160, s[52:55], 0 offen
	buffer_load_dwordx4 v[242:245], v160, s[52:55], s46 offen
	buffer_load_dwordx4 v[246:249], v160, s[52:55], s47 offen
	buffer_load_dwordx4 v[250:253], v160, s[52:55], s58 offen
	v_add_u32_e32 v160, 0x80, v160
.Lgwq0_last:
	s_movk_i32 s46, 0x7fff
	v_bfe_u32 v136, v112, 16, 1
	v_bfe_u32 v137, v113, 16, 1
	v_bfe_u32 v138, v114, 16, 1
	v_bfe_u32 v139, v115, 16, 1
	v_add3_u32 v112, v112, v136, s46
	v_add3_u32 v113, v113, v137, s46
	v_add3_u32 v114, v114, v138, s46
	v_add3_u32 v115, v115, v139, s46
	s_mov_b32 s101, 0x0
	buffer_store_short_d16_hi v112, v128, s[96:99], s101 offen
	buffer_store_short_d16_hi v113, v129, s[96:99], s101 offen
	buffer_store_short_d16_hi v114, v130, s[96:99], s101 offen
	buffer_store_short_d16_hi v115, v131, s[96:99], s101 offen
	v_bfe_u32 v136, v116, 16, 1
	v_bfe_u32 v137, v117, 16, 1
	v_bfe_u32 v138, v118, 16, 1
	v_bfe_u32 v139, v119, 16, 1
	v_add3_u32 v116, v116, v136, s46
	v_add3_u32 v117, v117, v137, s46
	v_add3_u32 v118, v118, v138, s46
	v_add3_u32 v119, v119, v139, s46
	s_mov_b32 s101, 0x8000
	buffer_store_short_d16_hi v116, v128, s[96:99], s101 offen
	buffer_store_short_d16_hi v117, v129, s[96:99], s101 offen
	buffer_store_short_d16_hi v118, v130, s[96:99], s101 offen
	buffer_store_short_d16_hi v119, v131, s[96:99], s101 offen
	v_bfe_u32 v136, v120, 16, 1
	v_bfe_u32 v137, v121, 16, 1
	v_bfe_u32 v138, v122, 16, 1
	v_bfe_u32 v139, v123, 16, 1
	v_add3_u32 v120, v120, v136, s46
	v_add3_u32 v121, v121, v137, s46
	v_add3_u32 v122, v122, v138, s46
	v_add3_u32 v123, v123, v139, s46
	s_mov_b32 s101, 0x10000
	buffer_store_short_d16_hi v120, v128, s[96:99], s101 offen
	buffer_store_short_d16_hi v121, v129, s[96:99], s101 offen
	buffer_store_short_d16_hi v122, v130, s[96:99], s101 offen
	buffer_store_short_d16_hi v123, v131, s[96:99], s101 offen
	v_bfe_u32 v136, v124, 16, 1
	v_bfe_u32 v137, v125, 16, 1
	v_bfe_u32 v138, v126, 16, 1
	v_bfe_u32 v139, v127, 16, 1
	v_add3_u32 v124, v124, v136, s46
	v_add3_u32 v125, v125, v137, s46
	v_add3_u32 v126, v126, v138, s46
	v_add3_u32 v127, v127, v139, s46
	s_mov_b32 s101, 0x18000
	buffer_store_short_d16_hi v124, v128, s[96:99], s101 offen
	buffer_store_short_d16_hi v125, v129, s[96:99], s101 offen
	buffer_store_short_d16_hi v126, v130, s[96:99], s101 offen
	buffer_store_short_d16_hi v127, v131, s[96:99], s101 offen
	v_bfe_u32 v136, v96, 16, 1
	v_bfe_u32 v137, v97, 16, 1
	v_bfe_u32 v138, v98, 16, 1
	v_bfe_u32 v139, v99, 16, 1
	v_add3_u32 v96, v96, v136, s46
	v_add3_u32 v97, v97, v137, s46
	v_add3_u32 v98, v98, v138, s46
	v_add3_u32 v99, v99, v139, s46
	s_mov_b32 s101, 0x0
	buffer_store_short_d16_hi v96, v128, s[96:99], s101 offen offset:64
	buffer_store_short_d16_hi v97, v129, s[96:99], s101 offen offset:64
	buffer_store_short_d16_hi v98, v130, s[96:99], s101 offen offset:64
	buffer_store_short_d16_hi v99, v131, s[96:99], s101 offen offset:64
	v_bfe_u32 v136, v100, 16, 1
	v_bfe_u32 v137, v101, 16, 1
	v_bfe_u32 v138, v102, 16, 1
	v_bfe_u32 v139, v103, 16, 1
	v_add3_u32 v100, v100, v136, s46
	v_add3_u32 v101, v101, v137, s46
	v_add3_u32 v102, v102, v138, s46
	v_add3_u32 v103, v103, v139, s46
	s_mov_b32 s101, 0x8000
	buffer_store_short_d16_hi v100, v128, s[96:99], s101 offen offset:64
	buffer_store_short_d16_hi v101, v129, s[96:99], s101 offen offset:64
	buffer_store_short_d16_hi v102, v130, s[96:99], s101 offen offset:64
	buffer_store_short_d16_hi v103, v131, s[96:99], s101 offen offset:64
	v_bfe_u32 v136, v104, 16, 1
	v_bfe_u32 v137, v105, 16, 1
	v_bfe_u32 v138, v106, 16, 1
	v_bfe_u32 v139, v107, 16, 1
	v_add3_u32 v104, v104, v136, s46
	v_add3_u32 v105, v105, v137, s46
	v_add3_u32 v106, v106, v138, s46
	v_add3_u32 v107, v107, v139, s46
	s_mov_b32 s101, 0x10000
	buffer_store_short_d16_hi v104, v128, s[96:99], s101 offen offset:64
	buffer_store_short_d16_hi v105, v129, s[96:99], s101 offen offset:64
	buffer_store_short_d16_hi v106, v130, s[96:99], s101 offen offset:64
	buffer_store_short_d16_hi v107, v131, s[96:99], s101 offen offset:64
	v_bfe_u32 v136, v108, 16, 1
	v_bfe_u32 v137, v109, 16, 1
	v_bfe_u32 v138, v110, 16, 1
	v_bfe_u32 v139, v111, 16, 1
	v_add3_u32 v108, v108, v136, s46
	v_add3_u32 v109, v109, v137, s46
	v_add3_u32 v110, v110, v138, s46
	v_add3_u32 v111, v111, v139, s46
	s_mov_b32 s101, 0x18000
	buffer_store_short_d16_hi v108, v128, s[96:99], s101 offen offset:64
	buffer_store_short_d16_hi v109, v129, s[96:99], s101 offen offset:64
	buffer_store_short_d16_hi v110, v130, s[96:99], s101 offen offset:64
	buffer_store_short_d16_hi v111, v131, s[96:99], s101 offen offset:64
	v_bfe_u32 v136, v80, 16, 1
	v_bfe_u32 v137, v81, 16, 1
	v_bfe_u32 v138, v82, 16, 1
	v_bfe_u32 v139, v83, 16, 1
	v_add3_u32 v80, v80, v136, s46
	v_add3_u32 v81, v81, v137, s46
	v_add3_u32 v82, v82, v138, s46
	v_add3_u32 v83, v83, v139, s46
	s_mov_b32 s101, 0x20000
	buffer_store_short_d16_hi v80, v128, s[96:99], s101 offen
	buffer_store_short_d16_hi v81, v129, s[96:99], s101 offen
	buffer_store_short_d16_hi v82, v130, s[96:99], s101 offen
	buffer_store_short_d16_hi v83, v131, s[96:99], s101 offen
	v_bfe_u32 v136, v84, 16, 1
	v_bfe_u32 v137, v85, 16, 1
	v_bfe_u32 v138, v86, 16, 1
	v_bfe_u32 v139, v87, 16, 1
	v_add3_u32 v84, v84, v136, s46
	v_add3_u32 v85, v85, v137, s46
	v_add3_u32 v86, v86, v138, s46
	v_add3_u32 v87, v87, v139, s46
	s_mov_b32 s101, 0x28000
	buffer_store_short_d16_hi v84, v128, s[96:99], s101 offen
	buffer_store_short_d16_hi v85, v129, s[96:99], s101 offen
	buffer_store_short_d16_hi v86, v130, s[96:99], s101 offen
	buffer_store_short_d16_hi v87, v131, s[96:99], s101 offen
	v_bfe_u32 v136, v88, 16, 1
	v_bfe_u32 v137, v89, 16, 1
	v_bfe_u32 v138, v90, 16, 1
	v_bfe_u32 v139, v91, 16, 1
	v_add3_u32 v88, v88, v136, s46
	v_add3_u32 v89, v89, v137, s46
	v_add3_u32 v90, v90, v138, s46
	v_add3_u32 v91, v91, v139, s46
	s_mov_b32 s101, 0x30000
	buffer_store_short_d16_hi v88, v128, s[96:99], s101 offen
	buffer_store_short_d16_hi v89, v129, s[96:99], s101 offen
	buffer_store_short_d16_hi v90, v130, s[96:99], s101 offen
	buffer_store_short_d16_hi v91, v131, s[96:99], s101 offen
	v_bfe_u32 v136, v92, 16, 1
	v_bfe_u32 v137, v93, 16, 1
	v_bfe_u32 v138, v94, 16, 1
	v_bfe_u32 v139, v95, 16, 1
	v_add3_u32 v92, v92, v136, s46
	v_add3_u32 v93, v93, v137, s46
	v_add3_u32 v94, v94, v138, s46
	v_add3_u32 v95, v95, v139, s46
	s_mov_b32 s101, 0x38000
	buffer_store_short_d16_hi v92, v128, s[96:99], s101 offen
	buffer_store_short_d16_hi v93, v129, s[96:99], s101 offen
	buffer_store_short_d16_hi v94, v130, s[96:99], s101 offen
	buffer_store_short_d16_hi v95, v131, s[96:99], s101 offen
	v_bfe_u32 v136, v64, 16, 1
	v_bfe_u32 v137, v65, 16, 1
	v_bfe_u32 v138, v66, 16, 1
	v_bfe_u32 v139, v67, 16, 1
	v_add3_u32 v64, v64, v136, s46
	v_add3_u32 v65, v65, v137, s46
	v_add3_u32 v66, v66, v138, s46
	v_add3_u32 v67, v67, v139, s46
	s_mov_b32 s101, 0x20000
	buffer_store_short_d16_hi v64, v128, s[96:99], s101 offen offset:64
	buffer_store_short_d16_hi v65, v129, s[96:99], s101 offen offset:64
	buffer_store_short_d16_hi v66, v130, s[96:99], s101 offen offset:64
	buffer_store_short_d16_hi v67, v131, s[96:99], s101 offen offset:64
	v_bfe_u32 v136, v68, 16, 1
	v_bfe_u32 v137, v69, 16, 1
	v_bfe_u32 v138, v70, 16, 1
	v_bfe_u32 v139, v71, 16, 1
	v_add3_u32 v68, v68, v136, s46
	v_add3_u32 v69, v69, v137, s46
	v_add3_u32 v70, v70, v138, s46
	v_add3_u32 v71, v71, v139, s46
	s_mov_b32 s101, 0x28000
	buffer_store_short_d16_hi v68, v128, s[96:99], s101 offen offset:64
	buffer_store_short_d16_hi v69, v129, s[96:99], s101 offen offset:64
	buffer_store_short_d16_hi v70, v130, s[96:99], s101 offen offset:64
	buffer_store_short_d16_hi v71, v131, s[96:99], s101 offen offset:64
	v_bfe_u32 v136, v72, 16, 1
	v_bfe_u32 v137, v73, 16, 1
	v_bfe_u32 v138, v74, 16, 1
	v_bfe_u32 v139, v75, 16, 1
	v_add3_u32 v72, v72, v136, s46
	v_add3_u32 v73, v73, v137, s46
	v_add3_u32 v74, v74, v138, s46
	v_add3_u32 v75, v75, v139, s46
	s_mov_b32 s101, 0x30000
	buffer_store_short_d16_hi v72, v128, s[96:99], s101 offen offset:64
	buffer_store_short_d16_hi v73, v129, s[96:99], s101 offen offset:64
	buffer_store_short_d16_hi v74, v130, s[96:99], s101 offen offset:64
	buffer_store_short_d16_hi v75, v131, s[96:99], s101 offen offset:64
	v_bfe_u32 v136, v76, 16, 1
	v_bfe_u32 v137, v77, 16, 1
	v_bfe_u32 v138, v78, 16, 1
	v_bfe_u32 v139, v79, 16, 1
	v_add3_u32 v76, v76, v136, s46
	v_add3_u32 v77, v77, v137, s46
	v_add3_u32 v78, v78, v138, s46
	v_add3_u32 v79, v79, v139, s46
	s_mov_b32 s101, 0x38000
	buffer_store_short_d16_hi v76, v128, s[96:99], s101 offen offset:64
	buffer_store_short_d16_hi v77, v129, s[96:99], s101 offen offset:64
	buffer_store_short_d16_hi v78, v130, s[96:99], s101 offen offset:64
	buffer_store_short_d16_hi v79, v131, s[96:99], s101 offen offset:64
	v_bfe_u32 v136, v48, 16, 1
	v_bfe_u32 v137, v49, 16, 1
	v_bfe_u32 v138, v50, 16, 1
	v_bfe_u32 v139, v51, 16, 1
	v_add3_u32 v48, v48, v136, s46
	v_add3_u32 v49, v49, v137, s46
	v_add3_u32 v50, v50, v138, s46
	v_add3_u32 v51, v51, v139, s46
	s_mov_b32 s101, 0x40000
	buffer_store_short_d16_hi v48, v128, s[96:99], s101 offen
	buffer_store_short_d16_hi v49, v129, s[96:99], s101 offen
	buffer_store_short_d16_hi v50, v130, s[96:99], s101 offen
	buffer_store_short_d16_hi v51, v131, s[96:99], s101 offen
	v_bfe_u32 v136, v52, 16, 1
	v_bfe_u32 v137, v53, 16, 1
	v_bfe_u32 v138, v54, 16, 1
	v_bfe_u32 v139, v55, 16, 1
	v_add3_u32 v52, v52, v136, s46
	v_add3_u32 v53, v53, v137, s46
	v_add3_u32 v54, v54, v138, s46
	v_add3_u32 v55, v55, v139, s46
	s_mov_b32 s101, 0x48000
	buffer_store_short_d16_hi v52, v128, s[96:99], s101 offen
	buffer_store_short_d16_hi v53, v129, s[96:99], s101 offen
	buffer_store_short_d16_hi v54, v130, s[96:99], s101 offen
	buffer_store_short_d16_hi v55, v131, s[96:99], s101 offen
	v_bfe_u32 v136, v56, 16, 1
	v_bfe_u32 v137, v57, 16, 1
	v_bfe_u32 v138, v58, 16, 1
	v_bfe_u32 v139, v59, 16, 1
	v_add3_u32 v56, v56, v136, s46
	v_add3_u32 v57, v57, v137, s46
	v_add3_u32 v58, v58, v138, s46
	v_add3_u32 v59, v59, v139, s46
	s_mov_b32 s101, 0x50000
	buffer_store_short_d16_hi v56, v128, s[96:99], s101 offen
	buffer_store_short_d16_hi v57, v129, s[96:99], s101 offen
	buffer_store_short_d16_hi v58, v130, s[96:99], s101 offen
	buffer_store_short_d16_hi v59, v131, s[96:99], s101 offen
	v_bfe_u32 v136, v60, 16, 1
	v_bfe_u32 v137, v61, 16, 1
	v_bfe_u32 v138, v62, 16, 1
	v_bfe_u32 v139, v63, 16, 1
	v_add3_u32 v60, v60, v136, s46
	v_add3_u32 v61, v61, v137, s46
	v_add3_u32 v62, v62, v138, s46
	v_add3_u32 v63, v63, v139, s46
	s_mov_b32 s101, 0x58000
	buffer_store_short_d16_hi v60, v128, s[96:99], s101 offen
	buffer_store_short_d16_hi v61, v129, s[96:99], s101 offen
	buffer_store_short_d16_hi v62, v130, s[96:99], s101 offen
	buffer_store_short_d16_hi v63, v131, s[96:99], s101 offen
	v_bfe_u32 v136, v32, 16, 1
	v_bfe_u32 v137, v33, 16, 1
	v_bfe_u32 v138, v34, 16, 1
	v_bfe_u32 v139, v35, 16, 1
	v_add3_u32 v32, v32, v136, s46
	v_add3_u32 v33, v33, v137, s46
	v_add3_u32 v34, v34, v138, s46
	v_add3_u32 v35, v35, v139, s46
	s_mov_b32 s101, 0x40000
	buffer_store_short_d16_hi v32, v128, s[96:99], s101 offen offset:64
	buffer_store_short_d16_hi v33, v129, s[96:99], s101 offen offset:64
	buffer_store_short_d16_hi v34, v130, s[96:99], s101 offen offset:64
	buffer_store_short_d16_hi v35, v131, s[96:99], s101 offen offset:64
	v_bfe_u32 v136, v36, 16, 1
	v_bfe_u32 v137, v37, 16, 1
	v_bfe_u32 v138, v38, 16, 1
	v_bfe_u32 v139, v39, 16, 1
	v_add3_u32 v36, v36, v136, s46
	v_add3_u32 v37, v37, v137, s46
	v_add3_u32 v38, v38, v138, s46
	v_add3_u32 v39, v39, v139, s46
	s_mov_b32 s101, 0x48000
	buffer_store_short_d16_hi v36, v128, s[96:99], s101 offen offset:64
	buffer_store_short_d16_hi v37, v129, s[96:99], s101 offen offset:64
	buffer_store_short_d16_hi v38, v130, s[96:99], s101 offen offset:64
	buffer_store_short_d16_hi v39, v131, s[96:99], s101 offen offset:64
	v_bfe_u32 v136, v40, 16, 1
	v_bfe_u32 v137, v41, 16, 1
	v_bfe_u32 v138, v42, 16, 1
	v_bfe_u32 v139, v43, 16, 1
	v_add3_u32 v40, v40, v136, s46
	v_add3_u32 v41, v41, v137, s46
	v_add3_u32 v42, v42, v138, s46
	v_add3_u32 v43, v43, v139, s46
	s_mov_b32 s101, 0x50000
	buffer_store_short_d16_hi v40, v128, s[96:99], s101 offen offset:64
	buffer_store_short_d16_hi v41, v129, s[96:99], s101 offen offset:64
	buffer_store_short_d16_hi v42, v130, s[96:99], s101 offen offset:64
	buffer_store_short_d16_hi v43, v131, s[96:99], s101 offen offset:64
	v_bfe_u32 v136, v44, 16, 1
	v_bfe_u32 v137, v45, 16, 1
	v_bfe_u32 v138, v46, 16, 1
	v_bfe_u32 v139, v47, 16, 1
	v_add3_u32 v44, v44, v136, s46
	v_add3_u32 v45, v45, v137, s46
	v_add3_u32 v46, v46, v138, s46
	v_add3_u32 v47, v47, v139, s46
	s_mov_b32 s101, 0x58000
	buffer_store_short_d16_hi v44, v128, s[96:99], s101 offen offset:64
	buffer_store_short_d16_hi v45, v129, s[96:99], s101 offen offset:64
	buffer_store_short_d16_hi v46, v130, s[96:99], s101 offen offset:64
	buffer_store_short_d16_hi v47, v131, s[96:99], s101 offen offset:64
	v_bfe_u32 v136, v16, 16, 1
	v_bfe_u32 v137, v17, 16, 1
	v_bfe_u32 v138, v18, 16, 1
	v_bfe_u32 v139, v19, 16, 1
	v_add3_u32 v16, v16, v136, s46
	v_add3_u32 v17, v17, v137, s46
	v_add3_u32 v18, v18, v138, s46
	v_add3_u32 v19, v19, v139, s46
	s_mov_b32 s101, 0x60000
	buffer_store_short_d16_hi v16, v128, s[96:99], s101 offen
	buffer_store_short_d16_hi v17, v129, s[96:99], s101 offen
	buffer_store_short_d16_hi v18, v130, s[96:99], s101 offen
	buffer_store_short_d16_hi v19, v131, s[96:99], s101 offen
	v_bfe_u32 v136, v20, 16, 1
	v_bfe_u32 v137, v21, 16, 1
	v_bfe_u32 v138, v22, 16, 1
	v_bfe_u32 v139, v23, 16, 1
	v_add3_u32 v20, v20, v136, s46
	v_add3_u32 v21, v21, v137, s46
	v_add3_u32 v22, v22, v138, s46
	v_add3_u32 v23, v23, v139, s46
	s_mov_b32 s101, 0x68000
	buffer_store_short_d16_hi v20, v128, s[96:99], s101 offen
	buffer_store_short_d16_hi v21, v129, s[96:99], s101 offen
	buffer_store_short_d16_hi v22, v130, s[96:99], s101 offen
	buffer_store_short_d16_hi v23, v131, s[96:99], s101 offen
	v_bfe_u32 v136, v24, 16, 1
	v_bfe_u32 v137, v25, 16, 1
	v_bfe_u32 v138, v26, 16, 1
	v_bfe_u32 v139, v27, 16, 1
	v_add3_u32 v24, v24, v136, s46
	v_add3_u32 v25, v25, v137, s46
	v_add3_u32 v26, v26, v138, s46
	v_add3_u32 v27, v27, v139, s46
	s_mov_b32 s101, 0x70000
	buffer_store_short_d16_hi v24, v128, s[96:99], s101 offen
	buffer_store_short_d16_hi v25, v129, s[96:99], s101 offen
	buffer_store_short_d16_hi v26, v130, s[96:99], s101 offen
	buffer_store_short_d16_hi v27, v131, s[96:99], s101 offen
	v_bfe_u32 v136, v28, 16, 1
	v_bfe_u32 v137, v29, 16, 1
	v_bfe_u32 v138, v30, 16, 1
	v_bfe_u32 v139, v31, 16, 1
	v_add3_u32 v28, v28, v136, s46
	v_add3_u32 v29, v29, v137, s46
	v_add3_u32 v30, v30, v138, s46
	v_add3_u32 v31, v31, v139, s46
	s_mov_b32 s101, 0x78000
	buffer_store_short_d16_hi v28, v128, s[96:99], s101 offen
	buffer_store_short_d16_hi v29, v129, s[96:99], s101 offen
	buffer_store_short_d16_hi v30, v130, s[96:99], s101 offen
	buffer_store_short_d16_hi v31, v131, s[96:99], s101 offen
	v_bfe_u32 v136, v0, 16, 1
	v_bfe_u32 v137, v1, 16, 1
	v_bfe_u32 v138, v2, 16, 1
	v_bfe_u32 v139, v3, 16, 1
	v_add3_u32 v0, v0, v136, s46
	v_add3_u32 v1, v1, v137, s46
	v_add3_u32 v2, v2, v138, s46
	v_add3_u32 v3, v3, v139, s46
	s_mov_b32 s101, 0x60000
	buffer_store_short_d16_hi v0, v128, s[96:99], s101 offen offset:64
	buffer_store_short_d16_hi v1, v129, s[96:99], s101 offen offset:64
	buffer_store_short_d16_hi v2, v130, s[96:99], s101 offen offset:64
	buffer_store_short_d16_hi v3, v131, s[96:99], s101 offen offset:64
	v_bfe_u32 v136, v4, 16, 1
	v_bfe_u32 v137, v5, 16, 1
	v_bfe_u32 v138, v6, 16, 1
	v_bfe_u32 v139, v7, 16, 1
	v_add3_u32 v4, v4, v136, s46
	v_add3_u32 v5, v5, v137, s46
	v_add3_u32 v6, v6, v138, s46
	v_add3_u32 v7, v7, v139, s46
	s_mov_b32 s101, 0x68000
	buffer_store_short_d16_hi v4, v128, s[96:99], s101 offen offset:64
	buffer_store_short_d16_hi v5, v129, s[96:99], s101 offen offset:64
	buffer_store_short_d16_hi v6, v130, s[96:99], s101 offen offset:64
	buffer_store_short_d16_hi v7, v131, s[96:99], s101 offen offset:64
	v_bfe_u32 v136, v8, 16, 1
	v_bfe_u32 v137, v9, 16, 1
	v_bfe_u32 v138, v10, 16, 1
	v_bfe_u32 v139, v11, 16, 1
	v_add3_u32 v8, v8, v136, s46
	v_add3_u32 v9, v9, v137, s46
	v_add3_u32 v10, v10, v138, s46
	v_add3_u32 v11, v11, v139, s46
	s_mov_b32 s101, 0x70000
	buffer_store_short_d16_hi v8, v128, s[96:99], s101 offen offset:64
	buffer_store_short_d16_hi v9, v129, s[96:99], s101 offen offset:64
	buffer_store_short_d16_hi v10, v130, s[96:99], s101 offen offset:64
	buffer_store_short_d16_hi v11, v131, s[96:99], s101 offen offset:64
	v_bfe_u32 v136, v12, 16, 1
	v_bfe_u32 v137, v13, 16, 1
	v_bfe_u32 v138, v14, 16, 1
	v_bfe_u32 v139, v15, 16, 1
	v_add3_u32 v12, v12, v136, s46
	v_add3_u32 v13, v13, v137, s46
	v_add3_u32 v14, v14, v138, s46
	v_add3_u32 v15, v15, v139, s46
	s_mov_b32 s101, 0x78000
	buffer_store_short_d16_hi v12, v128, s[96:99], s101 offen offset:64
	buffer_store_short_d16_hi v13, v129, s[96:99], s101 offen offset:64
	buffer_store_short_d16_hi v14, v130, s[96:99], s101 offen offset:64
	buffer_store_short_d16_hi v15, v131, s[96:99], s101 offen offset:64
	s_cmpk_lt_i32 s39, 0x200
	s_cbranch_scc1 .Lgwq0_tile
	s_branch .LBB0_1433

.LBB0_1641:
	s_and_b32 s100, s39, 7
	s_bfe_u32 s101, s39, 0x50003
	s_lshr_b32 s82, s39, 8
	s_lshl_b32 s64, s82, 2
	s_and_b32 s82, s101, 3
	s_add_u32 s64, s64, s82
	s_lshl_b32 s82, s100, 3
	s_lshr_b32 s101, s101, 2
	s_add_u32 s82, s82, s101
	s_lshl_b32 s64, s64, 8
	s_lshl_b32 s82, s82, 8
	s_lshl_b32 s100, s64, 12
	s_add_u32 s100, s100, 0x1b80000
	s_add_u32 s48, s92, s100
	s_addc_u32 s49, s93, 0
	s_and_b32 s49, s49, 0xffff
	s_mov_b32 s50, 0x100000
	s_mov_b32 s51, 0x20000
	s_lshl_b32 s100, s82, 12
	s_add_u32 s100, s100, 0x6224000
	s_add_u32 s52, s92, s100
	s_addc_u32 s53, s93, 0
	s_and_b32 s53, s53, 0xffff
	s_sub_u32 s100, 0x4000, s82
	s_min_u32 s100, s100, 0x100
	s_lshl_b32 s54, s100, 12
	s_mov_b32 s55, 0x20000
	s_mov_b32 s46, 0x40000
	s_mov_b32 s47, 0x80000
	s_mov_b32 s58, 0xc0000
	v_lshrrev_b32_e32 v128, 3, v190
	v_and_b32_e32 v129, 7, v190
	v_lshlrev_b32_e32 v129, 4, v129
	v_lshl_add_u32 v160, v128, 12, v129
	v_mul_u32_u24_e32 v130, 0x90, v128
	v_add_u32_e32 v170, v130, v129
	v_add_u32_e32 v171, 0x12000, v170
	v_and_b32_e32 v131, 31, v190
	v_bfe_u32 v132, v190, 5, 1
	v_bfe_u32 v133, v190, 6, 2
	v_bfe_u32 v134, v190, 8, 1
	v_lshl_add_u32 v135, v134, 7, v131
	v_mul_u32_u24_e32 v135, 0x90, v135
	v_lshl_add_u32 v175, v132, 4, v135
	v_lshl_add_u32 v136, v133, 6, v131
	v_mul_u32_u24_e32 v136, 0x90, v136
	v_lshl_add_u32 v136, v132, 4, v136
	v_add_u32_e32 v254, 0x12000, v136
	buffer_load_dwordx4 v[216:219], v160, s[48:51], 0 offen
	buffer_load_dwordx4 v[220:223], v160, s[48:51], s46 offen
	buffer_load_dwordx4 v[224:227], v160, s[48:51], s47 offen
	buffer_load_dwordx4 v[228:231], v160, s[48:51], s58 offen
	buffer_load_dwordx4 v[232:235], v160, s[52:55], 0 offen
	buffer_load_dwordx4 v[236:239], v160, s[52:55], s46 offen
	buffer_load_dwordx4 v[152:155], v160, s[52:55], s47 offen
	buffer_load_dwordx4 v[156:159], v160, s[52:55], s58 offen
	v_add_u32_e32 v160, 0x80, v160
	buffer_load_dwordx4 v[162:165], v160, s[48:51], 0 offen
	buffer_load_dwordx4 v[166:169], v160, s[48:51], s46 offen
	buffer_load_dwordx4 v[176:179], v160, s[48:51], s47 offen
	buffer_load_dwordx4 v[180:183], v160, s[48:51], s58 offen
	buffer_load_dwordx4 v[184:187], v160, s[52:55], 0 offen
	buffer_load_dwordx4 v[242:245], v160, s[52:55], s46 offen
	buffer_load_dwordx4 v[246:249], v160, s[52:55], s47 offen
	buffer_load_dwordx4 v[250:253], v160, s[52:55], s58 offen
	v_add_u32_e32 v160, 0x80, v160

.Lgin1_loop:
	ds_read_b128 v[144:147], v254 offset:0
	ds_read_b128 v[148:151], v254 offset:4608
	ds_read_b128 v[128:131], v175 offset:0
	ds_read_b128 v[132:135], v175 offset:4608
	ds_read_b128 v[136:139], v175 offset:9216
	ds_read_b128 v[140:143], v175 offset:13824
	v_mfma_f32_32x32x16_bf16 v[112:127], v[192:195], v[208:211], v[112:127]
	s_waitcnt vmcnt(8)
	v_mfma_f32_32x32x16_bf16 v[96:111], v[192:195], v[212:215], v[96:111]
	ds_write_b128 v170, v[162:165] offset:36864
	v_mfma_f32_32x32x16_bf16 v[80:95], v[196:199], v[208:211], v[80:95]
	ds_write_b128 v170, v[166:169] offset:46080
	v_mfma_f32_32x32x16_bf16 v[64:79], v[196:199], v[212:215], v[64:79]
	ds_write_b128 v170, v[176:179] offset:55296
	v_mfma_f32_32x32x16_bf16 v[48:63], v[200:203], v[208:211], v[48:63]
	ds_write_b128 v170, v[180:183] offset:64512
	v_mfma_f32_32x32x16_bf16 v[32:47], v[200:203], v[212:215], v[32:47]
	ds_write_b128 v171, v[184:187] offset:36864
	v_mfma_f32_32x32x16_bf16 v[16:31], v[204:207], v[208:211], v[16:31]
	ds_write_b128 v171, v[242:245] offset:46080
	v_mfma_f32_32x32x16_bf16 v[0:15], v[204:207], v[212:215], v[0:15]
	ds_write_b128 v171, v[246:249] offset:55296
	ds_write_b128 v171, v[250:253] offset:64512
	s_waitcnt lgkmcnt(8)
	v_mfma_f32_32x32x16_bf16 v[112:127], v[128:131], v[144:147], v[112:127]
	ds_read_b128 v[208:211], v254 offset:32
	v_mfma_f32_32x32x16_bf16 v[96:111], v[128:131], v[148:151], v[96:111]
	ds_read_b128 v[212:215], v254 offset:4640
	ds_read_b128 v[192:195], v175 offset:32
	v_mfma_f32_32x32x16_bf16 v[80:95], v[132:135], v[144:147], v[80:95]
	ds_read_b128 v[196:199], v175 offset:4640
	ds_read_b128 v[200:203], v175 offset:9248
	v_mfma_f32_32x32x16_bf16 v[64:79], v[132:135], v[148:151], v[64:79]
	ds_read_b128 v[204:207], v175 offset:13856
	buffer_load_dwordx4 v[162:165], v160, s[48:51], 0 offen
	v_mfma_f32_32x32x16_bf16 v[48:63], v[136:139], v[144:147], v[48:63]
	buffer_load_dwordx4 v[166:169], v160, s[48:51], s46 offen
	buffer_load_dwordx4 v[176:179], v160, s[48:51], s47 offen
	v_mfma_f32_32x32x16_bf16 v[32:47], v[136:139], v[148:151], v[32:47]
	buffer_load_dwordx4 v[180:183], v160, s[48:51], s58 offen
	buffer_load_dwordx4 v[184:187], v160, s[52:55], 0 offen
	v_mfma_f32_32x32x16_bf16 v[16:31], v[140:143], v[144:147], v[16:31]
	buffer_load_dwordx4 v[242:245], v160, s[52:55], s46 offen
	buffer_load_dwordx4 v[246:249], v160, s[52:55], s47 offen
	v_mfma_f32_32x32x16_bf16 v[0:15], v[140:143], v[148:151], v[0:15]
	buffer_load_dwordx4 v[250:253], v160, s[52:55], s58 offen
	v_add_u32_e32 v160, 0x80, v160
	s_waitcnt lgkmcnt(0)
	v_mfma_f32_32x32x16_bf16 v[112:127], v[192:195], v[208:211], v[112:127]
	v_mfma_f32_32x32x16_bf16 v[96:111], v[192:195], v[212:215], v[96:111]
	ds_read_b128 v[144:147], v254 offset:64
	v_mfma_f32_32x32x16_bf16 v[80:95], v[196:199], v[208:211], v[80:95]
	ds_read_b128 v[148:151], v254 offset:4672
	v_mfma_f32_32x32x16_bf16 v[64:79], v[196:199], v[212:215], v[64:79]
	ds_read_b128 v[128:131], v175 offset:64
	v_mfma_f32_32x32x16_bf16 v[48:63], v[200:203], v[208:211], v[48:63]
	v_mfma_f32_32x32x16_bf16 v[32:47], v[200:203], v[212:215], v[32:47]
	ds_read_b128 v[132:135], v175 offset:4672
	v_mfma_f32_32x32x16_bf16 v[16:31], v[204:207], v[208:211], v[16:31]
	ds_read_b128 v[136:139], v175 offset:9280
	v_mfma_f32_32x32x16_bf16 v[0:15], v[204:207], v[212:215], v[0:15]
	ds_read_b128 v[140:143], v175 offset:13888
	s_waitcnt lgkmcnt(0)
	v_mfma_f32_32x32x16_bf16 v[112:127], v[128:131], v[144:147], v[112:127]
	v_mfma_f32_32x32x16_bf16 v[96:111], v[128:131], v[148:151], v[96:111]
	ds_read_b128 v[208:211], v254 offset:96
	v_mfma_f32_32x32x16_bf16 v[80:95], v[132:135], v[144:147], v[80:95]
	ds_read_b128 v[212:215], v254 offset:4704
	v_mfma_f32_32x32x16_bf16 v[64:79], v[132:135], v[148:151], v[64:79]
	ds_read_b128 v[192:195], v175 offset:96
	v_mfma_f32_32x32x16_bf16 v[48:63], v[136:139], v[144:147], v[48:63]
	v_mfma_f32_32x32x16_bf16 v[32:47], v[136:139], v[148:151], v[32:47]
	ds_read_b128 v[196:199], v175 offset:4704
	v_mfma_f32_32x32x16_bf16 v[16:31], v[140:143], v[144:147], v[16:31]
	ds_read_b128 v[200:203], v175 offset:9312
	v_mfma_f32_32x32x16_bf16 v[0:15], v[140:143], v[148:151], v[0:15]
	ds_read_b128 v[204:207], v175 offset:13920
	s_waitcnt lgkmcnt(0)
	s_barrier
	ds_read_b128 v[144:147], v254 offset:36864
	ds_read_b128 v[148:151], v254 offset:41472
	ds_read_b128 v[128:131], v175 offset:36864
	ds_read_b128 v[132:135], v175 offset:41472
	ds_read_b128 v[136:139], v175 offset:46080
	ds_read_b128 v[140:143], v175 offset:50688
	v_mfma_f32_32x32x16_bf16 v[112:127], v[192:195], v[208:211], v[112:127]
	s_waitcnt vmcnt(8)
	v_mfma_f32_32x32x16_bf16 v[96:111], v[192:195], v[212:215], v[96:111]
	ds_write_b128 v170, v[216:219] offset:0
	v_mfma_f32_32x32x16_bf16 v[80:95], v[196:199], v[208:211], v[80:95]
	ds_write_b128 v170, v[220:223] offset:9216
	v_mfma_f32_32x32x16_bf16 v[64:79], v[196:199], v[212:215], v[64:79]
	ds_write_b128 v170, v[224:227] offset:18432
	v_mfma_f32_32x32x16_bf16 v[48:63], v[200:203], v[208:211], v[48:63]
	ds_write_b128 v170, v[228:231] offset:27648
	v_mfma_f32_32x32x16_bf16 v[32:47], v[200:203], v[212:215], v[32:47]
	ds_write_b128 v171, v[232:235] offset:0
	v_mfma_f32_32x32x16_bf16 v[16:31], v[204:207], v[208:211], v[16:31]
	ds_write_b128 v171, v[236:239] offset:9216
	v_mfma_f32_32x32x16_bf16 v[0:15], v[204:207], v[212:215], v[0:15]
	ds_write_b128 v171, v[152:155] offset:18432
	ds_write_b128 v171, v[156:159] offset:27648
	s_waitcnt lgkmcnt(8)
	v_mfma_f32_32x32x16_bf16 v[112:127], v[128:131], v[144:147], v[112:127]
	ds_read_b128 v[208:211], v254 offset:36896
	v_mfma_f32_32x32x16_bf16 v[96:111], v[128:131], v[148:151], v[96:111]
	ds_read_b128 v[212:215], v254 offset:41504
	ds_read_b128 v[192:195], v175 offset:36896
	v_mfma_f32_32x32x16_bf16 v[80:95], v[132:135], v[144:147], v[80:95]
	ds_read_b128 v[196:199], v175 offset:41504
	ds_read_b128 v[200:203], v175 offset:46112
	v_mfma_f32_32x32x16_bf16 v[64:79], v[132:135], v[148:151], v[64:79]
	ds_read_b128 v[204:207], v175 offset:50720
	buffer_load_dwordx4 v[216:219], v160, s[48:51], 0 offen
	v_mfma_f32_32x32x16_bf16 v[48:63], v[136:139], v[144:147], v[48:63]
	buffer_load_dwordx4 v[220:223], v160, s[48:51], s46 offen
	buffer_load_dwordx4 v[224:227], v160, s[48:51], s47 offen
	v_mfma_f32_32x32x16_bf16 v[32:47], v[136:139], v[148:151], v[32:47]
	buffer_load_dwordx4 v[228:231], v160, s[48:51], s58 offen
	buffer_load_dwordx4 v[232:235], v160, s[52:55], 0 offen
	v_mfma_f32_32x32x16_bf16 v[16:31], v[140:143], v[144:147], v[16:31]
	buffer_load_dwordx4 v[236:239], v160, s[52:55], s46 offen
	buffer_load_dwordx4 v[152:155], v160, s[52:55], s47 offen
	v_mfma_f32_32x32x16_bf16 v[0:15], v[140:143], v[148:151], v[0:15]
	buffer_load_dwordx4 v[156:159], v160, s[52:55], s58 offen
	v_add_u32_e32 v160, 0x80, v160
	s_waitcnt lgkmcnt(0)
	v_mfma_f32_32x32x16_bf16 v[112:127], v[192:195], v[208:211], v[112:127]
	v_mfma_f32_32x32x16_bf16 v[96:111], v[192:195], v[212:215], v[96:111]
	ds_read_b128 v[144:147], v254 offset:36928
	v_mfma_f32_32x32x16_bf16 v[80:95], v[196:199], v[208:211], v[80:95]
	ds_read_b128 v[148:151], v254 offset:41536
	v_mfma_f32_32x32x16_bf16 v[64:79], v[196:199], v[212:215], v[64:79]
	ds_read_b128 v[128:131], v175 offset:36928
	v_mfma_f32_32x32x16_bf16 v[48:63], v[200:203], v[208:211], v[48:63]
	v_mfma_f32_32x32x16_bf16 v[32:47], v[200:203], v[212:215], v[32:47]
	ds_read_b128 v[132:135], v175 offset:41536
	v_mfma_f32_32x32x16_bf16 v[16:31], v[204:207], v[208:211], v[16:31]
	ds_read_b128 v[136:139], v175 offset:46144
	v_mfma_f32_32x32x16_bf16 v[0:15], v[204:207], v[212:215], v[0:15]
	ds_read_b128 v[140:143], v175 offset:50752
	s_waitcnt lgkmcnt(0)
	v_mfma_f32_32x32x16_bf16 v[112:127], v[128:131], v[144:147], v[112:127]
	v_mfma_f32_32x32x16_bf16 v[96:111], v[128:131], v[148:151], v[96:111]
	ds_read_b128 v[208:211], v254 offset:36960
	v_mfma_f32_32x32x16_bf16 v[80:95], v[132:135], v[144:147], v[80:95]
	ds_read_b128 v[212:215], v254 offset:41568
	v_mfma_f32_32x32x16_bf16 v[64:79], v[132:135], v[148:151], v[64:79]
	ds_read_b128 v[192:195], v175 offset:36960
	v_mfma_f32_32x32x16_bf16 v[48:63], v[136:139], v[144:147], v[48:63]
	v_mfma_f32_32x32x16_bf16 v[32:47], v[136:139], v[148:151], v[32:47]
	ds_read_b128 v[196:199], v175 offset:41568
	v_mfma_f32_32x32x16_bf16 v[16:31], v[140:143], v[144:147], v[16:31]
	ds_read_b128 v[200:203], v175 offset:46176
	v_mfma_f32_32x32x16_bf16 v[0:15], v[140:143], v[148:151], v[0:15]
	ds_read_b128 v[204:207], v175 offset:50784
	s_waitcnt lgkmcnt(0)
	s_barrier
	s_add_i32 s59, s59, -1
	s_cmp_lg_u32 s59, 0
	s_cbranch_scc1 .Lgin1_loop
	ds_read_b128 v[144:147], v254 offset:0
	ds_read_b128 v[148:151], v254 offset:4608
	ds_read_b128 v[128:131], v175 offset:0
	ds_read_b128 v[132:135], v175 offset:4608
	ds_read_b128 v[136:139], v175 offset:9216
	ds_read_b128 v[140:143], v175 offset:13824
	v_mfma_f32_32x32x16_bf16 v[112:127], v[192:195], v[208:211], v[112:127]
	s_waitcnt vmcnt(8)
	v_mfma_f32_32x32x16_bf16 v[96:111], v[192:195], v[212:215], v[96:111]
	ds_write_b128 v170, v[162:165] offset:36864
	v_mfma_f32_32x32x16_bf16 v[80:95], v[196:199], v[208:211], v[80:95]
	ds_write_b128 v170, v[166:169] offset:46080
	v_mfma_f32_32x32x16_bf16 v[64:79], v[196:199], v[212:215], v[64:79]
	ds_write_b128 v170, v[176:179] offset:55296
	v_mfma_f32_32x32x16_bf16 v[48:63], v[200:203], v[208:211], v[48:63]
	ds_write_b128 v170, v[180:183] offset:64512
	v_mfma_f32_32x32x16_bf16 v[32:47], v[200:203], v[212:215], v[32:47]
	ds_write_b128 v171, v[184:187] offset:36864
	v_mfma_f32_32x32x16_bf16 v[16:31], v[204:207], v[208:211], v[16:31]
	ds_write_b128 v171, v[242:245] offset:46080
	v_mfma_f32_32x32x16_bf16 v[0:15], v[204:207], v[212:215], v[0:15]
	ds_write_b128 v171, v[246:249] offset:55296
	ds_write_b128 v171, v[250:253] offset:64512
	s_waitcnt lgkmcnt(8)
	v_mfma_f32_32x32x16_bf16 v[112:127], v[128:131], v[144:147], v[112:127]
	ds_read_b128 v[208:211], v254 offset:32
	v_mfma_f32_32x32x16_bf16 v[96:111], v[128:131], v[148:151], v[96:111]
	ds_read_b128 v[212:215], v254 offset:4640
	ds_read_b128 v[192:195], v175 offset:32
	v_mfma_f32_32x32x16_bf16 v[80:95], v[132:135], v[144:147], v[80:95]
	ds_read_b128 v[196:199], v175 offset:4640
	ds_read_b128 v[200:203], v175 offset:9248
	v_mfma_f32_32x32x16_bf16 v[64:79], v[132:135], v[148:151], v[64:79]
	ds_read_b128 v[204:207], v175 offset:13856
	buffer_load_dwordx4 v[162:165], v160, s[48:51], 0 offen
	v_mfma_f32_32x32x16_bf16 v[48:63], v[136:139], v[144:147], v[48:63]
	buffer_load_dwordx4 v[166:169], v160, s[48:51], s46 offen
	buffer_load_dwordx4 v[176:179], v160, s[48:51], s47 offen
	v_mfma_f32_32x32x16_bf16 v[32:47], v[136:139], v[148:151], v[32:47]
	buffer_load_dwordx4 v[180:183], v160, s[48:51], s58 offen
	buffer_load_dwordx4 v[184:187], v160, s[52:55], 0 offen
	v_mfma_f32_32x32x16_bf16 v[16:31], v[140:143], v[144:147], v[16:31]
	buffer_load_dwordx4 v[242:245], v160, s[52:55], s46 offen
	buffer_load_dwordx4 v[246:249], v160, s[52:55], s47 offen
	v_mfma_f32_32x32x16_bf16 v[0:15], v[140:143], v[148:151], v[0:15]
	buffer_load_dwordx4 v[250:253], v160, s[52:55], s58 offen
	v_add_u32_e32 v160, 0x80, v160
	s_waitcnt lgkmcnt(0)
	v_mfma_f32_32x32x16_bf16 v[112:127], v[192:195], v[208:211], v[112:127]
	v_mfma_f32_32x32x16_bf16 v[96:111], v[192:195], v[212:215], v[96:111]
	ds_read_b128 v[144:147], v254 offset:64
	v_mfma_f32_32x32x16_bf16 v[80:95], v[196:199], v[208:211], v[80:95]
	ds_read_b128 v[148:151], v254 offset:4672
	v_mfma_f32_32x32x16_bf16 v[64:79], v[196:199], v[212:215], v[64:79]
	ds_read_b128 v[128:131], v175 offset:64
	v_mfma_f32_32x32x16_bf16 v[48:63], v[200:203], v[208:211], v[48:63]
	v_mfma_f32_32x32x16_bf16 v[32:47], v[200:203], v[212:215], v[32:47]
	ds_read_b128 v[132:135], v175 offset:4672
	v_mfma_f32_32x32x16_bf16 v[16:31], v[204:207], v[208:211], v[16:31]
	ds_read_b128 v[136:139], v175 offset:9280
	v_mfma_f32_32x32x16_bf16 v[0:15], v[204:207], v[212:215], v[0:15]
	ds_read_b128 v[140:143], v175 offset:13888
	s_waitcnt lgkmcnt(0)
	v_mfma_f32_32x32x16_bf16 v[112:127], v[128:131], v[144:147], v[112:127]
	v_mfma_f32_32x32x16_bf16 v[96:111], v[128:131], v[148:151], v[96:111]
	ds_read_b128 v[208:211], v254 offset:96
	v_mfma_f32_32x32x16_bf16 v[80:95], v[132:135], v[144:147], v[80:95]
	ds_read_b128 v[212:215], v254 offset:4704
	v_mfma_f32_32x32x16_bf16 v[64:79], v[132:135], v[148:151], v[64:79]
	ds_read_b128 v[192:195], v175 offset:96
	v_mfma_f32_32x32x16_bf16 v[48:63], v[136:139], v[144:147], v[48:63]
	v_mfma_f32_32x32x16_bf16 v[32:47], v[136:139], v[148:151], v[32:47]
	ds_read_b128 v[196:199], v175 offset:4704
	v_mfma_f32_32x32x16_bf16 v[16:31], v[140:143], v[144:147], v[16:31]
	ds_read_b128 v[200:203], v175 offset:9312
	v_mfma_f32_32x32x16_bf16 v[0:15], v[140:143], v[148:151], v[0:15]
	ds_read_b128 v[204:207], v175 offset:13920
	s_waitcnt lgkmcnt(0)
	s_barrier
	ds_read_b128 v[144:147], v254 offset:36864
	ds_read_b128 v[148:151], v254 offset:41472
	ds_read_b128 v[128:131], v175 offset:36864
	ds_read_b128 v[132:135], v175 offset:41472
	ds_read_b128 v[136:139], v175 offset:46080
	ds_read_b128 v[140:143], v175 offset:50688
	v_mfma_f32_32x32x16_bf16 v[112:127], v[192:195], v[208:211], v[112:127]
	s_waitcnt vmcnt(8)
	v_mfma_f32_32x32x16_bf16 v[96:111], v[192:195], v[212:215], v[96:111]
	ds_write_b128 v170, v[216:219] offset:0
	v_mfma_f32_32x32x16_bf16 v[80:95], v[196:199], v[208:211], v[80:95]
	ds_write_b128 v170, v[220:223] offset:9216
	v_mfma_f32_32x32x16_bf16 v[64:79], v[196:199], v[212:215], v[64:79]
	ds_write_b128 v170, v[224:227] offset:18432
	v_mfma_f32_32x32x16_bf16 v[48:63], v[200:203], v[208:211], v[48:63]
	ds_write_b128 v170, v[228:231] offset:27648
	v_mfma_f32_32x32x16_bf16 v[32:47], v[200:203], v[212:215], v[32:47]
	ds_write_b128 v171, v[232:235] offset:0
	v_mfma_f32_32x32x16_bf16 v[16:31], v[204:207], v[208:211], v[16:31]
	ds_write_b128 v171, v[236:239] offset:9216
	v_mfma_f32_32x32x16_bf16 v[0:15], v[204:207], v[212:215], v[0:15]
	ds_write_b128 v171, v[152:155] offset:18432
	ds_write_b128 v171, v[156:159] offset:27648
	s_waitcnt lgkmcnt(8)
	v_mfma_f32_32x32x16_bf16 v[112:127], v[128:131], v[144:147], v[112:127]
	v_mfma_f32_32x32x16_bf16 v[96:111], v[128:131], v[148:151], v[96:111]
	ds_read_b128 v[208:211], v254 offset:36896
	v_mfma_f32_32x32x16_bf16 v[80:95], v[132:135], v[144:147], v[80:95]
	ds_read_b128 v[212:215], v254 offset:41504
	v_mfma_f32_32x32x16_bf16 v[64:79], v[132:135], v[148:151], v[64:79]
	ds_read_b128 v[192:195], v175 offset:36896
	v_mfma_f32_32x32x16_bf16 v[48:63], v[136:139], v[144:147], v[48:63]
	v_mfma_f32_32x32x16_bf16 v[32:47], v[136:139], v[148:151], v[32:47]
	ds_read_b128 v[196:199], v175 offset:41504
	v_mfma_f32_32x32x16_bf16 v[16:31], v[140:143], v[144:147], v[16:31]
	ds_read_b128 v[200:203], v175 offset:46112
	v_mfma_f32_32x32x16_bf16 v[0:15], v[140:143], v[148:151], v[0:15]
	ds_read_b128 v[204:207], v175 offset:50720
	s_waitcnt lgkmcnt(0)
	v_mfma_f32_32x32x16_bf16 v[112:127], v[192:195], v[208:211], v[112:127]
	v_mfma_f32_32x32x16_bf16 v[96:111], v[192:195], v[212:215], v[96:111]
	ds_read_b128 v[144:147], v254 offset:36928
	v_mfma_f32_32x32x16_bf16 v[80:95], v[196:199], v[208:211], v[80:95]
	ds_read_b128 v[148:151], v254 offset:41536
	v_mfma_f32_32x32x16_bf16 v[64:79], v[196:199], v[212:215], v[64:79]
	ds_read_b128 v[128:131], v175 offset:36928
	v_mfma_f32_32x32x16_bf16 v[48:63], v[200:203], v[208:211], v[48:63]
	v_mfma_f32_32x32x16_bf16 v[32:47], v[200:203], v[212:215], v[32:47]
	ds_read_b128 v[132:135], v175 offset:41536
	v_mfma_f32_32x32x16_bf16 v[16:31], v[204:207], v[208:211], v[16:31]
	ds_read_b128 v[136:139], v175 offset:46144
	v_mfma_f32_32x32x16_bf16 v[0:15], v[204:207], v[212:215], v[0:15]
	ds_read_b128 v[140:143], v175 offset:50752
	s_waitcnt lgkmcnt(0)
	v_mfma_f32_32x32x16_bf16 v[112:127], v[128:131], v[144:147], v[112:127]
	v_mfma_f32_32x32x16_bf16 v[96:111], v[128:131], v[148:151], v[96:111]
	ds_read_b128 v[208:211], v254 offset:36960
	v_mfma_f32_32x32x16_bf16 v[80:95], v[132:135], v[144:147], v[80:95]
	ds_read_b128 v[212:215], v254 offset:41568
	v_mfma_f32_32x32x16_bf16 v[64:79], v[132:135], v[148:151], v[64:79]
	ds_read_b128 v[192:195], v175 offset:36960
	v_mfma_f32_32x32x16_bf16 v[48:63], v[136:139], v[144:147], v[48:63]
	v_mfma_f32_32x32x16_bf16 v[32:47], v[136:139], v[148:151], v[32:47]
	ds_read_b128 v[196:199], v175 offset:41568
	v_mfma_f32_32x32x16_bf16 v[16:31], v[140:143], v[144:147], v[16:31]
	ds_read_b128 v[200:203], v175 offset:46176
	v_mfma_f32_32x32x16_bf16 v[0:15], v[140:143], v[148:151], v[0:15]
	ds_read_b128 v[204:207], v175 offset:50784
	s_waitcnt lgkmcnt(0)
	s_barrier
	ds_read_b128 v[144:147], v254 offset:0
	ds_read_b128 v[148:151], v254 offset:4608
	ds_read_b128 v[128:131], v175 offset:0
	ds_read_b128 v[132:135], v175 offset:4608
	ds_read_b128 v[136:139], v175 offset:9216
	ds_read_b128 v[140:143], v175 offset:13824
	v_mfma_f32_32x32x16_bf16 v[112:127], v[192:195], v[208:211], v[112:127]
	s_waitcnt vmcnt(0)
	v_mfma_f32_32x32x16_bf16 v[96:111], v[192:195], v[212:215], v[96:111]
	ds_write_b128 v170, v[162:165] offset:36864
	v_mfma_f32_32x32x16_bf16 v[80:95], v[196:199], v[208:211], v[80:95]
	ds_write_b128 v170, v[166:169] offset:46080
	v_mfma_f32_32x32x16_bf16 v[64:79], v[196:199], v[212:215], v[64:79]
	ds_write_b128 v170, v[176:179] offset:55296
	v_mfma_f32_32x32x16_bf16 v[48:63], v[200:203], v[208:211], v[48:63]
	ds_write_b128 v170, v[180:183] offset:64512
	v_mfma_f32_32x32x16_bf16 v[32:47], v[200:203], v[212:215], v[32:47]
	ds_write_b128 v171, v[184:187] offset:36864
	v_mfma_f32_32x32x16_bf16 v[16:31], v[204:207], v[208:211], v[16:31]
	ds_write_b128 v171, v[242:245] offset:46080
	v_mfma_f32_32x32x16_bf16 v[0:15], v[204:207], v[212:215], v[0:15]
	ds_write_b128 v171, v[246:249] offset:55296
	ds_write_b128 v171, v[250:253] offset:64512
	s_waitcnt lgkmcnt(8)
	v_mfma_f32_32x32x16_bf16 v[112:127], v[128:131], v[144:147], v[112:127]
	v_mfma_f32_32x32x16_bf16 v[96:111], v[128:131], v[148:151], v[96:111]
	ds_read_b128 v[208:211], v254 offset:32
	v_mfma_f32_32x32x16_bf16 v[80:95], v[132:135], v[144:147], v[80:95]
	ds_read_b128 v[212:215], v254 offset:4640
	v_mfma_f32_32x32x16_bf16 v[64:79], v[132:135], v[148:151], v[64:79]
	ds_read_b128 v[192:195], v175 offset:32
	v_mfma_f32_32x32x16_bf16 v[48:63], v[136:139], v[144:147], v[48:63]
	v_mfma_f32_32x32x16_bf16 v[32:47], v[136:139], v[148:151], v[32:47]
	ds_read_b128 v[196:199], v175 offset:4640
	v_mfma_f32_32x32x16_bf16 v[16:31], v[140:143], v[144:147], v[16:31]
	ds_read_b128 v[200:203], v175 offset:9248
	v_mfma_f32_32x32x16_bf16 v[0:15], v[140:143], v[148:151], v[0:15]
	ds_read_b128 v[204:207], v175 offset:13856
	s_waitcnt lgkmcnt(0)
	v_mfma_f32_32x32x16_bf16 v[112:127], v[192:195], v[208:211], v[112:127]
	v_mfma_f32_32x32x16_bf16 v[96:111], v[192:195], v[212:215], v[96:111]
	ds_read_b128 v[144:147], v254 offset:64
	v_mfma_f32_32x32x16_bf16 v[80:95], v[196:199], v[208:211], v[80:95]
	ds_read_b128 v[148:151], v254 offset:4672
	v_mfma_f32_32x32x16_bf16 v[64:79], v[196:199], v[212:215], v[64:79]
	ds_read_b128 v[128:131], v175 offset:64
	v_mfma_f32_32x32x16_bf16 v[48:63], v[200:203], v[208:211], v[48:63]
	v_mfma_f32_32x32x16_bf16 v[32:47], v[200:203], v[212:215], v[32:47]
	ds_read_b128 v[132:135], v175 offset:4672
	v_mfma_f32_32x32x16_bf16 v[16:31], v[204:207], v[208:211], v[16:31]
	ds_read_b128 v[136:139], v175 offset:9280
	v_mfma_f32_32x32x16_bf16 v[0:15], v[204:207], v[212:215], v[0:15]
	ds_read_b128 v[140:143], v175 offset:13888
	s_waitcnt lgkmcnt(0)
	v_mfma_f32_32x32x16_bf16 v[112:127], v[128:131], v[144:147], v[112:127]
	v_mfma_f32_32x32x16_bf16 v[96:111], v[128:131], v[148:151], v[96:111]
	ds_read_b128 v[208:211], v254 offset:96
	v_mfma_f32_32x32x16_bf16 v[80:95], v[132:135], v[144:147], v[80:95]
	ds_read_b128 v[212:215], v254 offset:4704
	v_mfma_f32_32x32x16_bf16 v[64:79], v[132:135], v[148:151], v[64:79]
	ds_read_b128 v[192:195], v175 offset:96
	v_mfma_f32_32x32x16_bf16 v[48:63], v[136:139], v[144:147], v[48:63]
	v_mfma_f32_32x32x16_bf16 v[32:47], v[136:139], v[148:151], v[32:47]
	ds_read_b128 v[196:199], v175 offset:4704
	v_mfma_f32_32x32x16_bf16 v[16:31], v[140:143], v[144:147], v[16:31]
	ds_read_b128 v[200:203], v175 offset:9312
	v_mfma_f32_32x32x16_bf16 v[0:15], v[140:143], v[148:151], v[0:15]
	ds_read_b128 v[204:207], v175 offset:13920
	s_waitcnt lgkmcnt(0)
	s_barrier
	ds_read_b128 v[144:147], v254 offset:36864
	ds_read_b128 v[148:151], v254 offset:41472
	ds_read_b128 v[128:131], v175 offset:36864
	ds_read_b128 v[132:135], v175 offset:41472
	ds_read_b128 v[136:139], v175 offset:46080
	ds_read_b128 v[140:143], v175 offset:50688
	v_mfma_f32_32x32x16_bf16 v[112:127], v[192:195], v[208:211], v[112:127]
	v_mfma_f32_32x32x16_bf16 v[96:111], v[192:195], v[212:215], v[96:111]
	v_mfma_f32_32x32x16_bf16 v[80:95], v[196:199], v[208:211], v[80:95]
	v_mfma_f32_32x32x16_bf16 v[64:79], v[196:199], v[212:215], v[64:79]
	v_mfma_f32_32x32x16_bf16 v[48:63], v[200:203], v[208:211], v[48:63]
	v_mfma_f32_32x32x16_bf16 v[32:47], v[200:203], v[212:215], v[32:47]
	v_mfma_f32_32x32x16_bf16 v[16:31], v[204:207], v[208:211], v[16:31]
	v_mfma_f32_32x32x16_bf16 v[0:15], v[204:207], v[212:215], v[0:15]
	s_waitcnt lgkmcnt(0)
	v_mfma_f32_32x32x16_bf16 v[112:127], v[128:131], v[144:147], v[112:127]
	v_mfma_f32_32x32x16_bf16 v[96:111], v[128:131], v[148:151], v[96:111]
	ds_read_b128 v[208:211], v254 offset:36896
	v_mfma_f32_32x32x16_bf16 v[80:95], v[132:135], v[144:147], v[80:95]
	ds_read_b128 v[212:215], v254 offset:41504
	v_mfma_f32_32x32x16_bf16 v[64:79], v[132:135], v[148:151], v[64:79]
	ds_read_b128 v[192:195], v175 offset:36896
	v_mfma_f32_32x32x16_bf16 v[48:63], v[136:139], v[144:147], v[48:63]
	v_mfma_f32_32x32x16_bf16 v[32:47], v[136:139], v[148:151], v[32:47]
	ds_read_b128 v[196:199], v175 offset:41504
	v_mfma_f32_32x32x16_bf16 v[16:31], v[140:143], v[144:147], v[16:31]
	ds_read_b128 v[200:203], v175 offset:46112
	v_mfma_f32_32x32x16_bf16 v[0:15], v[140:143], v[148:151], v[0:15]
	ds_read_b128 v[204:207], v175 offset:50720
	s_waitcnt lgkmcnt(0)
	v_mfma_f32_32x32x16_bf16 v[112:127], v[192:195], v[208:211], v[112:127]
	v_mfma_f32_32x32x16_bf16 v[96:111], v[192:195], v[212:215], v[96:111]
	ds_read_b128 v[144:147], v254 offset:36928
	v_mfma_f32_32x32x16_bf16 v[80:95], v[196:199], v[208:211], v[80:95]
	ds_read_b128 v[148:151], v254 offset:41536
	v_mfma_f32_32x32x16_bf16 v[64:79], v[196:199], v[212:215], v[64:79]
	ds_read_b128 v[128:131], v175 offset:36928
	v_mfma_f32_32x32x16_bf16 v[48:63], v[200:203], v[208:211], v[48:63]
	v_mfma_f32_32x32x16_bf16 v[32:47], v[200:203], v[212:215], v[32:47]
	ds_read_b128 v[132:135], v175 offset:41536
	v_mfma_f32_32x32x16_bf16 v[16:31], v[204:207], v[208:211], v[16:31]
	ds_read_b128 v[136:139], v175 offset:46144
	v_mfma_f32_32x32x16_bf16 v[0:15], v[204:207], v[212:215], v[0:15]
	ds_read_b128 v[140:143], v175 offset:50752
	s_waitcnt lgkmcnt(0)
	v_mfma_f32_32x32x16_bf16 v[112:127], v[128:131], v[144:147], v[112:127]
	v_mfma_f32_32x32x16_bf16 v[96:111], v[128:131], v[148:151], v[96:111]
	ds_read_b128 v[208:211], v254 offset:36960
	v_mfma_f32_32x32x16_bf16 v[80:95], v[132:135], v[144:147], v[80:95]
	ds_read_b128 v[212:215], v254 offset:41568
	v_mfma_f32_32x32x16_bf16 v[64:79], v[132:135], v[148:151], v[64:79]
	ds_read_b128 v[192:195], v175 offset:36960
	v_mfma_f32_32x32x16_bf16 v[48:63], v[136:139], v[144:147], v[48:63]
	v_mfma_f32_32x32x16_bf16 v[32:47], v[136:139], v[148:151], v[32:47]
	ds_read_b128 v[196:199], v175 offset:41568
	v_mfma_f32_32x32x16_bf16 v[16:31], v[140:143], v[144:147], v[16:31]
	ds_read_b128 v[200:203], v175 offset:46176
	v_mfma_f32_32x32x16_bf16 v[0:15], v[140:143], v[148:151], v[0:15]
	ds_read_b128 v[204:207], v175 offset:50784
	s_waitcnt lgkmcnt(0)
	s_barrier
	v_mfma_f32_32x32x16_bf16 v[112:127], v[192:195], v[208:211], v[112:127]
	v_mfma_f32_32x32x16_bf16 v[96:111], v[192:195], v[212:215], v[96:111]
	v_mfma_f32_32x32x16_bf16 v[80:95], v[196:199], v[208:211], v[80:95]
	v_mfma_f32_32x32x16_bf16 v[64:79], v[196:199], v[212:215], v[64:79]
	v_mfma_f32_32x32x16_bf16 v[48:63], v[200:203], v[208:211], v[48:63]
	v_mfma_f32_32x32x16_bf16 v[32:47], v[200:203], v[212:215], v[32:47]
	v_mfma_f32_32x32x16_bf16 v[16:31], v[204:207], v[208:211], v[16:31]
	v_mfma_f32_32x32x16_bf16 v[0:15], v[204:207], v[212:215], v[0:15]
	s_nop 7
	s_nop 7
	s_mul_i32 s100, s64, 0x8000
	s_mul_hi_u32 s101, s64, 0x8000
	s_add_u32 s100, s100, 0x17c24000
	s_addc_u32 s101, s101, 0
	s_add_u32 s96, s92, s100
	s_addc_u32 s97, s93, s101
	s_and_b32 s97, s97, 0xffff
	s_mov_b32 s98, 0x800000
	s_mov_b32 s99, 0x20000
	v_and_b32_e32 v132, 31, v190
	v_bfe_u32 v133, v190, 5, 1
	v_bfe_u32 v134, v190, 6, 2
	v_bfe_u32 v135, v190, 8, 1
	v_lshl_add_u32 v132, v134, 6, v132
	v_add_u32_e32 v132, s82, v132
	v_lshlrev_b32_e32 v132, 1, v132
	v_lshlrev_b32_e32 v135, 7, v135
	v_lshl_add_u32 v135, v133, 2, v135
	s_mov_b32 s47, 0x8000
	v_mul_lo_u32 v135, s47, v135
	v_add_u32_e32 v128, v135, v132
	v_add_u32_e32 v129, 0x8000, v128
	v_add_u32_e32 v130, 0x10000, v128
	v_add_u32_e32 v131, 0x18000, v128
	s_add_i32 s39, s39, s94
	s_cmpk_lt_i32 s39, 0x600
	s_cbranch_scc0 .Lgin1_last
	s_and_b32 s100, s39, 7
	s_bfe_u32 s101, s39, 0x50003
	s_lshr_b32 s82, s39, 8
	s_lshl_b32 s64, s82, 2
	s_and_b32 s82, s101, 3
	s_add_u32 s64, s64, s82
	s_lshl_b32 s82, s100, 3
	s_lshr_b32 s101, s101, 2
	s_add_u32 s82, s82, s101
	s_lshl_b32 s64, s64, 8
	s_lshl_b32 s82, s82, 8
	s_lshl_b32 s100, s64, 12
	s_add_u32 s100, s100, 0x1b80000
	s_add_u32 s48, s92, s100
	s_addc_u32 s49, s93, 0
	s_and_b32 s49, s49, 0xffff
	s_mov_b32 s50, 0x100000
	s_mov_b32 s51, 0x20000
	s_lshl_b32 s100, s82, 12
	s_add_u32 s100, s100, 0x6224000
	s_add_u32 s52, s92, s100
	s_addc_u32 s53, s93, 0
	s_and_b32 s53, s53, 0xffff
	s_sub_u32 s100, 0x4000, s82
	s_min_u32 s100, s100, 0x100
	s_lshl_b32 s54, s100, 12
	s_mov_b32 s55, 0x20000
	s_mov_b32 s46, 0x40000
	s_mov_b32 s47, 0x80000
	s_mov_b32 s58, 0xc0000
	v_lshrrev_b32_e32 v137, 3, v190
	v_and_b32_e32 v138, 7, v190
	v_lshlrev_b32_e32 v138, 4, v138
	v_lshl_add_u32 v160, v137, 12, v138
	buffer_load_dwordx4 v[216:219], v160, s[48:51], 0 offen
	buffer_load_dwordx4 v[220:223], v160, s[48:51], s46 offen
	buffer_load_dwordx4 v[224:227], v160, s[48:51], s47 offen
	buffer_load_dwordx4 v[228:231], v160, s[48:51], s58 offen
	buffer_load_dwordx4 v[232:235], v160, s[52:55], 0 offen
	buffer_load_dwordx4 v[236:239], v160, s[52:55], s46 offen
	buffer_load_dwordx4 v[152:155], v160, s[52:55], s47 offen
	buffer_load_dwordx4 v[156:159], v160, s[52:55], s58 offen
	v_add_u32_e32 v160, 0x80, v160
	buffer_load_dwordx4 v[162:165], v160, s[48:51], 0 offen
	buffer_load_dwordx4 v[166:169], v160, s[48:51], s46 offen
	buffer_load_dwordx4 v[176:179], v160, s[48:51], s47 offen
	buffer_load_dwordx4 v[180:183], v160, s[48:51], s58 offen
	buffer_load_dwordx4 v[184:187], v160, s[52:55], 0 offen
	buffer_load_dwordx4 v[242:245], v160, s[52:55], s46 offen
	buffer_load_dwordx4 v[246:249], v160, s[52:55], s47 offen
	buffer_load_dwordx4 v[250:253], v160, s[52:55], s58 offen
	v_add_u32_e32 v160, 0x80, v160
.Lgin1_last:
	s_movk_i32 s46, 0x7fff
	v_bfe_u32 v136, v112, 16, 1
	v_bfe_u32 v137, v113, 16, 1
	v_bfe_u32 v138, v114, 16, 1
	v_bfe_u32 v139, v115, 16, 1
	v_add3_u32 v112, v112, v136, s46
	v_add3_u32 v113, v113, v137, s46
	v_add3_u32 v114, v114, v138, s46
	v_add3_u32 v115, v115, v139, s46
	s_mov_b32 s101, 0x0
	buffer_store_short_d16_hi v112, v128, s[96:99], s101 offen
	buffer_store_short_d16_hi v113, v129, s[96:99], s101 offen
	buffer_store_short_d16_hi v114, v130, s[96:99], s101 offen
	buffer_store_short_d16_hi v115, v131, s[96:99], s101 offen
	v_bfe_u32 v136, v116, 16, 1
	v_bfe_u32 v137, v117, 16, 1
	v_bfe_u32 v138, v118, 16, 1
	v_bfe_u32 v139, v119, 16, 1
	v_add3_u32 v116, v116, v136, s46
	v_add3_u32 v117, v117, v137, s46
	v_add3_u32 v118, v118, v138, s46
	v_add3_u32 v119, v119, v139, s46
	s_mov_b32 s101, 0x40000
	buffer_store_short_d16_hi v116, v128, s[96:99], s101 offen
	buffer_store_short_d16_hi v117, v129, s[96:99], s101 offen
	buffer_store_short_d16_hi v118, v130, s[96:99], s101 offen
	buffer_store_short_d16_hi v119, v131, s[96:99], s101 offen
	v_bfe_u32 v136, v120, 16, 1
	v_bfe_u32 v137, v121, 16, 1
	v_bfe_u32 v138, v122, 16, 1
	v_bfe_u32 v139, v123, 16, 1
	v_add3_u32 v120, v120, v136, s46
	v_add3_u32 v121, v121, v137, s46
	v_add3_u32 v122, v122, v138, s46
	v_add3_u32 v123, v123, v139, s46
	s_mov_b32 s101, 0x80000
	buffer_store_short_d16_hi v120, v128, s[96:99], s101 offen
	buffer_store_short_d16_hi v121, v129, s[96:99], s101 offen
	buffer_store_short_d16_hi v122, v130, s[96:99], s101 offen
	buffer_store_short_d16_hi v123, v131, s[96:99], s101 offen
	v_bfe_u32 v136, v124, 16, 1
	v_bfe_u32 v137, v125, 16, 1
	v_bfe_u32 v138, v126, 16, 1
	v_bfe_u32 v139, v127, 16, 1
	v_add3_u32 v124, v124, v136, s46
	v_add3_u32 v125, v125, v137, s46
	v_add3_u32 v126, v126, v138, s46
	v_add3_u32 v127, v127, v139, s46
	s_mov_b32 s101, 0xc0000
	buffer_store_short_d16_hi v124, v128, s[96:99], s101 offen
	buffer_store_short_d16_hi v125, v129, s[96:99], s101 offen
	buffer_store_short_d16_hi v126, v130, s[96:99], s101 offen
	buffer_store_short_d16_hi v127, v131, s[96:99], s101 offen
	v_bfe_u32 v136, v96, 16, 1
	v_bfe_u32 v137, v97, 16, 1
	v_bfe_u32 v138, v98, 16, 1
	v_bfe_u32 v139, v99, 16, 1
	v_add3_u32 v96, v96, v136, s46
	v_add3_u32 v97, v97, v137, s46
	v_add3_u32 v98, v98, v138, s46
	v_add3_u32 v99, v99, v139, s46
	s_mov_b32 s101, 0x0
	buffer_store_short_d16_hi v96, v128, s[96:99], s101 offen offset:64
	buffer_store_short_d16_hi v97, v129, s[96:99], s101 offen offset:64
	buffer_store_short_d16_hi v98, v130, s[96:99], s101 offen offset:64
	buffer_store_short_d16_hi v99, v131, s[96:99], s101 offen offset:64
	v_bfe_u32 v136, v100, 16, 1
	v_bfe_u32 v137, v101, 16, 1
	v_bfe_u32 v138, v102, 16, 1
	v_bfe_u32 v139, v103, 16, 1
	v_add3_u32 v100, v100, v136, s46
	v_add3_u32 v101, v101, v137, s46
	v_add3_u32 v102, v102, v138, s46
	v_add3_u32 v103, v103, v139, s46
	s_mov_b32 s101, 0x40000
	buffer_store_short_d16_hi v100, v128, s[96:99], s101 offen offset:64
	buffer_store_short_d16_hi v101, v129, s[96:99], s101 offen offset:64
	buffer_store_short_d16_hi v102, v130, s[96:99], s101 offen offset:64
	buffer_store_short_d16_hi v103, v131, s[96:99], s101 offen offset:64
	v_bfe_u32 v136, v104, 16, 1
	v_bfe_u32 v137, v105, 16, 1
	v_bfe_u32 v138, v106, 16, 1
	v_bfe_u32 v139, v107, 16, 1
	v_add3_u32 v104, v104, v136, s46
	v_add3_u32 v105, v105, v137, s46
	v_add3_u32 v106, v106, v138, s46
	v_add3_u32 v107, v107, v139, s46
	s_mov_b32 s101, 0x80000
	buffer_store_short_d16_hi v104, v128, s[96:99], s101 offen offset:64
	buffer_store_short_d16_hi v105, v129, s[96:99], s101 offen offset:64
	buffer_store_short_d16_hi v106, v130, s[96:99], s101 offen offset:64
	buffer_store_short_d16_hi v107, v131, s[96:99], s101 offen offset:64
	v_bfe_u32 v136, v108, 16, 1
	v_bfe_u32 v137, v109, 16, 1
	v_bfe_u32 v138, v110, 16, 1
	v_bfe_u32 v139, v111, 16, 1
	v_add3_u32 v108, v108, v136, s46
	v_add3_u32 v109, v109, v137, s46
	v_add3_u32 v110, v110, v138, s46
	v_add3_u32 v111, v111, v139, s46
	s_mov_b32 s101, 0xc0000
	buffer_store_short_d16_hi v108, v128, s[96:99], s101 offen offset:64
	buffer_store_short_d16_hi v109, v129, s[96:99], s101 offen offset:64
	buffer_store_short_d16_hi v110, v130, s[96:99], s101 offen offset:64
	buffer_store_short_d16_hi v111, v131, s[96:99], s101 offen offset:64
	v_bfe_u32 v136, v80, 16, 1
	v_bfe_u32 v137, v81, 16, 1
	v_bfe_u32 v138, v82, 16, 1
	v_bfe_u32 v139, v83, 16, 1
	v_add3_u32 v80, v80, v136, s46
	v_add3_u32 v81, v81, v137, s46
	v_add3_u32 v82, v82, v138, s46
	v_add3_u32 v83, v83, v139, s46
	s_mov_b32 s101, 0x100000
	buffer_store_short_d16_hi v80, v128, s[96:99], s101 offen
	buffer_store_short_d16_hi v81, v129, s[96:99], s101 offen
	buffer_store_short_d16_hi v82, v130, s[96:99], s101 offen
	buffer_store_short_d16_hi v83, v131, s[96:99], s101 offen
	v_bfe_u32 v136, v84, 16, 1
	v_bfe_u32 v137, v85, 16, 1
	v_bfe_u32 v138, v86, 16, 1
	v_bfe_u32 v139, v87, 16, 1
	v_add3_u32 v84, v84, v136, s46
	v_add3_u32 v85, v85, v137, s46
	v_add3_u32 v86, v86, v138, s46
	v_add3_u32 v87, v87, v139, s46
	s_mov_b32 s101, 0x140000
	buffer_store_short_d16_hi v84, v128, s[96:99], s101 offen
	buffer_store_short_d16_hi v85, v129, s[96:99], s101 offen
	buffer_store_short_d16_hi v86, v130, s[96:99], s101 offen
	buffer_store_short_d16_hi v87, v131, s[96:99], s101 offen
	v_bfe_u32 v136, v88, 16, 1
	v_bfe_u32 v137, v89, 16, 1
	v_bfe_u32 v138, v90, 16, 1
	v_bfe_u32 v139, v91, 16, 1
	v_add3_u32 v88, v88, v136, s46
	v_add3_u32 v89, v89, v137, s46
	v_add3_u32 v90, v90, v138, s46
	v_add3_u32 v91, v91, v139, s46
	s_mov_b32 s101, 0x180000
	buffer_store_short_d16_hi v88, v128, s[96:99], s101 offen
	buffer_store_short_d16_hi v89, v129, s[96:99], s101 offen
	buffer_store_short_d16_hi v90, v130, s[96:99], s101 offen
	buffer_store_short_d16_hi v91, v131, s[96:99], s101 offen
	v_bfe_u32 v136, v92, 16, 1
	v_bfe_u32 v137, v93, 16, 1
	v_bfe_u32 v138, v94, 16, 1
	v_bfe_u32 v139, v95, 16, 1
	v_add3_u32 v92, v92, v136, s46
	v_add3_u32 v93, v93, v137, s46
	v_add3_u32 v94, v94, v138, s46
	v_add3_u32 v95, v95, v139, s46
	s_mov_b32 s101, 0x1c0000
	buffer_store_short_d16_hi v92, v128, s[96:99], s101 offen
	buffer_store_short_d16_hi v93, v129, s[96:99], s101 offen
	buffer_store_short_d16_hi v94, v130, s[96:99], s101 offen
	buffer_store_short_d16_hi v95, v131, s[96:99], s101 offen
	v_bfe_u32 v136, v64, 16, 1
	v_bfe_u32 v137, v65, 16, 1
	v_bfe_u32 v138, v66, 16, 1
	v_bfe_u32 v139, v67, 16, 1
	v_add3_u32 v64, v64, v136, s46
	v_add3_u32 v65, v65, v137, s46
	v_add3_u32 v66, v66, v138, s46
	v_add3_u32 v67, v67, v139, s46
	s_mov_b32 s101, 0x100000
	buffer_store_short_d16_hi v64, v128, s[96:99], s101 offen offset:64
	buffer_store_short_d16_hi v65, v129, s[96:99], s101 offen offset:64
	buffer_store_short_d16_hi v66, v130, s[96:99], s101 offen offset:64
	buffer_store_short_d16_hi v67, v131, s[96:99], s101 offen offset:64
	v_bfe_u32 v136, v68, 16, 1
	v_bfe_u32 v137, v69, 16, 1
	v_bfe_u32 v138, v70, 16, 1
	v_bfe_u32 v139, v71, 16, 1
	v_add3_u32 v68, v68, v136, s46
	v_add3_u32 v69, v69, v137, s46
	v_add3_u32 v70, v70, v138, s46
	v_add3_u32 v71, v71, v139, s46
	s_mov_b32 s101, 0x140000
	buffer_store_short_d16_hi v68, v128, s[96:99], s101 offen offset:64
	buffer_store_short_d16_hi v69, v129, s[96:99], s101 offen offset:64
	buffer_store_short_d16_hi v70, v130, s[96:99], s101 offen offset:64
	buffer_store_short_d16_hi v71, v131, s[96:99], s101 offen offset:64
	v_bfe_u32 v136, v72, 16, 1
	v_bfe_u32 v137, v73, 16, 1
	v_bfe_u32 v138, v74, 16, 1
	v_bfe_u32 v139, v75, 16, 1
	v_add3_u32 v72, v72, v136, s46
	v_add3_u32 v73, v73, v137, s46
	v_add3_u32 v74, v74, v138, s46
	v_add3_u32 v75, v75, v139, s46
	s_mov_b32 s101, 0x180000
	buffer_store_short_d16_hi v72, v128, s[96:99], s101 offen offset:64
	buffer_store_short_d16_hi v73, v129, s[96:99], s101 offen offset:64
	buffer_store_short_d16_hi v74, v130, s[96:99], s101 offen offset:64
	buffer_store_short_d16_hi v75, v131, s[96:99], s101 offen offset:64
	v_bfe_u32 v136, v76, 16, 1
	v_bfe_u32 v137, v77, 16, 1
	v_bfe_u32 v138, v78, 16, 1
	v_bfe_u32 v139, v79, 16, 1
	v_add3_u32 v76, v76, v136, s46
	v_add3_u32 v77, v77, v137, s46
	v_add3_u32 v78, v78, v138, s46
	v_add3_u32 v79, v79, v139, s46
	s_mov_b32 s101, 0x1c0000
	buffer_store_short_d16_hi v76, v128, s[96:99], s101 offen offset:64
	buffer_store_short_d16_hi v77, v129, s[96:99], s101 offen offset:64
	buffer_store_short_d16_hi v78, v130, s[96:99], s101 offen offset:64
	buffer_store_short_d16_hi v79, v131, s[96:99], s101 offen offset:64
	v_bfe_u32 v136, v48, 16, 1
	v_bfe_u32 v137, v49, 16, 1
	v_bfe_u32 v138, v50, 16, 1
	v_bfe_u32 v139, v51, 16, 1
	v_add3_u32 v48, v48, v136, s46
	v_add3_u32 v49, v49, v137, s46
	v_add3_u32 v50, v50, v138, s46
	v_add3_u32 v51, v51, v139, s46
	s_mov_b32 s101, 0x200000
	buffer_store_short_d16_hi v48, v128, s[96:99], s101 offen
	buffer_store_short_d16_hi v49, v129, s[96:99], s101 offen
	buffer_store_short_d16_hi v50, v130, s[96:99], s101 offen
	buffer_store_short_d16_hi v51, v131, s[96:99], s101 offen
	v_bfe_u32 v136, v52, 16, 1
	v_bfe_u32 v137, v53, 16, 1
	v_bfe_u32 v138, v54, 16, 1
	v_bfe_u32 v139, v55, 16, 1
	v_add3_u32 v52, v52, v136, s46
	v_add3_u32 v53, v53, v137, s46
	v_add3_u32 v54, v54, v138, s46
	v_add3_u32 v55, v55, v139, s46
	s_mov_b32 s101, 0x240000
	buffer_store_short_d16_hi v52, v128, s[96:99], s101 offen
	buffer_store_short_d16_hi v53, v129, s[96:99], s101 offen
	buffer_store_short_d16_hi v54, v130, s[96:99], s101 offen
	buffer_store_short_d16_hi v55, v131, s[96:99], s101 offen
	v_bfe_u32 v136, v56, 16, 1
	v_bfe_u32 v137, v57, 16, 1
	v_bfe_u32 v138, v58, 16, 1
	v_bfe_u32 v139, v59, 16, 1
	v_add3_u32 v56, v56, v136, s46
	v_add3_u32 v57, v57, v137, s46
	v_add3_u32 v58, v58, v138, s46
	v_add3_u32 v59, v59, v139, s46
	s_mov_b32 s101, 0x280000
	buffer_store_short_d16_hi v56, v128, s[96:99], s101 offen
	buffer_store_short_d16_hi v57, v129, s[96:99], s101 offen
	buffer_store_short_d16_hi v58, v130, s[96:99], s101 offen
	buffer_store_short_d16_hi v59, v131, s[96:99], s101 offen
	v_bfe_u32 v136, v60, 16, 1
	v_bfe_u32 v137, v61, 16, 1
	v_bfe_u32 v138, v62, 16, 1
	v_bfe_u32 v139, v63, 16, 1
	v_add3_u32 v60, v60, v136, s46
	v_add3_u32 v61, v61, v137, s46
	v_add3_u32 v62, v62, v138, s46
	v_add3_u32 v63, v63, v139, s46
	s_mov_b32 s101, 0x2c0000
	buffer_store_short_d16_hi v60, v128, s[96:99], s101 offen
	buffer_store_short_d16_hi v61, v129, s[96:99], s101 offen
	buffer_store_short_d16_hi v62, v130, s[96:99], s101 offen
	buffer_store_short_d16_hi v63, v131, s[96:99], s101 offen
	v_bfe_u32 v136, v32, 16, 1
	v_bfe_u32 v137, v33, 16, 1
	v_bfe_u32 v138, v34, 16, 1
	v_bfe_u32 v139, v35, 16, 1
	v_add3_u32 v32, v32, v136, s46
	v_add3_u32 v33, v33, v137, s46
	v_add3_u32 v34, v34, v138, s46
	v_add3_u32 v35, v35, v139, s46
	s_mov_b32 s101, 0x200000
	buffer_store_short_d16_hi v32, v128, s[96:99], s101 offen offset:64
	buffer_store_short_d16_hi v33, v129, s[96:99], s101 offen offset:64
	buffer_store_short_d16_hi v34, v130, s[96:99], s101 offen offset:64
	buffer_store_short_d16_hi v35, v131, s[96:99], s101 offen offset:64
	v_bfe_u32 v136, v36, 16, 1
	v_bfe_u32 v137, v37, 16, 1
	v_bfe_u32 v138, v38, 16, 1
	v_bfe_u32 v139, v39, 16, 1
	v_add3_u32 v36, v36, v136, s46
	v_add3_u32 v37, v37, v137, s46
	v_add3_u32 v38, v38, v138, s46
	v_add3_u32 v39, v39, v139, s46
	s_mov_b32 s101, 0x240000
	buffer_store_short_d16_hi v36, v128, s[96:99], s101 offen offset:64
	buffer_store_short_d16_hi v37, v129, s[96:99], s101 offen offset:64
	buffer_store_short_d16_hi v38, v130, s[96:99], s101 offen offset:64
	buffer_store_short_d16_hi v39, v131, s[96:99], s101 offen offset:64
	v_bfe_u32 v136, v40, 16, 1
	v_bfe_u32 v137, v41, 16, 1
	v_bfe_u32 v138, v42, 16, 1
	v_bfe_u32 v139, v43, 16, 1
	v_add3_u32 v40, v40, v136, s46
	v_add3_u32 v41, v41, v137, s46
	v_add3_u32 v42, v42, v138, s46
	v_add3_u32 v43, v43, v139, s46
	s_mov_b32 s101, 0x280000
	buffer_store_short_d16_hi v40, v128, s[96:99], s101 offen offset:64
	buffer_store_short_d16_hi v41, v129, s[96:99], s101 offen offset:64
	buffer_store_short_d16_hi v42, v130, s[96:99], s101 offen offset:64
	buffer_store_short_d16_hi v43, v131, s[96:99], s101 offen offset:64
	v_bfe_u32 v136, v44, 16, 1
	v_bfe_u32 v137, v45, 16, 1
	v_bfe_u32 v138, v46, 16, 1
	v_bfe_u32 v139, v47, 16, 1
	v_add3_u32 v44, v44, v136, s46
	v_add3_u32 v45, v45, v137, s46
	v_add3_u32 v46, v46, v138, s46
	v_add3_u32 v47, v47, v139, s46
	s_mov_b32 s101, 0x2c0000
	buffer_store_short_d16_hi v44, v128, s[96:99], s101 offen offset:64
	buffer_store_short_d16_hi v45, v129, s[96:99], s101 offen offset:64
	buffer_store_short_d16_hi v46, v130, s[96:99], s101 offen offset:64
	buffer_store_short_d16_hi v47, v131, s[96:99], s101 offen offset:64
	v_bfe_u32 v136, v16, 16, 1
	v_bfe_u32 v137, v17, 16, 1
	v_bfe_u32 v138, v18, 16, 1
	v_bfe_u32 v139, v19, 16, 1
	v_add3_u32 v16, v16, v136, s46
	v_add3_u32 v17, v17, v137, s46
	v_add3_u32 v18, v18, v138, s46
	v_add3_u32 v19, v19, v139, s46
	s_mov_b32 s101, 0x300000
	buffer_store_short_d16_hi v16, v128, s[96:99], s101 offen
	buffer_store_short_d16_hi v17, v129, s[96:99], s101 offen
	buffer_store_short_d16_hi v18, v130, s[96:99], s101 offen
	buffer_store_short_d16_hi v19, v131, s[96:99], s101 offen
	v_bfe_u32 v136, v20, 16, 1
	v_bfe_u32 v137, v21, 16, 1
	v_bfe_u32 v138, v22, 16, 1
	v_bfe_u32 v139, v23, 16, 1
	v_add3_u32 v20, v20, v136, s46
	v_add3_u32 v21, v21, v137, s46
	v_add3_u32 v22, v22, v138, s46
	v_add3_u32 v23, v23, v139, s46
	s_mov_b32 s101, 0x340000
	buffer_store_short_d16_hi v20, v128, s[96:99], s101 offen
	buffer_store_short_d16_hi v21, v129, s[96:99], s101 offen
	buffer_store_short_d16_hi v22, v130, s[96:99], s101 offen
	buffer_store_short_d16_hi v23, v131, s[96:99], s101 offen
	v_bfe_u32 v136, v24, 16, 1
	v_bfe_u32 v137, v25, 16, 1
	v_bfe_u32 v138, v26, 16, 1
	v_bfe_u32 v139, v27, 16, 1
	v_add3_u32 v24, v24, v136, s46
	v_add3_u32 v25, v25, v137, s46
	v_add3_u32 v26, v26, v138, s46
	v_add3_u32 v27, v27, v139, s46
	s_mov_b32 s101, 0x380000
	buffer_store_short_d16_hi v24, v128, s[96:99], s101 offen
	buffer_store_short_d16_hi v25, v129, s[96:99], s101 offen
	buffer_store_short_d16_hi v26, v130, s[96:99], s101 offen
	buffer_store_short_d16_hi v27, v131, s[96:99], s101 offen
	v_bfe_u32 v136, v28, 16, 1
	v_bfe_u32 v137, v29, 16, 1
	v_bfe_u32 v138, v30, 16, 1
	v_bfe_u32 v139, v31, 16, 1
	v_add3_u32 v28, v28, v136, s46
	v_add3_u32 v29, v29, v137, s46
	v_add3_u32 v30, v30, v138, s46
	v_add3_u32 v31, v31, v139, s46
	s_mov_b32 s101, 0x3c0000
	buffer_store_short_d16_hi v28, v128, s[96:99], s101 offen
	buffer_store_short_d16_hi v29, v129, s[96:99], s101 offen
	buffer_store_short_d16_hi v30, v130, s[96:99], s101 offen
	buffer_store_short_d16_hi v31, v131, s[96:99], s101 offen
	v_bfe_u32 v136, v0, 16, 1
	v_bfe_u32 v137, v1, 16, 1
	v_bfe_u32 v138, v2, 16, 1
	v_bfe_u32 v139, v3, 16, 1
	v_add3_u32 v0, v0, v136, s46
	v_add3_u32 v1, v1, v137, s46
	v_add3_u32 v2, v2, v138, s46
	v_add3_u32 v3, v3, v139, s46
	s_mov_b32 s101, 0x300000
	buffer_store_short_d16_hi v0, v128, s[96:99], s101 offen offset:64
	buffer_store_short_d16_hi v1, v129, s[96:99], s101 offen offset:64
	buffer_store_short_d16_hi v2, v130, s[96:99], s101 offen offset:64
	buffer_store_short_d16_hi v3, v131, s[96:99], s101 offen offset:64
	v_bfe_u32 v136, v4, 16, 1
	v_bfe_u32 v137, v5, 16, 1
	v_bfe_u32 v138, v6, 16, 1
	v_bfe_u32 v139, v7, 16, 1
	v_add3_u32 v4, v4, v136, s46
	v_add3_u32 v5, v5, v137, s46
	v_add3_u32 v6, v6, v138, s46
	v_add3_u32 v7, v7, v139, s46
	s_mov_b32 s101, 0x340000
	buffer_store_short_d16_hi v4, v128, s[96:99], s101 offen offset:64
	buffer_store_short_d16_hi v5, v129, s[96:99], s101 offen offset:64
	buffer_store_short_d16_hi v6, v130, s[96:99], s101 offen offset:64
	buffer_store_short_d16_hi v7, v131, s[96:99], s101 offen offset:64
	v_bfe_u32 v136, v8, 16, 1
	v_bfe_u32 v137, v9, 16, 1
	v_bfe_u32 v138, v10, 16, 1
	v_bfe_u32 v139, v11, 16, 1
	v_add3_u32 v8, v8, v136, s46
	v_add3_u32 v9, v9, v137, s46
	v_add3_u32 v10, v10, v138, s46
	v_add3_u32 v11, v11, v139, s46
	s_mov_b32 s101, 0x380000
	buffer_store_short_d16_hi v8, v128, s[96:99], s101 offen offset:64
	buffer_store_short_d16_hi v9, v129, s[96:99], s101 offen offset:64
	buffer_store_short_d16_hi v10, v130, s[96:99], s101 offen offset:64
	buffer_store_short_d16_hi v11, v131, s[96:99], s101 offen offset:64
	v_bfe_u32 v136, v12, 16, 1
	v_bfe_u32 v137, v13, 16, 1
	v_bfe_u32 v138, v14, 16, 1
	v_bfe_u32 v139, v15, 16, 1
	v_add3_u32 v12, v12, v136, s46
	v_add3_u32 v13, v13, v137, s46
	v_add3_u32 v14, v14, v138, s46
	v_add3_u32 v15, v15, v139, s46
	s_mov_b32 s101, 0x3c0000
	buffer_store_short_d16_hi v12, v128, s[96:99], s101 offen offset:64
	buffer_store_short_d16_hi v13, v129, s[96:99], s101 offen offset:64
	buffer_store_short_d16_hi v14, v130, s[96:99], s101 offen offset:64
	buffer_store_short_d16_hi v15, v131, s[96:99], s101 offen offset:64
	s_cmpk_lt_i32 s39, 0x600
	s_cbranch_scc1 .Lgin1_tile
	s_branch .LBB0_1659

.LBB0_2633:
	s_bfe_u32 s100, s38, 0x30005
	s_and_b32 s101, s38, 31
	s_lshr_b32 s82, s38, 8
	s_lshl_b32 s64, s82, 5
	s_lshr_b32 s82, s100, 3
	s_lshl_b32 s82, s82, 5
	s_add_u32 s64, s64, s82
	s_lshr_b32 s82, s101, 0
	s_add_u32 s64, s64, s82
	s_and_b32 s82, s100, 7
	s_lshl_b32 s82, s82, 0
	s_and_b32 s101, s101, 0
	s_add_u32 s82, s82, s101
	s_lshl_b32 s64, s64, 8
	s_lshl_b32 s82, s82, 8
	s_lshl_b32 s100, s64, 12
	s_add_u32 s100, s100, 0x6224000
	s_add_u32 s48, s92, s100
	s_addc_u32 s49, s93, 0
	s_and_b32 s49, s49, 0xffff
	s_mov_b32 s50, 0x100000
	s_mov_b32 s51, 0x20000
	s_lshl_b32 s100, s82, 12
	s_add_u32 s100, s100, 0x4380000
	s_add_u32 s52, s92, s100
	s_addc_u32 s53, s93, 0
	s_and_b32 s53, s53, 0xffff
	s_sub_u32 s100, 0x800, s82
	s_min_u32 s100, s100, 0x100
	s_lshl_b32 s54, s100, 12
	s_mov_b32 s55, 0x20000
	s_mov_b32 s46, 0x40000
	s_mov_b32 s47, 0x80000
	s_mov_b32 s58, 0xc0000
	v_lshrrev_b32_e32 v128, 3, v190
	v_and_b32_e32 v129, 7, v190
	v_lshlrev_b32_e32 v129, 4, v129
	v_lshl_add_u32 v160, v128, 12, v129
	v_mul_u32_u24_e32 v130, 0x90, v128
	v_add_u32_e32 v170, v130, v129
	v_add_u32_e32 v171, 0x12000, v170
	v_and_b32_e32 v131, 31, v190
	v_bfe_u32 v132, v190, 5, 1
	v_bfe_u32 v133, v190, 6, 2
	v_bfe_u32 v134, v190, 8, 1
	v_lshl_add_u32 v135, v134, 7, v131
	v_mul_u32_u24_e32 v135, 0x90, v135
	v_lshl_add_u32 v175, v132, 4, v135
	v_lshl_add_u32 v136, v133, 6, v131
	v_mul_u32_u24_e32 v136, 0x90, v136
	v_lshl_add_u32 v136, v132, 4, v136
	v_add_u32_e32 v254, 0x12000, v136
	buffer_load_dwordx4 v[216:219], v160, s[48:51], 0 offen
	buffer_load_dwordx4 v[220:223], v160, s[48:51], s46 offen
	buffer_load_dwordx4 v[224:227], v160, s[48:51], s47 offen
	buffer_load_dwordx4 v[228:231], v160, s[48:51], s58 offen
	buffer_load_dwordx4 v[232:235], v160, s[52:55], 0 offen
	buffer_load_dwordx4 v[236:239], v160, s[52:55], s46 offen
	buffer_load_dwordx4 v[152:155], v160, s[52:55], s47 offen
	buffer_load_dwordx4 v[156:159], v160, s[52:55], s58 offen
	v_add_u32_e32 v160, 0x80, v160
	buffer_load_dwordx4 v[162:165], v160, s[48:51], 0 offen
	buffer_load_dwordx4 v[166:169], v160, s[48:51], s46 offen
	buffer_load_dwordx4 v[176:179], v160, s[48:51], s47 offen
	buffer_load_dwordx4 v[180:183], v160, s[48:51], s58 offen
	buffer_load_dwordx4 v[184:187], v160, s[52:55], 0 offen
	buffer_load_dwordx4 v[242:245], v160, s[52:55], s46 offen
	buffer_load_dwordx4 v[246:249], v160, s[52:55], s47 offen
	buffer_load_dwordx4 v[250:253], v160, s[52:55], s58 offen
	v_add_u32_e32 v160, 0x80, v160

.Lgwq1_loop:
	ds_read_b128 v[144:147], v254 offset:0
	ds_read_b128 v[148:151], v254 offset:4608
	ds_read_b128 v[128:131], v175 offset:0
	ds_read_b128 v[132:135], v175 offset:4608
	ds_read_b128 v[136:139], v175 offset:9216
	ds_read_b128 v[140:143], v175 offset:13824
	v_mfma_f32_32x32x16_bf16 v[112:127], v[192:195], v[208:211], v[112:127]
	s_waitcnt vmcnt(8)
	v_mfma_f32_32x32x16_bf16 v[96:111], v[192:195], v[212:215], v[96:111]
	ds_write_b128 v170, v[162:165] offset:36864
	v_mfma_f32_32x32x16_bf16 v[80:95], v[196:199], v[208:211], v[80:95]
	ds_write_b128 v170, v[166:169] offset:46080
	v_mfma_f32_32x32x16_bf16 v[64:79], v[196:199], v[212:215], v[64:79]
	ds_write_b128 v170, v[176:179] offset:55296
	v_mfma_f32_32x32x16_bf16 v[48:63], v[200:203], v[208:211], v[48:63]
	ds_write_b128 v170, v[180:183] offset:64512
	v_mfma_f32_32x32x16_bf16 v[32:47], v[200:203], v[212:215], v[32:47]
	ds_write_b128 v171, v[184:187] offset:36864
	v_mfma_f32_32x32x16_bf16 v[16:31], v[204:207], v[208:211], v[16:31]
	ds_write_b128 v171, v[242:245] offset:46080
	v_mfma_f32_32x32x16_bf16 v[0:15], v[204:207], v[212:215], v[0:15]
	ds_write_b128 v171, v[246:249] offset:55296
	ds_write_b128 v171, v[250:253] offset:64512
	s_waitcnt lgkmcnt(8)
	v_mfma_f32_32x32x16_bf16 v[112:127], v[128:131], v[144:147], v[112:127]
	ds_read_b128 v[208:211], v254 offset:32
	v_mfma_f32_32x32x16_bf16 v[96:111], v[128:131], v[148:151], v[96:111]
	ds_read_b128 v[212:215], v254 offset:4640
	ds_read_b128 v[192:195], v175 offset:32
	v_mfma_f32_32x32x16_bf16 v[80:95], v[132:135], v[144:147], v[80:95]
	ds_read_b128 v[196:199], v175 offset:4640
	ds_read_b128 v[200:203], v175 offset:9248
	v_mfma_f32_32x32x16_bf16 v[64:79], v[132:135], v[148:151], v[64:79]
	ds_read_b128 v[204:207], v175 offset:13856
	buffer_load_dwordx4 v[162:165], v160, s[48:51], 0 offen
	v_mfma_f32_32x32x16_bf16 v[48:63], v[136:139], v[144:147], v[48:63]
	buffer_load_dwordx4 v[166:169], v160, s[48:51], s46 offen
	buffer_load_dwordx4 v[176:179], v160, s[48:51], s47 offen
	v_mfma_f32_32x32x16_bf16 v[32:47], v[136:139], v[148:151], v[32:47]
	buffer_load_dwordx4 v[180:183], v160, s[48:51], s58 offen
	buffer_load_dwordx4 v[184:187], v160, s[52:55], 0 offen
	v_mfma_f32_32x32x16_bf16 v[16:31], v[140:143], v[144:147], v[16:31]
	buffer_load_dwordx4 v[242:245], v160, s[52:55], s46 offen
	buffer_load_dwordx4 v[246:249], v160, s[52:55], s47 offen
	v_mfma_f32_32x32x16_bf16 v[0:15], v[140:143], v[148:151], v[0:15]
	buffer_load_dwordx4 v[250:253], v160, s[52:55], s58 offen
	v_add_u32_e32 v160, 0x80, v160
	s_waitcnt lgkmcnt(0)
	v_mfma_f32_32x32x16_bf16 v[112:127], v[192:195], v[208:211], v[112:127]
	v_mfma_f32_32x32x16_bf16 v[96:111], v[192:195], v[212:215], v[96:111]
	ds_read_b128 v[144:147], v254 offset:64
	v_mfma_f32_32x32x16_bf16 v[80:95], v[196:199], v[208:211], v[80:95]
	ds_read_b128 v[148:151], v254 offset:4672
	v_mfma_f32_32x32x16_bf16 v[64:79], v[196:199], v[212:215], v[64:79]
	ds_read_b128 v[128:131], v175 offset:64
	v_mfma_f32_32x32x16_bf16 v[48:63], v[200:203], v[208:211], v[48:63]
	v_mfma_f32_32x32x16_bf16 v[32:47], v[200:203], v[212:215], v[32:47]
	ds_read_b128 v[132:135], v175 offset:4672
	v_mfma_f32_32x32x16_bf16 v[16:31], v[204:207], v[208:211], v[16:31]
	ds_read_b128 v[136:139], v175 offset:9280
	v_mfma_f32_32x32x16_bf16 v[0:15], v[204:207], v[212:215], v[0:15]
	ds_read_b128 v[140:143], v175 offset:13888
	s_waitcnt lgkmcnt(0)
	v_mfma_f32_32x32x16_bf16 v[112:127], v[128:131], v[144:147], v[112:127]
	v_mfma_f32_32x32x16_bf16 v[96:111], v[128:131], v[148:151], v[96:111]
	ds_read_b128 v[208:211], v254 offset:96
	v_mfma_f32_32x32x16_bf16 v[80:95], v[132:135], v[144:147], v[80:95]
	ds_read_b128 v[212:215], v254 offset:4704
	v_mfma_f32_32x32x16_bf16 v[64:79], v[132:135], v[148:151], v[64:79]
	ds_read_b128 v[192:195], v175 offset:96
	v_mfma_f32_32x32x16_bf16 v[48:63], v[136:139], v[144:147], v[48:63]
	v_mfma_f32_32x32x16_bf16 v[32:47], v[136:139], v[148:151], v[32:47]
	ds_read_b128 v[196:199], v175 offset:4704
	v_mfma_f32_32x32x16_bf16 v[16:31], v[140:143], v[144:147], v[16:31]
	ds_read_b128 v[200:203], v175 offset:9312
	v_mfma_f32_32x32x16_bf16 v[0:15], v[140:143], v[148:151], v[0:15]
	ds_read_b128 v[204:207], v175 offset:13920
	s_waitcnt lgkmcnt(0)
	s_barrier
	ds_read_b128 v[144:147], v254 offset:36864
	ds_read_b128 v[148:151], v254 offset:41472
	ds_read_b128 v[128:131], v175 offset:36864
	ds_read_b128 v[132:135], v175 offset:41472
	ds_read_b128 v[136:139], v175 offset:46080
	ds_read_b128 v[140:143], v175 offset:50688
	v_mfma_f32_32x32x16_bf16 v[112:127], v[192:195], v[208:211], v[112:127]
	s_waitcnt vmcnt(8)
	v_mfma_f32_32x32x16_bf16 v[96:111], v[192:195], v[212:215], v[96:111]
	ds_write_b128 v170, v[216:219] offset:0
	v_mfma_f32_32x32x16_bf16 v[80:95], v[196:199], v[208:211], v[80:95]
	ds_write_b128 v170, v[220:223] offset:9216
	v_mfma_f32_32x32x16_bf16 v[64:79], v[196:199], v[212:215], v[64:79]
	ds_write_b128 v170, v[224:227] offset:18432
	v_mfma_f32_32x32x16_bf16 v[48:63], v[200:203], v[208:211], v[48:63]
	ds_write_b128 v170, v[228:231] offset:27648
	v_mfma_f32_32x32x16_bf16 v[32:47], v[200:203], v[212:215], v[32:47]
	ds_write_b128 v171, v[232:235] offset:0
	v_mfma_f32_32x32x16_bf16 v[16:31], v[204:207], v[208:211], v[16:31]
	ds_write_b128 v171, v[236:239] offset:9216
	v_mfma_f32_32x32x16_bf16 v[0:15], v[204:207], v[212:215], v[0:15]
	ds_write_b128 v171, v[152:155] offset:18432
	ds_write_b128 v171, v[156:159] offset:27648
	s_waitcnt lgkmcnt(8)
	v_mfma_f32_32x32x16_bf16 v[112:127], v[128:131], v[144:147], v[112:127]
	ds_read_b128 v[208:211], v254 offset:36896
	v_mfma_f32_32x32x16_bf16 v[96:111], v[128:131], v[148:151], v[96:111]
	ds_read_b128 v[212:215], v254 offset:41504
	ds_read_b128 v[192:195], v175 offset:36896
	v_mfma_f32_32x32x16_bf16 v[80:95], v[132:135], v[144:147], v[80:95]
	ds_read_b128 v[196:199], v175 offset:41504
	ds_read_b128 v[200:203], v175 offset:46112
	v_mfma_f32_32x32x16_bf16 v[64:79], v[132:135], v[148:151], v[64:79]
	ds_read_b128 v[204:207], v175 offset:50720
	buffer_load_dwordx4 v[216:219], v160, s[48:51], 0 offen
	v_mfma_f32_32x32x16_bf16 v[48:63], v[136:139], v[144:147], v[48:63]
	buffer_load_dwordx4 v[220:223], v160, s[48:51], s46 offen
	buffer_load_dwordx4 v[224:227], v160, s[48:51], s47 offen
	v_mfma_f32_32x32x16_bf16 v[32:47], v[136:139], v[148:151], v[32:47]
	buffer_load_dwordx4 v[228:231], v160, s[48:51], s58 offen
	buffer_load_dwordx4 v[232:235], v160, s[52:55], 0 offen
	v_mfma_f32_32x32x16_bf16 v[16:31], v[140:143], v[144:147], v[16:31]
	buffer_load_dwordx4 v[236:239], v160, s[52:55], s46 offen
	buffer_load_dwordx4 v[152:155], v160, s[52:55], s47 offen
	v_mfma_f32_32x32x16_bf16 v[0:15], v[140:143], v[148:151], v[0:15]
	buffer_load_dwordx4 v[156:159], v160, s[52:55], s58 offen
	v_add_u32_e32 v160, 0x80, v160
	s_waitcnt lgkmcnt(0)
	v_mfma_f32_32x32x16_bf16 v[112:127], v[192:195], v[208:211], v[112:127]
	v_mfma_f32_32x32x16_bf16 v[96:111], v[192:195], v[212:215], v[96:111]
	ds_read_b128 v[144:147], v254 offset:36928
	v_mfma_f32_32x32x16_bf16 v[80:95], v[196:199], v[208:211], v[80:95]
	ds_read_b128 v[148:151], v254 offset:41536
	v_mfma_f32_32x32x16_bf16 v[64:79], v[196:199], v[212:215], v[64:79]
	ds_read_b128 v[128:131], v175 offset:36928
	v_mfma_f32_32x32x16_bf16 v[48:63], v[200:203], v[208:211], v[48:63]
	v_mfma_f32_32x32x16_bf16 v[32:47], v[200:203], v[212:215], v[32:47]
	ds_read_b128 v[132:135], v175 offset:41536
	v_mfma_f32_32x32x16_bf16 v[16:31], v[204:207], v[208:211], v[16:31]
	ds_read_b128 v[136:139], v175 offset:46144
	v_mfma_f32_32x32x16_bf16 v[0:15], v[204:207], v[212:215], v[0:15]
	ds_read_b128 v[140:143], v175 offset:50752
	s_waitcnt lgkmcnt(0)
	v_mfma_f32_32x32x16_bf16 v[112:127], v[128:131], v[144:147], v[112:127]
	v_mfma_f32_32x32x16_bf16 v[96:111], v[128:131], v[148:151], v[96:111]
	ds_read_b128 v[208:211], v254 offset:36960
	v_mfma_f32_32x32x16_bf16 v[80:95], v[132:135], v[144:147], v[80:95]
	ds_read_b128 v[212:215], v254 offset:41568
	v_mfma_f32_32x32x16_bf16 v[64:79], v[132:135], v[148:151], v[64:79]
	ds_read_b128 v[192:195], v175 offset:36960
	v_mfma_f32_32x32x16_bf16 v[48:63], v[136:139], v[144:147], v[48:63]
	v_mfma_f32_32x32x16_bf16 v[32:47], v[136:139], v[148:151], v[32:47]
	ds_read_b128 v[196:199], v175 offset:41568
	v_mfma_f32_32x32x16_bf16 v[16:31], v[140:143], v[144:147], v[16:31]
	ds_read_b128 v[200:203], v175 offset:46176
	v_mfma_f32_32x32x16_bf16 v[0:15], v[140:143], v[148:151], v[0:15]
	ds_read_b128 v[204:207], v175 offset:50784
	s_waitcnt lgkmcnt(0)
	s_barrier
	s_add_i32 s59, s59, -1
	s_cmp_lg_u32 s59, 0
	s_cbranch_scc1 .Lgwq1_loop
	ds_read_b128 v[144:147], v254 offset:0
	ds_read_b128 v[148:151], v254 offset:4608
	ds_read_b128 v[128:131], v175 offset:0
	ds_read_b128 v[132:135], v175 offset:4608
	ds_read_b128 v[136:139], v175 offset:9216
	ds_read_b128 v[140:143], v175 offset:13824
	v_mfma_f32_32x32x16_bf16 v[112:127], v[192:195], v[208:211], v[112:127]
	s_waitcnt vmcnt(8)
	v_mfma_f32_32x32x16_bf16 v[96:111], v[192:195], v[212:215], v[96:111]
	ds_write_b128 v170, v[162:165] offset:36864
	v_mfma_f32_32x32x16_bf16 v[80:95], v[196:199], v[208:211], v[80:95]
	ds_write_b128 v170, v[166:169] offset:46080
	v_mfma_f32_32x32x16_bf16 v[64:79], v[196:199], v[212:215], v[64:79]
	ds_write_b128 v170, v[176:179] offset:55296
	v_mfma_f32_32x32x16_bf16 v[48:63], v[200:203], v[208:211], v[48:63]
	ds_write_b128 v170, v[180:183] offset:64512
	v_mfma_f32_32x32x16_bf16 v[32:47], v[200:203], v[212:215], v[32:47]
	ds_write_b128 v171, v[184:187] offset:36864
	v_mfma_f32_32x32x16_bf16 v[16:31], v[204:207], v[208:211], v[16:31]
	ds_write_b128 v171, v[242:245] offset:46080
	v_mfma_f32_32x32x16_bf16 v[0:15], v[204:207], v[212:215], v[0:15]
	ds_write_b128 v171, v[246:249] offset:55296
	ds_write_b128 v171, v[250:253] offset:64512
	s_waitcnt lgkmcnt(8)
	v_mfma_f32_32x32x16_bf16 v[112:127], v[128:131], v[144:147], v[112:127]
	ds_read_b128 v[208:211], v254 offset:32
	v_mfma_f32_32x32x16_bf16 v[96:111], v[128:131], v[148:151], v[96:111]
	ds_read_b128 v[212:215], v254 offset:4640
	ds_read_b128 v[192:195], v175 offset:32
	v_mfma_f32_32x32x16_bf16 v[80:95], v[132:135], v[144:147], v[80:95]
	ds_read_b128 v[196:199], v175 offset:4640
	ds_read_b128 v[200:203], v175 offset:9248
	v_mfma_f32_32x32x16_bf16 v[64:79], v[132:135], v[148:151], v[64:79]
	ds_read_b128 v[204:207], v175 offset:13856
	buffer_load_dwordx4 v[162:165], v160, s[48:51], 0 offen
	v_mfma_f32_32x32x16_bf16 v[48:63], v[136:139], v[144:147], v[48:63]
	buffer_load_dwordx4 v[166:169], v160, s[48:51], s46 offen
	buffer_load_dwordx4 v[176:179], v160, s[48:51], s47 offen
	v_mfma_f32_32x32x16_bf16 v[32:47], v[136:139], v[148:151], v[32:47]
	buffer_load_dwordx4 v[180:183], v160, s[48:51], s58 offen
	buffer_load_dwordx4 v[184:187], v160, s[52:55], 0 offen
	v_mfma_f32_32x32x16_bf16 v[16:31], v[140:143], v[144:147], v[16:31]
	buffer_load_dwordx4 v[242:245], v160, s[52:55], s46 offen
	buffer_load_dwordx4 v[246:249], v160, s[52:55], s47 offen
	v_mfma_f32_32x32x16_bf16 v[0:15], v[140:143], v[148:151], v[0:15]
	buffer_load_dwordx4 v[250:253], v160, s[52:55], s58 offen
	v_add_u32_e32 v160, 0x80, v160
	s_waitcnt lgkmcnt(0)
	v_mfma_f32_32x32x16_bf16 v[112:127], v[192:195], v[208:211], v[112:127]
	v_mfma_f32_32x32x16_bf16 v[96:111], v[192:195], v[212:215], v[96:111]
	ds_read_b128 v[144:147], v254 offset:64
	v_mfma_f32_32x32x16_bf16 v[80:95], v[196:199], v[208:211], v[80:95]
	ds_read_b128 v[148:151], v254 offset:4672
	v_mfma_f32_32x32x16_bf16 v[64:79], v[196:199], v[212:215], v[64:79]
	ds_read_b128 v[128:131], v175 offset:64
	v_mfma_f32_32x32x16_bf16 v[48:63], v[200:203], v[208:211], v[48:63]
	v_mfma_f32_32x32x16_bf16 v[32:47], v[200:203], v[212:215], v[32:47]
	ds_read_b128 v[132:135], v175 offset:4672
	v_mfma_f32_32x32x16_bf16 v[16:31], v[204:207], v[208:211], v[16:31]
	ds_read_b128 v[136:139], v175 offset:9280
	v_mfma_f32_32x32x16_bf16 v[0:15], v[204:207], v[212:215], v[0:15]
	ds_read_b128 v[140:143], v175 offset:13888
	s_waitcnt lgkmcnt(0)
	v_mfma_f32_32x32x16_bf16 v[112:127], v[128:131], v[144:147], v[112:127]
	v_mfma_f32_32x32x16_bf16 v[96:111], v[128:131], v[148:151], v[96:111]
	ds_read_b128 v[208:211], v254 offset:96
	v_mfma_f32_32x32x16_bf16 v[80:95], v[132:135], v[144:147], v[80:95]
	ds_read_b128 v[212:215], v254 offset:4704
	v_mfma_f32_32x32x16_bf16 v[64:79], v[132:135], v[148:151], v[64:79]
	ds_read_b128 v[192:195], v175 offset:96
	v_mfma_f32_32x32x16_bf16 v[48:63], v[136:139], v[144:147], v[48:63]
	v_mfma_f32_32x32x16_bf16 v[32:47], v[136:139], v[148:151], v[32:47]
	ds_read_b128 v[196:199], v175 offset:4704
	v_mfma_f32_32x32x16_bf16 v[16:31], v[140:143], v[144:147], v[16:31]
	ds_read_b128 v[200:203], v175 offset:9312
	v_mfma_f32_32x32x16_bf16 v[0:15], v[140:143], v[148:151], v[0:15]
	ds_read_b128 v[204:207], v175 offset:13920
	s_waitcnt lgkmcnt(0)
	s_barrier
	ds_read_b128 v[144:147], v254 offset:36864
	ds_read_b128 v[148:151], v254 offset:41472
	ds_read_b128 v[128:131], v175 offset:36864
	ds_read_b128 v[132:135], v175 offset:41472
	ds_read_b128 v[136:139], v175 offset:46080
	ds_read_b128 v[140:143], v175 offset:50688
	v_mfma_f32_32x32x16_bf16 v[112:127], v[192:195], v[208:211], v[112:127]
	s_waitcnt vmcnt(8)
	v_mfma_f32_32x32x16_bf16 v[96:111], v[192:195], v[212:215], v[96:111]
	ds_write_b128 v170, v[216:219] offset:0
	v_mfma_f32_32x32x16_bf16 v[80:95], v[196:199], v[208:211], v[80:95]
	ds_write_b128 v170, v[220:223] offset:9216
	v_mfma_f32_32x32x16_bf16 v[64:79], v[196:199], v[212:215], v[64:79]
	ds_write_b128 v170, v[224:227] offset:18432
	v_mfma_f32_32x32x16_bf16 v[48:63], v[200:203], v[208:211], v[48:63]
	ds_write_b128 v170, v[228:231] offset:27648
	v_mfma_f32_32x32x16_bf16 v[32:47], v[200:203], v[212:215], v[32:47]
	ds_write_b128 v171, v[232:235] offset:0
	v_mfma_f32_32x32x16_bf16 v[16:31], v[204:207], v[208:211], v[16:31]
	ds_write_b128 v171, v[236:239] offset:9216
	v_mfma_f32_32x32x16_bf16 v[0:15], v[204:207], v[212:215], v[0:15]
	ds_write_b128 v171, v[152:155] offset:18432
	ds_write_b128 v171, v[156:159] offset:27648
	s_waitcnt lgkmcnt(8)
	v_mfma_f32_32x32x16_bf16 v[112:127], v[128:131], v[144:147], v[112:127]
	v_mfma_f32_32x32x16_bf16 v[96:111], v[128:131], v[148:151], v[96:111]
	ds_read_b128 v[208:211], v254 offset:36896
	v_mfma_f32_32x32x16_bf16 v[80:95], v[132:135], v[144:147], v[80:95]
	ds_read_b128 v[212:215], v254 offset:41504
	v_mfma_f32_32x32x16_bf16 v[64:79], v[132:135], v[148:151], v[64:79]
	ds_read_b128 v[192:195], v175 offset:36896
	v_mfma_f32_32x32x16_bf16 v[48:63], v[136:139], v[144:147], v[48:63]
	v_mfma_f32_32x32x16_bf16 v[32:47], v[136:139], v[148:151], v[32:47]
	ds_read_b128 v[196:199], v175 offset:41504
	v_mfma_f32_32x32x16_bf16 v[16:31], v[140:143], v[144:147], v[16:31]
	ds_read_b128 v[200:203], v175 offset:46112
	v_mfma_f32_32x32x16_bf16 v[0:15], v[140:143], v[148:151], v[0:15]
	ds_read_b128 v[204:207], v175 offset:50720
	s_waitcnt lgkmcnt(0)
	v_mfma_f32_32x32x16_bf16 v[112:127], v[192:195], v[208:211], v[112:127]
	v_mfma_f32_32x32x16_bf16 v[96:111], v[192:195], v[212:215], v[96:111]
	ds_read_b128 v[144:147], v254 offset:36928
	v_mfma_f32_32x32x16_bf16 v[80:95], v[196:199], v[208:211], v[80:95]
	ds_read_b128 v[148:151], v254 offset:41536
	v_mfma_f32_32x32x16_bf16 v[64:79], v[196:199], v[212:215], v[64:79]
	ds_read_b128 v[128:131], v175 offset:36928
	v_mfma_f32_32x32x16_bf16 v[48:63], v[200:203], v[208:211], v[48:63]
	v_mfma_f32_32x32x16_bf16 v[32:47], v[200:203], v[212:215], v[32:47]
	ds_read_b128 v[132:135], v175 offset:41536
	v_mfma_f32_32x32x16_bf16 v[16:31], v[204:207], v[208:211], v[16:31]
	ds_read_b128 v[136:139], v175 offset:46144
	v_mfma_f32_32x32x16_bf16 v[0:15], v[204:207], v[212:215], v[0:15]
	ds_read_b128 v[140:143], v175 offset:50752
	s_waitcnt lgkmcnt(0)
	v_mfma_f32_32x32x16_bf16 v[112:127], v[128:131], v[144:147], v[112:127]
	v_mfma_f32_32x32x16_bf16 v[96:111], v[128:131], v[148:151], v[96:111]
	ds_read_b128 v[208:211], v254 offset:36960
	v_mfma_f32_32x32x16_bf16 v[80:95], v[132:135], v[144:147], v[80:95]
	ds_read_b128 v[212:215], v254 offset:41568
	v_mfma_f32_32x32x16_bf16 v[64:79], v[132:135], v[148:151], v[64:79]
	ds_read_b128 v[192:195], v175 offset:36960
	v_mfma_f32_32x32x16_bf16 v[48:63], v[136:139], v[144:147], v[48:63]
	v_mfma_f32_32x32x16_bf16 v[32:47], v[136:139], v[148:151], v[32:47]
	ds_read_b128 v[196:199], v175 offset:41568
	v_mfma_f32_32x32x16_bf16 v[16:31], v[140:143], v[144:147], v[16:31]
	ds_read_b128 v[200:203], v175 offset:46176
	v_mfma_f32_32x32x16_bf16 v[0:15], v[140:143], v[148:151], v[0:15]
	ds_read_b128 v[204:207], v175 offset:50784
	s_waitcnt lgkmcnt(0)
	s_barrier
	ds_read_b128 v[144:147], v254 offset:0
	ds_read_b128 v[148:151], v254 offset:4608
	ds_read_b128 v[128:131], v175 offset:0
	ds_read_b128 v[132:135], v175 offset:4608
	ds_read_b128 v[136:139], v175 offset:9216
	ds_read_b128 v[140:143], v175 offset:13824
	v_mfma_f32_32x32x16_bf16 v[112:127], v[192:195], v[208:211], v[112:127]
	s_waitcnt vmcnt(0)
	v_mfma_f32_32x32x16_bf16 v[96:111], v[192:195], v[212:215], v[96:111]
	ds_write_b128 v170, v[162:165] offset:36864
	v_mfma_f32_32x32x16_bf16 v[80:95], v[196:199], v[208:211], v[80:95]
	ds_write_b128 v170, v[166:169] offset:46080
	v_mfma_f32_32x32x16_bf16 v[64:79], v[196:199], v[212:215], v[64:79]
	ds_write_b128 v170, v[176:179] offset:55296
	v_mfma_f32_32x32x16_bf16 v[48:63], v[200:203], v[208:211], v[48:63]
	ds_write_b128 v170, v[180:183] offset:64512
	v_mfma_f32_32x32x16_bf16 v[32:47], v[200:203], v[212:215], v[32:47]
	ds_write_b128 v171, v[184:187] offset:36864
	v_mfma_f32_32x32x16_bf16 v[16:31], v[204:207], v[208:211], v[16:31]
	ds_write_b128 v171, v[242:245] offset:46080
	v_mfma_f32_32x32x16_bf16 v[0:15], v[204:207], v[212:215], v[0:15]
	ds_write_b128 v171, v[246:249] offset:55296
	ds_write_b128 v171, v[250:253] offset:64512
	s_waitcnt lgkmcnt(8)
	v_mfma_f32_32x32x16_bf16 v[112:127], v[128:131], v[144:147], v[112:127]
	v_mfma_f32_32x32x16_bf16 v[96:111], v[128:131], v[148:151], v[96:111]
	ds_read_b128 v[208:211], v254 offset:32
	v_mfma_f32_32x32x16_bf16 v[80:95], v[132:135], v[144:147], v[80:95]
	ds_read_b128 v[212:215], v254 offset:4640
	v_mfma_f32_32x32x16_bf16 v[64:79], v[132:135], v[148:151], v[64:79]
	ds_read_b128 v[192:195], v175 offset:32
	v_mfma_f32_32x32x16_bf16 v[48:63], v[136:139], v[144:147], v[48:63]
	v_mfma_f32_32x32x16_bf16 v[32:47], v[136:139], v[148:151], v[32:47]
	ds_read_b128 v[196:199], v175 offset:4640
	v_mfma_f32_32x32x16_bf16 v[16:31], v[140:143], v[144:147], v[16:31]
	ds_read_b128 v[200:203], v175 offset:9248
	v_mfma_f32_32x32x16_bf16 v[0:15], v[140:143], v[148:151], v[0:15]
	ds_read_b128 v[204:207], v175 offset:13856
	s_waitcnt lgkmcnt(0)
	v_mfma_f32_32x32x16_bf16 v[112:127], v[192:195], v[208:211], v[112:127]
	v_mfma_f32_32x32x16_bf16 v[96:111], v[192:195], v[212:215], v[96:111]
	ds_read_b128 v[144:147], v254 offset:64
	v_mfma_f32_32x32x16_bf16 v[80:95], v[196:199], v[208:211], v[80:95]
	ds_read_b128 v[148:151], v254 offset:4672
	v_mfma_f32_32x32x16_bf16 v[64:79], v[196:199], v[212:215], v[64:79]
	ds_read_b128 v[128:131], v175 offset:64
	v_mfma_f32_32x32x16_bf16 v[48:63], v[200:203], v[208:211], v[48:63]
	v_mfma_f32_32x32x16_bf16 v[32:47], v[200:203], v[212:215], v[32:47]
	ds_read_b128 v[132:135], v175 offset:4672
	v_mfma_f32_32x32x16_bf16 v[16:31], v[204:207], v[208:211], v[16:31]
	ds_read_b128 v[136:139], v175 offset:9280
	v_mfma_f32_32x32x16_bf16 v[0:15], v[204:207], v[212:215], v[0:15]
	ds_read_b128 v[140:143], v175 offset:13888
	s_waitcnt lgkmcnt(0)
	v_mfma_f32_32x32x16_bf16 v[112:127], v[128:131], v[144:147], v[112:127]
	v_mfma_f32_32x32x16_bf16 v[96:111], v[128:131], v[148:151], v[96:111]
	ds_read_b128 v[208:211], v254 offset:96
	v_mfma_f32_32x32x16_bf16 v[80:95], v[132:135], v[144:147], v[80:95]
	ds_read_b128 v[212:215], v254 offset:4704
	v_mfma_f32_32x32x16_bf16 v[64:79], v[132:135], v[148:151], v[64:79]
	ds_read_b128 v[192:195], v175 offset:96
	v_mfma_f32_32x32x16_bf16 v[48:63], v[136:139], v[144:147], v[48:63]
	v_mfma_f32_32x32x16_bf16 v[32:47], v[136:139], v[148:151], v[32:47]
	ds_read_b128 v[196:199], v175 offset:4704
	v_mfma_f32_32x32x16_bf16 v[16:31], v[140:143], v[144:147], v[16:31]
	ds_read_b128 v[200:203], v175 offset:9312
	v_mfma_f32_32x32x16_bf16 v[0:15], v[140:143], v[148:151], v[0:15]
	ds_read_b128 v[204:207], v175 offset:13920
	s_waitcnt lgkmcnt(0)
	s_barrier
	ds_read_b128 v[144:147], v254 offset:36864
	ds_read_b128 v[148:151], v254 offset:41472
	ds_read_b128 v[128:131], v175 offset:36864
	ds_read_b128 v[132:135], v175 offset:41472
	ds_read_b128 v[136:139], v175 offset:46080
	ds_read_b128 v[140:143], v175 offset:50688
	v_mfma_f32_32x32x16_bf16 v[112:127], v[192:195], v[208:211], v[112:127]
	v_mfma_f32_32x32x16_bf16 v[96:111], v[192:195], v[212:215], v[96:111]
	v_mfma_f32_32x32x16_bf16 v[80:95], v[196:199], v[208:211], v[80:95]
	v_mfma_f32_32x32x16_bf16 v[64:79], v[196:199], v[212:215], v[64:79]
	v_mfma_f32_32x32x16_bf16 v[48:63], v[200:203], v[208:211], v[48:63]
	v_mfma_f32_32x32x16_bf16 v[32:47], v[200:203], v[212:215], v[32:47]
	v_mfma_f32_32x32x16_bf16 v[16:31], v[204:207], v[208:211], v[16:31]
	v_mfma_f32_32x32x16_bf16 v[0:15], v[204:207], v[212:215], v[0:15]
	s_waitcnt lgkmcnt(0)
	v_mfma_f32_32x32x16_bf16 v[112:127], v[128:131], v[144:147], v[112:127]
	v_mfma_f32_32x32x16_bf16 v[96:111], v[128:131], v[148:151], v[96:111]
	ds_read_b128 v[208:211], v254 offset:36896
	v_mfma_f32_32x32x16_bf16 v[80:95], v[132:135], v[144:147], v[80:95]
	ds_read_b128 v[212:215], v254 offset:41504
	v_mfma_f32_32x32x16_bf16 v[64:79], v[132:135], v[148:151], v[64:79]
	ds_read_b128 v[192:195], v175 offset:36896
	v_mfma_f32_32x32x16_bf16 v[48:63], v[136:139], v[144:147], v[48:63]
	v_mfma_f32_32x32x16_bf16 v[32:47], v[136:139], v[148:151], v[32:47]
	ds_read_b128 v[196:199], v175 offset:41504
	v_mfma_f32_32x32x16_bf16 v[16:31], v[140:143], v[144:147], v[16:31]
	ds_read_b128 v[200:203], v175 offset:46112
	v_mfma_f32_32x32x16_bf16 v[0:15], v[140:143], v[148:151], v[0:15]
	ds_read_b128 v[204:207], v175 offset:50720
	s_waitcnt lgkmcnt(0)
	v_mfma_f32_32x32x16_bf16 v[112:127], v[192:195], v[208:211], v[112:127]
	v_mfma_f32_32x32x16_bf16 v[96:111], v[192:195], v[212:215], v[96:111]
	ds_read_b128 v[144:147], v254 offset:36928
	v_mfma_f32_32x32x16_bf16 v[80:95], v[196:199], v[208:211], v[80:95]
	ds_read_b128 v[148:151], v254 offset:41536
	v_mfma_f32_32x32x16_bf16 v[64:79], v[196:199], v[212:215], v[64:79]
	ds_read_b128 v[128:131], v175 offset:36928
	v_mfma_f32_32x32x16_bf16 v[48:63], v[200:203], v[208:211], v[48:63]
	v_mfma_f32_32x32x16_bf16 v[32:47], v[200:203], v[212:215], v[32:47]
	ds_read_b128 v[132:135], v175 offset:41536
	v_mfma_f32_32x32x16_bf16 v[16:31], v[204:207], v[208:211], v[16:31]
	ds_read_b128 v[136:139], v175 offset:46144
	v_mfma_f32_32x32x16_bf16 v[0:15], v[204:207], v[212:215], v[0:15]
	ds_read_b128 v[140:143], v175 offset:50752
	s_waitcnt lgkmcnt(0)
	v_mfma_f32_32x32x16_bf16 v[112:127], v[128:131], v[144:147], v[112:127]
	v_mfma_f32_32x32x16_bf16 v[96:111], v[128:131], v[148:151], v[96:111]
	ds_read_b128 v[208:211], v254 offset:36960
	v_mfma_f32_32x32x16_bf16 v[80:95], v[132:135], v[144:147], v[80:95]
	ds_read_b128 v[212:215], v254 offset:41568
	v_mfma_f32_32x32x16_bf16 v[64:79], v[132:135], v[148:151], v[64:79]
	ds_read_b128 v[192:195], v175 offset:36960
	v_mfma_f32_32x32x16_bf16 v[48:63], v[136:139], v[144:147], v[48:63]
	v_mfma_f32_32x32x16_bf16 v[32:47], v[136:139], v[148:151], v[32:47]
	ds_read_b128 v[196:199], v175 offset:41568
	v_mfma_f32_32x32x16_bf16 v[16:31], v[140:143], v[144:147], v[16:31]
	ds_read_b128 v[200:203], v175 offset:46176
	v_mfma_f32_32x32x16_bf16 v[0:15], v[140:143], v[148:151], v[0:15]
	ds_read_b128 v[204:207], v175 offset:50784
	s_waitcnt lgkmcnt(0)
	s_barrier
	v_mfma_f32_32x32x16_bf16 v[112:127], v[192:195], v[208:211], v[112:127]
	v_mfma_f32_32x32x16_bf16 v[96:111], v[192:195], v[212:215], v[96:111]
	v_mfma_f32_32x32x16_bf16 v[80:95], v[196:199], v[208:211], v[80:95]
	v_mfma_f32_32x32x16_bf16 v[64:79], v[196:199], v[212:215], v[64:79]
	v_mfma_f32_32x32x16_bf16 v[48:63], v[200:203], v[208:211], v[48:63]
	v_mfma_f32_32x32x16_bf16 v[32:47], v[200:203], v[212:215], v[32:47]
	v_mfma_f32_32x32x16_bf16 v[16:31], v[204:207], v[208:211], v[16:31]
	v_mfma_f32_32x32x16_bf16 v[0:15], v[204:207], v[212:215], v[0:15]
	s_nop 7
	s_nop 7
	s_mul_i32 s100, s64, 0x1000
	s_mul_hi_u32 s101, s64, 0x1000
	s_add_u32 s100, s100, 0xa224000
	s_addc_u32 s101, s101, 0
	s_add_u32 s96, s92, s100
	s_addc_u32 s97, s93, s101
	s_and_b32 s97, s97, 0xffff
	s_mov_b32 s98, 0x100000
	s_mov_b32 s99, 0x20000
	v_and_b32_e32 v132, 31, v190
	v_bfe_u32 v133, v190, 5, 1
	v_bfe_u32 v134, v190, 6, 2
	v_bfe_u32 v135, v190, 8, 1
	v_lshl_add_u32 v132, v134, 6, v132
	v_add_u32_e32 v132, s82, v132
	v_lshlrev_b32_e32 v132, 1, v132
	v_lshlrev_b32_e32 v135, 7, v135
	v_lshl_add_u32 v135, v133, 2, v135
	s_mov_b32 s47, 0x1000
	v_mul_lo_u32 v135, s47, v135
	v_add_u32_e32 v128, v135, v132
	v_add_u32_e32 v129, 0x1000, v128
	v_add_u32_e32 v130, 0x2000, v128
	v_add_u32_e32 v131, 0x3000, v128
	s_add_i32 s38, s38, s94
	s_cmpk_lt_i32 s38, 0x200
	s_cbranch_scc0 .Lgwq1_last
	s_bfe_u32 s100, s38, 0x30005
	s_and_b32 s101, s38, 31
	s_lshr_b32 s82, s38, 8
	s_lshl_b32 s64, s82, 5
	s_lshr_b32 s82, s100, 3
	s_lshl_b32 s82, s82, 5
	s_add_u32 s64, s64, s82
	s_lshr_b32 s82, s101, 0
	s_add_u32 s64, s64, s82
	s_and_b32 s82, s100, 7
	s_lshl_b32 s82, s82, 0
	s_and_b32 s101, s101, 0
	s_add_u32 s82, s82, s101
	s_lshl_b32 s64, s64, 8
	s_lshl_b32 s82, s82, 8
	s_lshl_b32 s100, s64, 12
	s_add_u32 s100, s100, 0x6224000
	s_add_u32 s48, s92, s100
	s_addc_u32 s49, s93, 0
	s_and_b32 s49, s49, 0xffff
	s_mov_b32 s50, 0x100000
	s_mov_b32 s51, 0x20000
	s_lshl_b32 s100, s82, 12
	s_add_u32 s100, s100, 0x4380000
	s_add_u32 s52, s92, s100
	s_addc_u32 s53, s93, 0
	s_and_b32 s53, s53, 0xffff
	s_sub_u32 s100, 0x800, s82
	s_min_u32 s100, s100, 0x100
	s_lshl_b32 s54, s100, 12
	s_mov_b32 s55, 0x20000
	s_mov_b32 s46, 0x40000
	s_mov_b32 s47, 0x80000
	s_mov_b32 s58, 0xc0000
	v_lshrrev_b32_e32 v137, 3, v190
	v_and_b32_e32 v138, 7, v190
	v_lshlrev_b32_e32 v138, 4, v138
	v_lshl_add_u32 v160, v137, 12, v138
	buffer_load_dwordx4 v[216:219], v160, s[48:51], 0 offen
	buffer_load_dwordx4 v[220:223], v160, s[48:51], s46 offen
	buffer_load_dwordx4 v[224:227], v160, s[48:51], s47 offen
	buffer_load_dwordx4 v[228:231], v160, s[48:51], s58 offen
	buffer_load_dwordx4 v[232:235], v160, s[52:55], 0 offen
	buffer_load_dwordx4 v[236:239], v160, s[52:55], s46 offen
	buffer_load_dwordx4 v[152:155], v160, s[52:55], s47 offen
	buffer_load_dwordx4 v[156:159], v160, s[52:55], s58 offen
	v_add_u32_e32 v160, 0x80, v160
	buffer_load_dwordx4 v[162:165], v160, s[48:51], 0 offen
	buffer_load_dwordx4 v[166:169], v160, s[48:51], s46 offen
	buffer_load_dwordx4 v[176:179], v160, s[48:51], s47 offen
	buffer_load_dwordx4 v[180:183], v160, s[48:51], s58 offen
	buffer_load_dwordx4 v[184:187], v160, s[52:55], 0 offen
	buffer_load_dwordx4 v[242:245], v160, s[52:55], s46 offen
	buffer_load_dwordx4 v[246:249], v160, s[52:55], s47 offen
	buffer_load_dwordx4 v[250:253], v160, s[52:55], s58 offen
	v_add_u32_e32 v160, 0x80, v160
.Lgwq1_last:
	s_movk_i32 s46, 0x7fff
	v_bfe_u32 v136, v112, 16, 1
	v_bfe_u32 v137, v113, 16, 1
	v_bfe_u32 v138, v114, 16, 1
	v_bfe_u32 v139, v115, 16, 1
	v_add3_u32 v112, v112, v136, s46
	v_add3_u32 v113, v113, v137, s46
	v_add3_u32 v114, v114, v138, s46
	v_add3_u32 v115, v115, v139, s46
	s_mov_b32 s101, 0x0
	buffer_store_short_d16_hi v112, v128, s[96:99], s101 offen
	buffer_store_short_d16_hi v113, v129, s[96:99], s101 offen
	buffer_store_short_d16_hi v114, v130, s[96:99], s101 offen
	buffer_store_short_d16_hi v115, v131, s[96:99], s101 offen
	v_bfe_u32 v136, v116, 16, 1
	v_bfe_u32 v137, v117, 16, 1
	v_bfe_u32 v138, v118, 16, 1
	v_bfe_u32 v139, v119, 16, 1
	v_add3_u32 v116, v116, v136, s46
	v_add3_u32 v117, v117, v137, s46
	v_add3_u32 v118, v118, v138, s46
	v_add3_u32 v119, v119, v139, s46
	s_mov_b32 s101, 0x8000
	buffer_store_short_d16_hi v116, v128, s[96:99], s101 offen
	buffer_store_short_d16_hi v117, v129, s[96:99], s101 offen
	buffer_store_short_d16_hi v118, v130, s[96:99], s101 offen
	buffer_store_short_d16_hi v119, v131, s[96:99], s101 offen
	v_bfe_u32 v136, v120, 16, 1
	v_bfe_u32 v137, v121, 16, 1
	v_bfe_u32 v138, v122, 16, 1
	v_bfe_u32 v139, v123, 16, 1
	v_add3_u32 v120, v120, v136, s46
	v_add3_u32 v121, v121, v137, s46
	v_add3_u32 v122, v122, v138, s46
	v_add3_u32 v123, v123, v139, s46
	s_mov_b32 s101, 0x10000
	buffer_store_short_d16_hi v120, v128, s[96:99], s101 offen
	buffer_store_short_d16_hi v121, v129, s[96:99], s101 offen
	buffer_store_short_d16_hi v122, v130, s[96:99], s101 offen
	buffer_store_short_d16_hi v123, v131, s[96:99], s101 offen
	v_bfe_u32 v136, v124, 16, 1
	v_bfe_u32 v137, v125, 16, 1
	v_bfe_u32 v138, v126, 16, 1
	v_bfe_u32 v139, v127, 16, 1
	v_add3_u32 v124, v124, v136, s46
	v_add3_u32 v125, v125, v137, s46
	v_add3_u32 v126, v126, v138, s46
	v_add3_u32 v127, v127, v139, s46
	s_mov_b32 s101, 0x18000
	buffer_store_short_d16_hi v124, v128, s[96:99], s101 offen
	buffer_store_short_d16_hi v125, v129, s[96:99], s101 offen
	buffer_store_short_d16_hi v126, v130, s[96:99], s101 offen
	buffer_store_short_d16_hi v127, v131, s[96:99], s101 offen
	v_bfe_u32 v136, v96, 16, 1
	v_bfe_u32 v137, v97, 16, 1
	v_bfe_u32 v138, v98, 16, 1
	v_bfe_u32 v139, v99, 16, 1
	v_add3_u32 v96, v96, v136, s46
	v_add3_u32 v97, v97, v137, s46
	v_add3_u32 v98, v98, v138, s46
	v_add3_u32 v99, v99, v139, s46
	s_mov_b32 s101, 0x0
	buffer_store_short_d16_hi v96, v128, s[96:99], s101 offen offset:64
	buffer_store_short_d16_hi v97, v129, s[96:99], s101 offen offset:64
	buffer_store_short_d16_hi v98, v130, s[96:99], s101 offen offset:64
	buffer_store_short_d16_hi v99, v131, s[96:99], s101 offen offset:64
	v_bfe_u32 v136, v100, 16, 1
	v_bfe_u32 v137, v101, 16, 1
	v_bfe_u32 v138, v102, 16, 1
	v_bfe_u32 v139, v103, 16, 1
	v_add3_u32 v100, v100, v136, s46
	v_add3_u32 v101, v101, v137, s46
	v_add3_u32 v102, v102, v138, s46
	v_add3_u32 v103, v103, v139, s46
	s_mov_b32 s101, 0x8000
	buffer_store_short_d16_hi v100, v128, s[96:99], s101 offen offset:64
	buffer_store_short_d16_hi v101, v129, s[96:99], s101 offen offset:64
	buffer_store_short_d16_hi v102, v130, s[96:99], s101 offen offset:64
	buffer_store_short_d16_hi v103, v131, s[96:99], s101 offen offset:64
	v_bfe_u32 v136, v104, 16, 1
	v_bfe_u32 v137, v105, 16, 1
	v_bfe_u32 v138, v106, 16, 1
	v_bfe_u32 v139, v107, 16, 1
	v_add3_u32 v104, v104, v136, s46
	v_add3_u32 v105, v105, v137, s46
	v_add3_u32 v106, v106, v138, s46
	v_add3_u32 v107, v107, v139, s46
	s_mov_b32 s101, 0x10000
	buffer_store_short_d16_hi v104, v128, s[96:99], s101 offen offset:64
	buffer_store_short_d16_hi v105, v129, s[96:99], s101 offen offset:64
	buffer_store_short_d16_hi v106, v130, s[96:99], s101 offen offset:64
	buffer_store_short_d16_hi v107, v131, s[96:99], s101 offen offset:64
	v_bfe_u32 v136, v108, 16, 1
	v_bfe_u32 v137, v109, 16, 1
	v_bfe_u32 v138, v110, 16, 1
	v_bfe_u32 v139, v111, 16, 1
	v_add3_u32 v108, v108, v136, s46
	v_add3_u32 v109, v109, v137, s46
	v_add3_u32 v110, v110, v138, s46
	v_add3_u32 v111, v111, v139, s46
	s_mov_b32 s101, 0x18000
	buffer_store_short_d16_hi v108, v128, s[96:99], s101 offen offset:64
	buffer_store_short_d16_hi v109, v129, s[96:99], s101 offen offset:64
	buffer_store_short_d16_hi v110, v130, s[96:99], s101 offen offset:64
	buffer_store_short_d16_hi v111, v131, s[96:99], s101 offen offset:64
	v_bfe_u32 v136, v80, 16, 1
	v_bfe_u32 v137, v81, 16, 1
	v_bfe_u32 v138, v82, 16, 1
	v_bfe_u32 v139, v83, 16, 1
	v_add3_u32 v80, v80, v136, s46
	v_add3_u32 v81, v81, v137, s46
	v_add3_u32 v82, v82, v138, s46
	v_add3_u32 v83, v83, v139, s46
	s_mov_b32 s101, 0x20000
	buffer_store_short_d16_hi v80, v128, s[96:99], s101 offen
	buffer_store_short_d16_hi v81, v129, s[96:99], s101 offen
	buffer_store_short_d16_hi v82, v130, s[96:99], s101 offen
	buffer_store_short_d16_hi v83, v131, s[96:99], s101 offen
	v_bfe_u32 v136, v84, 16, 1
	v_bfe_u32 v137, v85, 16, 1
	v_bfe_u32 v138, v86, 16, 1
	v_bfe_u32 v139, v87, 16, 1
	v_add3_u32 v84, v84, v136, s46
	v_add3_u32 v85, v85, v137, s46
	v_add3_u32 v86, v86, v138, s46
	v_add3_u32 v87, v87, v139, s46
	s_mov_b32 s101, 0x28000
	buffer_store_short_d16_hi v84, v128, s[96:99], s101 offen
	buffer_store_short_d16_hi v85, v129, s[96:99], s101 offen
	buffer_store_short_d16_hi v86, v130, s[96:99], s101 offen
	buffer_store_short_d16_hi v87, v131, s[96:99], s101 offen
	v_bfe_u32 v136, v88, 16, 1
	v_bfe_u32 v137, v89, 16, 1
	v_bfe_u32 v138, v90, 16, 1
	v_bfe_u32 v139, v91, 16, 1
	v_add3_u32 v88, v88, v136, s46
	v_add3_u32 v89, v89, v137, s46
	v_add3_u32 v90, v90, v138, s46
	v_add3_u32 v91, v91, v139, s46
	s_mov_b32 s101, 0x30000
	buffer_store_short_d16_hi v88, v128, s[96:99], s101 offen
	buffer_store_short_d16_hi v89, v129, s[96:99], s101 offen
	buffer_store_short_d16_hi v90, v130, s[96:99], s101 offen
	buffer_store_short_d16_hi v91, v131, s[96:99], s101 offen
	v_bfe_u32 v136, v92, 16, 1
	v_bfe_u32 v137, v93, 16, 1
	v_bfe_u32 v138, v94, 16, 1
	v_bfe_u32 v139, v95, 16, 1
	v_add3_u32 v92, v92, v136, s46
	v_add3_u32 v93, v93, v137, s46
	v_add3_u32 v94, v94, v138, s46
	v_add3_u32 v95, v95, v139, s46
	s_mov_b32 s101, 0x38000
	buffer_store_short_d16_hi v92, v128, s[96:99], s101 offen
	buffer_store_short_d16_hi v93, v129, s[96:99], s101 offen
	buffer_store_short_d16_hi v94, v130, s[96:99], s101 offen
	buffer_store_short_d16_hi v95, v131, s[96:99], s101 offen
	v_bfe_u32 v136, v64, 16, 1
	v_bfe_u32 v137, v65, 16, 1
	v_bfe_u32 v138, v66, 16, 1
	v_bfe_u32 v139, v67, 16, 1
	v_add3_u32 v64, v64, v136, s46
	v_add3_u32 v65, v65, v137, s46
	v_add3_u32 v66, v66, v138, s46
	v_add3_u32 v67, v67, v139, s46
	s_mov_b32 s101, 0x20000
	buffer_store_short_d16_hi v64, v128, s[96:99], s101 offen offset:64
	buffer_store_short_d16_hi v65, v129, s[96:99], s101 offen offset:64
	buffer_store_short_d16_hi v66, v130, s[96:99], s101 offen offset:64
	buffer_store_short_d16_hi v67, v131, s[96:99], s101 offen offset:64
	v_bfe_u32 v136, v68, 16, 1
	v_bfe_u32 v137, v69, 16, 1
	v_bfe_u32 v138, v70, 16, 1
	v_bfe_u32 v139, v71, 16, 1
	v_add3_u32 v68, v68, v136, s46
	v_add3_u32 v69, v69, v137, s46
	v_add3_u32 v70, v70, v138, s46
	v_add3_u32 v71, v71, v139, s46
	s_mov_b32 s101, 0x28000
	buffer_store_short_d16_hi v68, v128, s[96:99], s101 offen offset:64
	buffer_store_short_d16_hi v69, v129, s[96:99], s101 offen offset:64
	buffer_store_short_d16_hi v70, v130, s[96:99], s101 offen offset:64
	buffer_store_short_d16_hi v71, v131, s[96:99], s101 offen offset:64
	v_bfe_u32 v136, v72, 16, 1
	v_bfe_u32 v137, v73, 16, 1
	v_bfe_u32 v138, v74, 16, 1
	v_bfe_u32 v139, v75, 16, 1
	v_add3_u32 v72, v72, v136, s46
	v_add3_u32 v73, v73, v137, s46
	v_add3_u32 v74, v74, v138, s46
	v_add3_u32 v75, v75, v139, s46
	s_mov_b32 s101, 0x30000
	buffer_store_short_d16_hi v72, v128, s[96:99], s101 offen offset:64
	buffer_store_short_d16_hi v73, v129, s[96:99], s101 offen offset:64
	buffer_store_short_d16_hi v74, v130, s[96:99], s101 offen offset:64
	buffer_store_short_d16_hi v75, v131, s[96:99], s101 offen offset:64
	v_bfe_u32 v136, v76, 16, 1
	v_bfe_u32 v137, v77, 16, 1
	v_bfe_u32 v138, v78, 16, 1
	v_bfe_u32 v139, v79, 16, 1
	v_add3_u32 v76, v76, v136, s46
	v_add3_u32 v77, v77, v137, s46
	v_add3_u32 v78, v78, v138, s46
	v_add3_u32 v79, v79, v139, s46
	s_mov_b32 s101, 0x38000
	buffer_store_short_d16_hi v76, v128, s[96:99], s101 offen offset:64
	buffer_store_short_d16_hi v77, v129, s[96:99], s101 offen offset:64
	buffer_store_short_d16_hi v78, v130, s[96:99], s101 offen offset:64
	buffer_store_short_d16_hi v79, v131, s[96:99], s101 offen offset:64
	v_bfe_u32 v136, v48, 16, 1
	v_bfe_u32 v137, v49, 16, 1
	v_bfe_u32 v138, v50, 16, 1
	v_bfe_u32 v139, v51, 16, 1
	v_add3_u32 v48, v48, v136, s46
	v_add3_u32 v49, v49, v137, s46
	v_add3_u32 v50, v50, v138, s46
	v_add3_u32 v51, v51, v139, s46
	s_mov_b32 s101, 0x40000
	buffer_store_short_d16_hi v48, v128, s[96:99], s101 offen
	buffer_store_short_d16_hi v49, v129, s[96:99], s101 offen
	buffer_store_short_d16_hi v50, v130, s[96:99], s101 offen
	buffer_store_short_d16_hi v51, v131, s[96:99], s101 offen
	v_bfe_u32 v136, v52, 16, 1
	v_bfe_u32 v137, v53, 16, 1
	v_bfe_u32 v138, v54, 16, 1
	v_bfe_u32 v139, v55, 16, 1
	v_add3_u32 v52, v52, v136, s46
	v_add3_u32 v53, v53, v137, s46
	v_add3_u32 v54, v54, v138, s46
	v_add3_u32 v55, v55, v139, s46
	s_mov_b32 s101, 0x48000
	buffer_store_short_d16_hi v52, v128, s[96:99], s101 offen
	buffer_store_short_d16_hi v53, v129, s[96:99], s101 offen
	buffer_store_short_d16_hi v54, v130, s[96:99], s101 offen
	buffer_store_short_d16_hi v55, v131, s[96:99], s101 offen
	v_bfe_u32 v136, v56, 16, 1
	v_bfe_u32 v137, v57, 16, 1
	v_bfe_u32 v138, v58, 16, 1
	v_bfe_u32 v139, v59, 16, 1
	v_add3_u32 v56, v56, v136, s46
	v_add3_u32 v57, v57, v137, s46
	v_add3_u32 v58, v58, v138, s46
	v_add3_u32 v59, v59, v139, s46
	s_mov_b32 s101, 0x50000
	buffer_store_short_d16_hi v56, v128, s[96:99], s101 offen
	buffer_store_short_d16_hi v57, v129, s[96:99], s101 offen
	buffer_store_short_d16_hi v58, v130, s[96:99], s101 offen
	buffer_store_short_d16_hi v59, v131, s[96:99], s101 offen
	v_bfe_u32 v136, v60, 16, 1
	v_bfe_u32 v137, v61, 16, 1
	v_bfe_u32 v138, v62, 16, 1
	v_bfe_u32 v139, v63, 16, 1
	v_add3_u32 v60, v60, v136, s46
	v_add3_u32 v61, v61, v137, s46
	v_add3_u32 v62, v62, v138, s46
	v_add3_u32 v63, v63, v139, s46
	s_mov_b32 s101, 0x58000
	buffer_store_short_d16_hi v60, v128, s[96:99], s101 offen
	buffer_store_short_d16_hi v61, v129, s[96:99], s101 offen
	buffer_store_short_d16_hi v62, v130, s[96:99], s101 offen
	buffer_store_short_d16_hi v63, v131, s[96:99], s101 offen
	v_bfe_u32 v136, v32, 16, 1
	v_bfe_u32 v137, v33, 16, 1
	v_bfe_u32 v138, v34, 16, 1
	v_bfe_u32 v139, v35, 16, 1
	v_add3_u32 v32, v32, v136, s46
	v_add3_u32 v33, v33, v137, s46
	v_add3_u32 v34, v34, v138, s46
	v_add3_u32 v35, v35, v139, s46
	s_mov_b32 s101, 0x40000
	buffer_store_short_d16_hi v32, v128, s[96:99], s101 offen offset:64
	buffer_store_short_d16_hi v33, v129, s[96:99], s101 offen offset:64
	buffer_store_short_d16_hi v34, v130, s[96:99], s101 offen offset:64
	buffer_store_short_d16_hi v35, v131, s[96:99], s101 offen offset:64
	v_bfe_u32 v136, v36, 16, 1
	v_bfe_u32 v137, v37, 16, 1
	v_bfe_u32 v138, v38, 16, 1
	v_bfe_u32 v139, v39, 16, 1
	v_add3_u32 v36, v36, v136, s46
	v_add3_u32 v37, v37, v137, s46
	v_add3_u32 v38, v38, v138, s46
	v_add3_u32 v39, v39, v139, s46
	s_mov_b32 s101, 0x48000
	buffer_store_short_d16_hi v36, v128, s[96:99], s101 offen offset:64
	buffer_store_short_d16_hi v37, v129, s[96:99], s101 offen offset:64
	buffer_store_short_d16_hi v38, v130, s[96:99], s101 offen offset:64
	buffer_store_short_d16_hi v39, v131, s[96:99], s101 offen offset:64
	v_bfe_u32 v136, v40, 16, 1
	v_bfe_u32 v137, v41, 16, 1
	v_bfe_u32 v138, v42, 16, 1
	v_bfe_u32 v139, v43, 16, 1
	v_add3_u32 v40, v40, v136, s46
	v_add3_u32 v41, v41, v137, s46
	v_add3_u32 v42, v42, v138, s46
	v_add3_u32 v43, v43, v139, s46
	s_mov_b32 s101, 0x50000
	buffer_store_short_d16_hi v40, v128, s[96:99], s101 offen offset:64
	buffer_store_short_d16_hi v41, v129, s[96:99], s101 offen offset:64
	buffer_store_short_d16_hi v42, v130, s[96:99], s101 offen offset:64
	buffer_store_short_d16_hi v43, v131, s[96:99], s101 offen offset:64
	v_bfe_u32 v136, v44, 16, 1
	v_bfe_u32 v137, v45, 16, 1
	v_bfe_u32 v138, v46, 16, 1
	v_bfe_u32 v139, v47, 16, 1
	v_add3_u32 v44, v44, v136, s46
	v_add3_u32 v45, v45, v137, s46
	v_add3_u32 v46, v46, v138, s46
	v_add3_u32 v47, v47, v139, s46
	s_mov_b32 s101, 0x58000
	buffer_store_short_d16_hi v44, v128, s[96:99], s101 offen offset:64
	buffer_store_short_d16_hi v45, v129, s[96:99], s101 offen offset:64
	buffer_store_short_d16_hi v46, v130, s[96:99], s101 offen offset:64
	buffer_store_short_d16_hi v47, v131, s[96:99], s101 offen offset:64
	v_bfe_u32 v136, v16, 16, 1
	v_bfe_u32 v137, v17, 16, 1
	v_bfe_u32 v138, v18, 16, 1
	v_bfe_u32 v139, v19, 16, 1
	v_add3_u32 v16, v16, v136, s46
	v_add3_u32 v17, v17, v137, s46
	v_add3_u32 v18, v18, v138, s46
	v_add3_u32 v19, v19, v139, s46
	s_mov_b32 s101, 0x60000
	buffer_store_short_d16_hi v16, v128, s[96:99], s101 offen
	buffer_store_short_d16_hi v17, v129, s[96:99], s101 offen
	buffer_store_short_d16_hi v18, v130, s[96:99], s101 offen
	buffer_store_short_d16_hi v19, v131, s[96:99], s101 offen
	v_bfe_u32 v136, v20, 16, 1
	v_bfe_u32 v137, v21, 16, 1
	v_bfe_u32 v138, v22, 16, 1
	v_bfe_u32 v139, v23, 16, 1
	v_add3_u32 v20, v20, v136, s46
	v_add3_u32 v21, v21, v137, s46
	v_add3_u32 v22, v22, v138, s46
	v_add3_u32 v23, v23, v139, s46
	s_mov_b32 s101, 0x68000
	buffer_store_short_d16_hi v20, v128, s[96:99], s101 offen
	buffer_store_short_d16_hi v21, v129, s[96:99], s101 offen
	buffer_store_short_d16_hi v22, v130, s[96:99], s101 offen
	buffer_store_short_d16_hi v23, v131, s[96:99], s101 offen
	v_bfe_u32 v136, v24, 16, 1
	v_bfe_u32 v137, v25, 16, 1
	v_bfe_u32 v138, v26, 16, 1
	v_bfe_u32 v139, v27, 16, 1
	v_add3_u32 v24, v24, v136, s46
	v_add3_u32 v25, v25, v137, s46
	v_add3_u32 v26, v26, v138, s46
	v_add3_u32 v27, v27, v139, s46
	s_mov_b32 s101, 0x70000
	buffer_store_short_d16_hi v24, v128, s[96:99], s101 offen
	buffer_store_short_d16_hi v25, v129, s[96:99], s101 offen
	buffer_store_short_d16_hi v26, v130, s[96:99], s101 offen
	buffer_store_short_d16_hi v27, v131, s[96:99], s101 offen
	v_bfe_u32 v136, v28, 16, 1
	v_bfe_u32 v137, v29, 16, 1
	v_bfe_u32 v138, v30, 16, 1
	v_bfe_u32 v139, v31, 16, 1
	v_add3_u32 v28, v28, v136, s46
	v_add3_u32 v29, v29, v137, s46
	v_add3_u32 v30, v30, v138, s46
	v_add3_u32 v31, v31, v139, s46
	s_mov_b32 s101, 0x78000
	buffer_store_short_d16_hi v28, v128, s[96:99], s101 offen
	buffer_store_short_d16_hi v29, v129, s[96:99], s101 offen
	buffer_store_short_d16_hi v30, v130, s[96:99], s101 offen
	buffer_store_short_d16_hi v31, v131, s[96:99], s101 offen
	v_bfe_u32 v136, v0, 16, 1
	v_bfe_u32 v137, v1, 16, 1
	v_bfe_u32 v138, v2, 16, 1
	v_bfe_u32 v139, v3, 16, 1
	v_add3_u32 v0, v0, v136, s46
	v_add3_u32 v1, v1, v137, s46
	v_add3_u32 v2, v2, v138, s46
	v_add3_u32 v3, v3, v139, s46
	s_mov_b32 s101, 0x60000
	buffer_store_short_d16_hi v0, v128, s[96:99], s101 offen offset:64
	buffer_store_short_d16_hi v1, v129, s[96:99], s101 offen offset:64
	buffer_store_short_d16_hi v2, v130, s[96:99], s101 offen offset:64
	buffer_store_short_d16_hi v3, v131, s[96:99], s101 offen offset:64
	v_bfe_u32 v136, v4, 16, 1
	v_bfe_u32 v137, v5, 16, 1
	v_bfe_u32 v138, v6, 16, 1
	v_bfe_u32 v139, v7, 16, 1
	v_add3_u32 v4, v4, v136, s46
	v_add3_u32 v5, v5, v137, s46
	v_add3_u32 v6, v6, v138, s46
	v_add3_u32 v7, v7, v139, s46
	s_mov_b32 s101, 0x68000
	buffer_store_short_d16_hi v4, v128, s[96:99], s101 offen offset:64
	buffer_store_short_d16_hi v5, v129, s[96:99], s101 offen offset:64
	buffer_store_short_d16_hi v6, v130, s[96:99], s101 offen offset:64
	buffer_store_short_d16_hi v7, v131, s[96:99], s101 offen offset:64
	v_bfe_u32 v136, v8, 16, 1
	v_bfe_u32 v137, v9, 16, 1
	v_bfe_u32 v138, v10, 16, 1
	v_bfe_u32 v139, v11, 16, 1
	v_add3_u32 v8, v8, v136, s46
	v_add3_u32 v9, v9, v137, s46
	v_add3_u32 v10, v10, v138, s46
	v_add3_u32 v11, v11, v139, s46
	s_mov_b32 s101, 0x70000
	buffer_store_short_d16_hi v8, v128, s[96:99], s101 offen offset:64
	buffer_store_short_d16_hi v9, v129, s[96:99], s101 offen offset:64
	buffer_store_short_d16_hi v10, v130, s[96:99], s101 offen offset:64
	buffer_store_short_d16_hi v11, v131, s[96:99], s101 offen offset:64
	v_bfe_u32 v136, v12, 16, 1
	v_bfe_u32 v137, v13, 16, 1
	v_bfe_u32 v138, v14, 16, 1
	v_bfe_u32 v139, v15, 16, 1
	v_add3_u32 v12, v12, v136, s46
	v_add3_u32 v13, v13, v137, s46
	v_add3_u32 v14, v14, v138, s46
	v_add3_u32 v15, v15, v139, s46
	s_mov_b32 s101, 0x78000
	buffer_store_short_d16_hi v12, v128, s[96:99], s101 offen offset:64
	buffer_store_short_d16_hi v13, v129, s[96:99], s101 offen offset:64
	buffer_store_short_d16_hi v14, v130, s[96:99], s101 offen offset:64
	buffer_store_short_d16_hi v15, v131, s[96:99], s101 offen offset:64
	s_cmpk_lt_i32 s38, 0x200
	s_cbranch_scc1 .Lgwq1_tile
	s_branch .LBB0_2651
